# v22 plus non-temporal hint on the norm phases' residual-stream row loads (read-once rows no longer evict GEMM operands from L2)
# speedup vs baseline: 1.0236x; 1.0090x over previous
; DI void modnorm_rows(const Params& p, int l, int which  , bool from_inputs, bool skip_ctx, int w0, int wstride, int lane) {
;   const float* g = (which ? p.norm2_g : p.norm1_g) + l * DM;
;   f32x4 gg[4];
; #pragma unroll
;   for (int i = 0; i < 4; ++i) gg[i] = *(const f32x4*)(g + i * 256 + lane * 4);
;   const int nrows = skip_ctx ? 8 * NLAT : T_TOK;
;   auto rowof = [&](int i) -> int { return skip_ctx ? (i / NLAT) * TB + NCTX + (i % NLAT) : i; };
;   int i = w0;
;   if (i >= nrows) return;
;   f32x4 vn[4];
;   {
;     const int row = rowof(i); const float* src = xsrc_row(p, from_inputs, row / TB, row % TB);
; #pragma unroll
;     for (int q = 0; q < 4; ++q) vn[q] = *(const f32x4*)(src + q * 256 + lane * 4);
;   }
;   for (; i < nrows; i += wstride) {
;     const int row = rowof(i); const int b = row / TB, s = row % TB;
;     f32x4 v[4];
; #pragma unroll
;     for (int q = 0; q < 4; ++q) v[q] = vn[q];
;     if (i + wstride < nrows) {
;       const int rn = rowof(i + wstride); const float* src = xsrc_row(p, from_inputs, rn / TB, rn % TB);
; #pragma unroll
;       for (int q = 0; q < 4; ++q) vn[q] = *(const f32x4*)(src + q * 256 + lane * 4);
;     }
;     const float* mod = p.MOD + (size_t)(l * 9 + (s < NCTX ? 8 : b)) * 6144 + (which ? 3 * 1024 : 0);
;     f32x4 sh[4], sc[4];
; #pragma unroll
;     for (int q = 0; q < 4; ++q) { sh[q] = *(const f32x4*)(mod + q * 256 + lane * 4); sc[q] = *(const f32x4*)(mod + 1024 + q * 256 + lane * 4); }
; template <int KSEL> DI void run_phase(const Params& p, int ph, char* lds) {
;     ...
;       modnorm_rows(p, l, 1, false, last, bid * 4 + wid, G * 4, lane);
.LBB0_228:
	s_andn2_b64 vcc, exec, s[0:1]
	s_cbranch_vccnz .LBB0_249
	v_readlane_b32 s0, v252, 9
	s_nop 1
	v_add_u32_e32 v1, s0, v158
	v_readlane_b32 s0, v250, 4
	v_readlane_b32 s1, v250, 5
	s_and_b64 s[0:1], s[0:1], exec
	s_movk_i32 s0, 0x4800
	s_cselect_b32 s26, 0x4000, s0
	v_cmp_gt_i32_e32 vcc, s26, v1
	s_and_saveexec_b64 s[2:3], vcc
	s_cbranch_execz .LBB0_248
	v_readlane_b32 s0, v252, 9
	v_lshlrev_b32_e32 v244, 4, v115
	v_lshlrev_b32_e32 v245, 3, v115
	v_add_u32_e32 v1, s0, v158
	s_nop 1
	v_readfirstlane_b32 s20, v1
	v_readlane_b32 s4, v254, 42
	v_readlane_b32 s5, v254, 43
	v_readlane_b32 s12, v254, 28
	v_readlane_b32 s13, v254, 29
	v_readlane_b32 s14, v254, 32
	v_readlane_b32 s15, v254, 33
	v_readlane_b32 s16, v253, 40
	v_readlane_b32 s17, v253, 41
	v_readlane_b32 s18, v250, 4
	v_readlane_b32 s19, v250, 5
	s_nop 3
	s_lshl_b32 s0, s49, 12
	s_add_u32 s4, s4, s0
	s_addc_u32 s5, s5, 0
	global_load_dwordx4 v[2:5], v244, s[4:5]
	global_load_dwordx4 v[6:9], v244, s[4:5] offset:1024
	global_load_dwordx4 v[10:13], v244, s[4:5] offset:2048
	global_load_dwordx4 v[14:17], v244, s[4:5] offset:3072
	s_mov_b32 s12, s56
	s_mov_b32 s13, s57
	s_mov_b32 s14, s64
	s_mov_b32 s15, s65
	s_cmp_lg_u64 s[18:19], 0
	s_cbranch_scc1 .Lnorm2_last
	s_lshr_b32 s39, s20, 5
	s_lshl_b32 s39, s39, 2
	s_and_b32 s38, s20, 3
	s_or_b32 s39, s39, s38
	s_lshr_b32 s38, s20, 2
	s_and_b32 s38, s38, 7
	s_mul_i32 s37, s38, 0x900
	s_add_i32 s37, s37, s39
	s_add_i32 s21, s37, 0
	s_mul_hi_u32 s7, s21, 0x38e38e39
	s_lshr_b32 s7, s7, 9
	s_mul_i32 s8, s7, 0x900
	s_sub_i32 s8, s21, s8
	s_lshl_b32 s9, s7, 11
	s_add_i32 s9, s9, s8
	s_add_i32 s9, s9, 0xffffff00
	s_lshl_b32 s10, s7, 8
	s_add_i32 s10, s10, s8
	s_cmpk_gt_i32 s8, 0xff
	s_cselect_b32 s9, s9, s10
	s_cselect_b32 s26, s12, s14
	s_cselect_b32 s27, s13, s15
	s_cselect_b32 s10, s7, 8
	s_lshl_b32 s9, s9, 12
	s_add_u32 s26, s26, s9
	s_addc_u32 s27, s27, 0
	s_add_i32 s10, s10, s82
	s_mul_i32 s10, s10, s24
	s_add_u32 s28, s58, s10
	s_addc_u32 s29, s59, 0
	s_add_u32 s28, s28, 0x3000
	s_addc_u32 s29, s29, 0
	s_add_u32 s0, s28, 0x1000
	s_addc_u32 s1, s29, 0
	global_load_dwordx4 v[18:21], v244, s[26:27] nt
	global_load_dwordx4 v[22:25], v244, s[26:27] offset:1024 nt
	global_load_dwordx4 v[26:29], v244, s[26:27] offset:2048 nt
	global_load_dwordx4 v[30:33], v244, s[26:27] offset:3072 nt
	global_load_dwordx4 v[34:37], v244, s[28:29]
	global_load_dwordx4 v[38:41], v244, s[28:29] offset:1024
	global_load_dwordx4 v[42:45], v244, s[28:29] offset:2048
	global_load_dwordx4 v[46:49], v244, s[28:29] offset:3072
	global_load_dwordx4 v[50:53], v244, s[0:1]
	global_load_dwordx4 v[54:57], v244, s[0:1] offset:1024
	global_load_dwordx4 v[58:61], v244, s[0:1] offset:2048
	global_load_dwordx4 v[62:65], v244, s[0:1] offset:3072
	s_add_i32 s21, s37, 256
	s_mul_hi_u32 s7, s21, 0x38e38e39
	s_lshr_b32 s7, s7, 9
	s_mul_i32 s8, s7, 0x900
	s_sub_i32 s8, s21, s8
	s_lshl_b32 s9, s7, 11
	s_add_i32 s9, s9, s8
	s_add_i32 s9, s9, 0xffffff00
	s_lshl_b32 s10, s7, 8
	s_add_i32 s10, s10, s8
	s_cmpk_gt_i32 s8, 0xff
	s_cselect_b32 s9, s9, s10
	s_cselect_b32 s26, s12, s14
	s_cselect_b32 s27, s13, s15
	s_cselect_b32 s10, s7, 8
	s_lshl_b32 s9, s9, 12
	s_add_u32 s26, s26, s9
	s_addc_u32 s27, s27, 0
	s_add_i32 s10, s10, s82
	s_mul_i32 s10, s10, s24
	s_add_u32 s28, s58, s10
	s_addc_u32 s29, s59, 0
	s_add_u32 s28, s28, 0x3000
	s_addc_u32 s29, s29, 0
	s_add_u32 s0, s28, 0x1000
	s_addc_u32 s1, s29, 0
	global_load_dwordx4 v[66:69], v244, s[26:27] nt
	global_load_dwordx4 v[70:73], v244, s[26:27] offset:1024 nt
	global_load_dwordx4 v[74:77], v244, s[26:27] offset:2048 nt
	global_load_dwordx4 v[78:81], v244, s[26:27] offset:3072 nt
	global_load_dwordx4 v[82:85], v244, s[28:29]
	global_load_dwordx4 v[86:89], v244, s[28:29] offset:1024
	global_load_dwordx4 v[90:93], v244, s[28:29] offset:2048
	global_load_dwordx4 v[94:97], v244, s[28:29] offset:3072
	global_load_dwordx4 v[98:101], v244, s[0:1]
	global_load_dwordx4 v[102:105], v244, s[0:1] offset:1024
	global_load_dwordx4 v[106:109], v244, s[0:1] offset:2048
	global_load_dwordx4 v[118:121], v244, s[0:1] offset:3072
	s_add_i32 s21, s37, 512
	s_mul_hi_u32 s7, s21, 0x38e38e39
	s_lshr_b32 s7, s7, 9
	s_mul_i32 s8, s7, 0x900
	s_sub_i32 s8, s21, s8
	s_lshl_b32 s9, s7, 11
	s_add_i32 s9, s9, s8
	s_add_i32 s9, s9, 0xffffff00
	s_lshl_b32 s10, s7, 8
	s_add_i32 s10, s10, s8
	s_cmpk_gt_i32 s8, 0xff
	s_cselect_b32 s9, s9, s10
	s_cselect_b32 s26, s12, s14
	s_cselect_b32 s27, s13, s15
	s_cselect_b32 s10, s7, 8
	s_lshl_b32 s9, s9, 12
	s_add_u32 s26, s26, s9
	s_addc_u32 s27, s27, 0
	s_add_i32 s10, s10, s82
	s_mul_i32 s10, s10, s24
	s_add_u32 s28, s58, s10
	s_addc_u32 s29, s59, 0
	s_add_u32 s28, s28, 0x3000
	s_addc_u32 s29, s29, 0
	s_add_u32 s0, s28, 0x1000
	s_addc_u32 s1, s29, 0
	global_load_dwordx4 v[122:125], v244, s[26:27] nt
	global_load_dwordx4 v[126:129], v244, s[26:27] offset:1024 nt
	global_load_dwordx4 v[130:133], v244, s[26:27] offset:2048 nt
	global_load_dwordx4 v[134:137], v244, s[26:27] offset:3072 nt
	global_load_dwordx4 v[160:163], v244, s[28:29]
	global_load_dwordx4 v[164:167], v244, s[28:29] offset:1024
	global_load_dwordx4 v[168:171], v244, s[28:29] offset:2048
	global_load_dwordx4 v[172:175], v244, s[28:29] offset:3072
	global_load_dwordx4 v[176:179], v244, s[0:1]
	global_load_dwordx4 v[180:183], v244, s[0:1] offset:1024
	global_load_dwordx4 v[184:187], v244, s[0:1] offset:2048
	global_load_dwordx4 v[188:191], v244, s[0:1] offset:3072
	s_waitcnt vmcnt(24)
; DI unsigned pk_bf16(float lo, float hi) { f32x2 v = {lo, hi}; bf16v2 b = __builtin_convertvector(v, bf16v2); return __builtin_bit_cast(unsigned, b); }
; DI float red64(float x) { for (int o = 32; o > 0; o >>= 1) x += __shfl_xor(x, o); return x; }
; DI void modnorm_rows(const Params& p, int l, int which  , bool from_inputs, bool skip_ctx, int w0, int wstride, int lane) {
;     ...
;   for (; i < nrows; i += wstride) {
;     const int row = rowof(i); const int b = row / TB, s = row % TB;
;     f32x4 v[4];
; #pragma unroll
;     for (int q = 0; q < 4; ++q) v[q] = vn[q];
;     if (i + wstride < nrows) {
;       const int rn = rowof(i + wstride); const float* src = xsrc_row(p, from_inputs, rn / TB, rn % TB);
; #pragma unroll
;       for (int q = 0; q < 4; ++q) vn[q] = *(const f32x4*)(src + q * 256 + lane * 4);
;     }
;     const float* mod = p.MOD + (size_t)(l * 9 + (s < NCTX ? 8 : b)) * 6144 + (which ? 3 * 1024 : 0);
;     f32x4 sh[4], sc[4];
; #pragma unroll
;     for (int q = 0; q < 4; ++q) { sh[q] = *(const f32x4*)(mod + q * 256 + lane * 4); sc[q] = *(const f32x4*)(mod + 1024 + q * 256 + lane * 4); }
;     float ss = 0.f;
; #pragma unroll
;     for (int q = 0; q < 4; ++q) ss += v[q][0] * v[q][0] + v[q][1] * v[q][1] + v[q][2] * v[q][2] + v[q][3] * v[q][3];
;     ss = red64(ss);
;     const float rs = rsqrtf(ss * (1.f / 1024.f) + EPSF);
;     bf16_t* dst = p.HY + (size_t)row * DM;
; #pragma unroll
;     for (int q = 0; q < 4; ++q) {
;       float o[4];
; #pragma unroll
;       for (int j = 0; j < 4; ++j) o[j] = (v[q][j] * rs * gg[q][j]) * (1.f + sc[q][j]) + sh[q][j];
;       u32x2 w = {pk_bf16(o[0], o[1]), pk_bf16(o[2], o[3])};
;       *(u32x2*)(dst + q * 256 + lane * 4) = w;
;     }
;   }
	v_pk_mul_f32 v[246:247], v[18:19], v[18:19]
	v_pk_fma_f32 v[246:247], v[20:21], v[20:21], v[246:247]
	v_pk_fma_f32 v[246:247], v[22:23], v[22:23], v[246:247]
	v_pk_fma_f32 v[246:247], v[24:25], v[24:25], v[246:247]
	v_pk_fma_f32 v[246:247], v[26:27], v[26:27], v[246:247]
	v_pk_fma_f32 v[246:247], v[28:29], v[28:29], v[246:247]
	v_pk_fma_f32 v[246:247], v[30:31], v[30:31], v[246:247]
	v_pk_fma_f32 v[246:247], v[32:33], v[32:33], v[246:247]
	s_nop 0
	v_add_f32_e32 v246, v246, v247
	s_nop 1
	v_add_f32_dpp v246, v246, v246 quad_perm:[1,0,3,2] row_mask:0xf bank_mask:0xf
	s_nop 1
	v_add_f32_dpp v246, v246, v246 quad_perm:[2,3,0,1] row_mask:0xf bank_mask:0xf
	s_nop 1
	v_add_f32_dpp v246, v246, v246 row_half_mirror row_mask:0xf bank_mask:0xf
	s_nop 1
	v_add_f32_dpp v246, v246, v246 row_mirror row_mask:0xf bank_mask:0xf
	s_nop 1
	v_add_f32_dpp v246, v246, v246 row_bcast:15 row_mask:0xa bank_mask:0xf
	s_nop 1
	v_add_f32_dpp v246, v246, v246 row_bcast:31 row_mask:0xc bank_mask:0xf
	s_nop 1
	v_readlane_b32 s0, v246, 63
	s_add_i32 s21, s37, 0
	s_lshl_b32 s21, s21, 11
	s_add_u32 s10, s16, s21
	s_addc_u32 s11, s17, 0
	v_mov_b32_e32 v248, s0
	v_fmamk_f32 v248, v248, 0x3a800000, v143
	v_rsq_f32_e32 v248, v248
	s_nop 0
	v_pk_mul_f32 v[18:19], v[18:19], v[248:249] op_sel_hi:[1,0]
	v_pk_add_f32 v[50:51], v[50:51], 1.0 op_sel_hi:[1,0]
	v_pk_mul_f32 v[18:19], v[2:3], v[18:19]
	v_pk_fma_f32 v[18:19], v[50:51], v[18:19], v[34:35]
	v_pk_mul_f32 v[20:21], v[20:21], v[248:249] op_sel_hi:[1,0]
	v_pk_add_f32 v[52:53], v[52:53], 1.0 op_sel_hi:[1,0]
	v_pk_mul_f32 v[20:21], v[4:5], v[20:21]
	v_pk_fma_f32 v[20:21], v[52:53], v[20:21], v[36:37]
	v_cvt_pk_bf16_f32 v34, v18, v19
	v_cvt_pk_bf16_f32 v35, v20, v21
	global_store_dwordx2 v245, v[34:35], s[10:11]
	v_pk_mul_f32 v[22:23], v[22:23], v[248:249] op_sel_hi:[1,0]
	v_pk_add_f32 v[54:55], v[54:55], 1.0 op_sel_hi:[1,0]
	v_pk_mul_f32 v[22:23], v[6:7], v[22:23]
	v_pk_fma_f32 v[22:23], v[54:55], v[22:23], v[38:39]
	v_pk_mul_f32 v[24:25], v[24:25], v[248:249] op_sel_hi:[1,0]
	v_pk_add_f32 v[56:57], v[56:57], 1.0 op_sel_hi:[1,0]
	v_pk_mul_f32 v[24:25], v[8:9], v[24:25]
	v_pk_fma_f32 v[24:25], v[56:57], v[24:25], v[40:41]
	v_cvt_pk_bf16_f32 v38, v22, v23
	v_cvt_pk_bf16_f32 v39, v24, v25
	global_store_dwordx2 v245, v[38:39], s[10:11] offset:512
	v_pk_mul_f32 v[26:27], v[26:27], v[248:249] op_sel_hi:[1,0]
	v_pk_add_f32 v[58:59], v[58:59], 1.0 op_sel_hi:[1,0]
	v_pk_mul_f32 v[26:27], v[10:11], v[26:27]
	v_pk_fma_f32 v[26:27], v[58:59], v[26:27], v[42:43]
	v_pk_mul_f32 v[28:29], v[28:29], v[248:249] op_sel_hi:[1,0]
	v_pk_add_f32 v[60:61], v[60:61], 1.0 op_sel_hi:[1,0]
	v_pk_mul_f32 v[28:29], v[12:13], v[28:29]
	v_pk_fma_f32 v[28:29], v[60:61], v[28:29], v[44:45]
	v_cvt_pk_bf16_f32 v42, v26, v27
	v_cvt_pk_bf16_f32 v43, v28, v29
	global_store_dwordx2 v245, v[42:43], s[10:11] offset:1024
	v_pk_mul_f32 v[30:31], v[30:31], v[248:249] op_sel_hi:[1,0]
	v_pk_add_f32 v[62:63], v[62:63], 1.0 op_sel_hi:[1,0]
	v_pk_mul_f32 v[30:31], v[14:15], v[30:31]
	v_pk_fma_f32 v[30:31], v[62:63], v[30:31], v[46:47]
	v_pk_mul_f32 v[32:33], v[32:33], v[248:249] op_sel_hi:[1,0]
	v_pk_add_f32 v[64:65], v[64:65], 1.0 op_sel_hi:[1,0]
	v_pk_mul_f32 v[32:33], v[16:17], v[32:33]
	v_pk_fma_f32 v[32:33], v[64:65], v[32:33], v[48:49]
	v_cvt_pk_bf16_f32 v46, v30, v31
	v_cvt_pk_bf16_f32 v47, v32, v33
	global_store_dwordx2 v245, v[46:47], s[10:11] offset:1536
	s_add_i32 s21, s37, 768
	s_mul_hi_u32 s7, s21, 0x38e38e39
	s_lshr_b32 s7, s7, 9
	s_mul_i32 s8, s7, 0x900
	s_sub_i32 s8, s21, s8
	s_lshl_b32 s9, s7, 11
	s_add_i32 s9, s9, s8
	s_add_i32 s9, s9, 0xffffff00
	s_lshl_b32 s10, s7, 8
	s_add_i32 s10, s10, s8
	s_cmpk_gt_i32 s8, 0xff
	s_cselect_b32 s9, s9, s10
	s_cselect_b32 s26, s12, s14
	s_cselect_b32 s27, s13, s15
	s_cselect_b32 s10, s7, 8
	s_lshl_b32 s9, s9, 12
	s_add_u32 s26, s26, s9
	s_addc_u32 s27, s27, 0
	s_add_i32 s10, s10, s82
	s_mul_i32 s10, s10, s24
	s_add_u32 s28, s58, s10
	s_addc_u32 s29, s59, 0
	s_add_u32 s28, s28, 0x3000
	s_addc_u32 s29, s29, 0
	s_add_u32 s0, s28, 0x1000
	s_addc_u32 s1, s29, 0
	global_load_dwordx4 v[18:21], v244, s[26:27] nt
	global_load_dwordx4 v[22:25], v244, s[26:27] offset:1024 nt
	global_load_dwordx4 v[26:29], v244, s[26:27] offset:2048 nt
	global_load_dwordx4 v[30:33], v244, s[26:27] offset:3072 nt
	global_load_dwordx4 v[34:37], v244, s[28:29]
	global_load_dwordx4 v[38:41], v244, s[28:29] offset:1024
	global_load_dwordx4 v[42:45], v244, s[28:29] offset:2048
	global_load_dwordx4 v[46:49], v244, s[28:29] offset:3072
	global_load_dwordx4 v[50:53], v244, s[0:1]
	global_load_dwordx4 v[54:57], v244, s[0:1] offset:1024
	global_load_dwordx4 v[58:61], v244, s[0:1] offset:2048
	global_load_dwordx4 v[62:65], v244, s[0:1] offset:3072
	s_waitcnt vmcnt(28)
; DI unsigned pk_bf16(float lo, float hi) { f32x2 v = {lo, hi}; bf16v2 b = __builtin_convertvector(v, bf16v2); return __builtin_bit_cast(unsigned, b); }
; DI float red64(float x) { for (int o = 32; o > 0; o >>= 1) x += __shfl_xor(x, o); return x; }
; DI void modnorm_rows(const Params& p, int l, int which  , bool from_inputs, bool skip_ctx, int w0, int wstride, int lane) {
;     ...
;   for (; i < nrows; i += wstride) {
;     const int row = rowof(i); const int b = row / TB, s = row % TB;
;     f32x4 v[4];
; #pragma unroll
;     for (int q = 0; q < 4; ++q) v[q] = vn[q];
;     if (i + wstride < nrows) {
;       const int rn = rowof(i + wstride); const float* src = xsrc_row(p, from_inputs, rn / TB, rn % TB);
; #pragma unroll
;       for (int q = 0; q < 4; ++q) vn[q] = *(const f32x4*)(src + q * 256 + lane * 4);
;     }
;     const float* mod = p.MOD + (size_t)(l * 9 + (s < NCTX ? 8 : b)) * 6144 + (which ? 3 * 1024 : 0);
;     f32x4 sh[4], sc[4];
; #pragma unroll
;     for (int q = 0; q < 4; ++q) { sh[q] = *(const f32x4*)(mod + q * 256 + lane * 4); sc[q] = *(const f32x4*)(mod + 1024 + q * 256 + lane * 4); }
;     float ss = 0.f;
; #pragma unroll
;     for (int q = 0; q < 4; ++q) ss += v[q][0] * v[q][0] + v[q][1] * v[q][1] + v[q][2] * v[q][2] + v[q][3] * v[q][3];
;     ss = red64(ss);
;     const float rs = rsqrtf(ss * (1.f / 1024.f) + EPSF);
;     bf16_t* dst = p.HY + (size_t)row * DM;
; #pragma unroll
;     for (int q = 0; q < 4; ++q) {
;       float o[4];
; #pragma unroll
;       for (int j = 0; j < 4; ++j) o[j] = (v[q][j] * rs * gg[q][j]) * (1.f + sc[q][j]) + sh[q][j];
;       u32x2 w = {pk_bf16(o[0], o[1]), pk_bf16(o[2], o[3])};
;       *(u32x2*)(dst + q * 256 + lane * 4) = w;
;     }
;   }
	v_pk_mul_f32 v[246:247], v[66:67], v[66:67]
	v_pk_fma_f32 v[246:247], v[68:69], v[68:69], v[246:247]
	v_pk_fma_f32 v[246:247], v[70:71], v[70:71], v[246:247]
	v_pk_fma_f32 v[246:247], v[72:73], v[72:73], v[246:247]
	v_pk_fma_f32 v[246:247], v[74:75], v[74:75], v[246:247]
	v_pk_fma_f32 v[246:247], v[76:77], v[76:77], v[246:247]
	v_pk_fma_f32 v[246:247], v[78:79], v[78:79], v[246:247]
	v_pk_fma_f32 v[246:247], v[80:81], v[80:81], v[246:247]
	s_nop 0
	v_add_f32_e32 v246, v246, v247
	s_nop 1
	v_add_f32_dpp v246, v246, v246 quad_perm:[1,0,3,2] row_mask:0xf bank_mask:0xf
	s_nop 1
	v_add_f32_dpp v246, v246, v246 quad_perm:[2,3,0,1] row_mask:0xf bank_mask:0xf
	s_nop 1
	v_add_f32_dpp v246, v246, v246 row_half_mirror row_mask:0xf bank_mask:0xf
	s_nop 1
	v_add_f32_dpp v246, v246, v246 row_mirror row_mask:0xf bank_mask:0xf
	s_nop 1
	v_add_f32_dpp v246, v246, v246 row_bcast:15 row_mask:0xa bank_mask:0xf
	s_nop 1
	v_add_f32_dpp v246, v246, v246 row_bcast:31 row_mask:0xc bank_mask:0xf
	s_nop 1
	v_readlane_b32 s0, v246, 63
	s_add_i32 s21, s37, 256
	s_lshl_b32 s21, s21, 11
	s_add_u32 s10, s16, s21
	s_addc_u32 s11, s17, 0
	v_mov_b32_e32 v248, s0
	v_fmamk_f32 v248, v248, 0x3a800000, v143
	v_rsq_f32_e32 v248, v248
	s_nop 0
	v_pk_mul_f32 v[66:67], v[66:67], v[248:249] op_sel_hi:[1,0]
	v_pk_add_f32 v[98:99], v[98:99], 1.0 op_sel_hi:[1,0]
	v_pk_mul_f32 v[66:67], v[2:3], v[66:67]
	v_pk_fma_f32 v[66:67], v[98:99], v[66:67], v[82:83]
	v_pk_mul_f32 v[68:69], v[68:69], v[248:249] op_sel_hi:[1,0]
	v_pk_add_f32 v[100:101], v[100:101], 1.0 op_sel_hi:[1,0]
	v_pk_mul_f32 v[68:69], v[4:5], v[68:69]
	v_pk_fma_f32 v[68:69], v[100:101], v[68:69], v[84:85]
	v_cvt_pk_bf16_f32 v82, v66, v67
	v_cvt_pk_bf16_f32 v83, v68, v69
	global_store_dwordx2 v245, v[82:83], s[10:11]
	v_pk_mul_f32 v[70:71], v[70:71], v[248:249] op_sel_hi:[1,0]
	v_pk_add_f32 v[102:103], v[102:103], 1.0 op_sel_hi:[1,0]
	v_pk_mul_f32 v[70:71], v[6:7], v[70:71]
	v_pk_fma_f32 v[70:71], v[102:103], v[70:71], v[86:87]
	v_pk_mul_f32 v[72:73], v[72:73], v[248:249] op_sel_hi:[1,0]
	v_pk_add_f32 v[104:105], v[104:105], 1.0 op_sel_hi:[1,0]
	v_pk_mul_f32 v[72:73], v[8:9], v[72:73]
	v_pk_fma_f32 v[72:73], v[104:105], v[72:73], v[88:89]
	v_cvt_pk_bf16_f32 v86, v70, v71
	v_cvt_pk_bf16_f32 v87, v72, v73
	global_store_dwordx2 v245, v[86:87], s[10:11] offset:512
	v_pk_mul_f32 v[74:75], v[74:75], v[248:249] op_sel_hi:[1,0]
	v_pk_add_f32 v[106:107], v[106:107], 1.0 op_sel_hi:[1,0]
	v_pk_mul_f32 v[74:75], v[10:11], v[74:75]
	v_pk_fma_f32 v[74:75], v[106:107], v[74:75], v[90:91]
	v_pk_mul_f32 v[76:77], v[76:77], v[248:249] op_sel_hi:[1,0]
	v_pk_add_f32 v[108:109], v[108:109], 1.0 op_sel_hi:[1,0]
	v_pk_mul_f32 v[76:77], v[12:13], v[76:77]
	v_pk_fma_f32 v[76:77], v[108:109], v[76:77], v[92:93]
	v_cvt_pk_bf16_f32 v90, v74, v75
	v_cvt_pk_bf16_f32 v91, v76, v77
	global_store_dwordx2 v245, v[90:91], s[10:11] offset:1024
	v_pk_mul_f32 v[78:79], v[78:79], v[248:249] op_sel_hi:[1,0]
	v_pk_add_f32 v[118:119], v[118:119], 1.0 op_sel_hi:[1,0]
	v_pk_mul_f32 v[78:79], v[14:15], v[78:79]
	v_pk_fma_f32 v[78:79], v[118:119], v[78:79], v[94:95]
	v_pk_mul_f32 v[80:81], v[80:81], v[248:249] op_sel_hi:[1,0]
	v_pk_add_f32 v[120:121], v[120:121], 1.0 op_sel_hi:[1,0]
	v_pk_mul_f32 v[80:81], v[16:17], v[80:81]
	v_pk_fma_f32 v[80:81], v[120:121], v[80:81], v[96:97]
	v_cvt_pk_bf16_f32 v94, v78, v79
	v_cvt_pk_bf16_f32 v95, v80, v81
	global_store_dwordx2 v245, v[94:95], s[10:11] offset:1536
	s_add_i32 s21, s37, 1024
	s_mul_hi_u32 s7, s21, 0x38e38e39
	s_lshr_b32 s7, s7, 9
	s_mul_i32 s8, s7, 0x900
	s_sub_i32 s8, s21, s8
	s_lshl_b32 s9, s7, 11
	s_add_i32 s9, s9, s8
	s_add_i32 s9, s9, 0xffffff00
	s_lshl_b32 s10, s7, 8
	s_add_i32 s10, s10, s8
	s_cmpk_gt_i32 s8, 0xff
	s_cselect_b32 s9, s9, s10
	s_cselect_b32 s26, s12, s14
	s_cselect_b32 s27, s13, s15
	s_cselect_b32 s10, s7, 8
	s_lshl_b32 s9, s9, 12
	s_add_u32 s26, s26, s9
	s_addc_u32 s27, s27, 0
	s_add_i32 s10, s10, s82
	s_mul_i32 s10, s10, s24
	s_add_u32 s28, s58, s10
	s_addc_u32 s29, s59, 0
	s_add_u32 s28, s28, 0x3000
	s_addc_u32 s29, s29, 0
	s_add_u32 s0, s28, 0x1000
	s_addc_u32 s1, s29, 0
	global_load_dwordx4 v[66:69], v244, s[26:27] nt
	global_load_dwordx4 v[70:73], v244, s[26:27] offset:1024 nt
	global_load_dwordx4 v[74:77], v244, s[26:27] offset:2048 nt
	global_load_dwordx4 v[78:81], v244, s[26:27] offset:3072 nt
	global_load_dwordx4 v[82:85], v244, s[28:29]
	global_load_dwordx4 v[86:89], v244, s[28:29] offset:1024
	global_load_dwordx4 v[90:93], v244, s[28:29] offset:2048
	global_load_dwordx4 v[94:97], v244, s[28:29] offset:3072
	global_load_dwordx4 v[98:101], v244, s[0:1]
	global_load_dwordx4 v[102:105], v244, s[0:1] offset:1024
	global_load_dwordx4 v[106:109], v244, s[0:1] offset:2048
	global_load_dwordx4 v[118:121], v244, s[0:1] offset:3072
	s_waitcnt vmcnt(32)
; DI unsigned pk_bf16(float lo, float hi) { f32x2 v = {lo, hi}; bf16v2 b = __builtin_convertvector(v, bf16v2); return __builtin_bit_cast(unsigned, b); }
; DI float red64(float x) { for (int o = 32; o > 0; o >>= 1) x += __shfl_xor(x, o); return x; }
; DI void modnorm_rows(const Params& p, int l, int which  , bool from_inputs, bool skip_ctx, int w0, int wstride, int lane) {
;     ...
;   for (; i < nrows; i += wstride) {
;     const int row = rowof(i); const int b = row / TB, s = row % TB;
;     f32x4 v[4];
; #pragma unroll
;     for (int q = 0; q < 4; ++q) v[q] = vn[q];
;     if (i + wstride < nrows) {
;       const int rn = rowof(i + wstride); const float* src = xsrc_row(p, from_inputs, rn / TB, rn % TB);
; #pragma unroll
;       for (int q = 0; q < 4; ++q) vn[q] = *(const f32x4*)(src + q * 256 + lane * 4);
;     }
;     const float* mod = p.MOD + (size_t)(l * 9 + (s < NCTX ? 8 : b)) * 6144 + (which ? 3 * 1024 : 0);
;     f32x4 sh[4], sc[4];
; #pragma unroll
;     for (int q = 0; q < 4; ++q) { sh[q] = *(const f32x4*)(mod + q * 256 + lane * 4); sc[q] = *(const f32x4*)(mod + 1024 + q * 256 + lane * 4); }
;     float ss = 0.f;
; #pragma unroll
;     for (int q = 0; q < 4; ++q) ss += v[q][0] * v[q][0] + v[q][1] * v[q][1] + v[q][2] * v[q][2] + v[q][3] * v[q][3];
;     ss = red64(ss);
;     const float rs = rsqrtf(ss * (1.f / 1024.f) + EPSF);
;     bf16_t* dst = p.HY + (size_t)row * DM;
; #pragma unroll
;     for (int q = 0; q < 4; ++q) {
;       float o[4];
; #pragma unroll
;       for (int j = 0; j < 4; ++j) o[j] = (v[q][j] * rs * gg[q][j]) * (1.f + sc[q][j]) + sh[q][j];
;       u32x2 w = {pk_bf16(o[0], o[1]), pk_bf16(o[2], o[3])};
;       *(u32x2*)(dst + q * 256 + lane * 4) = w;
;     }
;   }
	v_pk_mul_f32 v[246:247], v[122:123], v[122:123]
	v_pk_fma_f32 v[246:247], v[124:125], v[124:125], v[246:247]
	v_pk_fma_f32 v[246:247], v[126:127], v[126:127], v[246:247]
	v_pk_fma_f32 v[246:247], v[128:129], v[128:129], v[246:247]
	v_pk_fma_f32 v[246:247], v[130:131], v[130:131], v[246:247]
	v_pk_fma_f32 v[246:247], v[132:133], v[132:133], v[246:247]
	v_pk_fma_f32 v[246:247], v[134:135], v[134:135], v[246:247]
	v_pk_fma_f32 v[246:247], v[136:137], v[136:137], v[246:247]
	s_nop 0
	v_add_f32_e32 v246, v246, v247
	s_nop 1
	v_add_f32_dpp v246, v246, v246 quad_perm:[1,0,3,2] row_mask:0xf bank_mask:0xf
	s_nop 1
	v_add_f32_dpp v246, v246, v246 quad_perm:[2,3,0,1] row_mask:0xf bank_mask:0xf
	s_nop 1
	v_add_f32_dpp v246, v246, v246 row_half_mirror row_mask:0xf bank_mask:0xf
	s_nop 1
	v_add_f32_dpp v246, v246, v246 row_mirror row_mask:0xf bank_mask:0xf
	s_nop 1
	v_add_f32_dpp v246, v246, v246 row_bcast:15 row_mask:0xa bank_mask:0xf
	s_nop 1
	v_add_f32_dpp v246, v246, v246 row_bcast:31 row_mask:0xc bank_mask:0xf
	s_nop 1
	v_readlane_b32 s0, v246, 63
	s_add_i32 s21, s37, 512
	s_lshl_b32 s21, s21, 11
	s_add_u32 s10, s16, s21
	s_addc_u32 s11, s17, 0
	v_mov_b32_e32 v248, s0
	v_fmamk_f32 v248, v248, 0x3a800000, v143
	v_rsq_f32_e32 v248, v248
	s_nop 0
	v_pk_mul_f32 v[122:123], v[122:123], v[248:249] op_sel_hi:[1,0]
	v_pk_add_f32 v[176:177], v[176:177], 1.0 op_sel_hi:[1,0]
	v_pk_mul_f32 v[122:123], v[2:3], v[122:123]
	v_pk_fma_f32 v[122:123], v[176:177], v[122:123], v[160:161]
	v_pk_mul_f32 v[124:125], v[124:125], v[248:249] op_sel_hi:[1,0]
	v_pk_add_f32 v[178:179], v[178:179], 1.0 op_sel_hi:[1,0]
	v_pk_mul_f32 v[124:125], v[4:5], v[124:125]
	v_pk_fma_f32 v[124:125], v[178:179], v[124:125], v[162:163]
	v_cvt_pk_bf16_f32 v160, v122, v123
	v_cvt_pk_bf16_f32 v161, v124, v125
	global_store_dwordx2 v245, v[160:161], s[10:11]
	v_pk_mul_f32 v[126:127], v[126:127], v[248:249] op_sel_hi:[1,0]
	v_pk_add_f32 v[180:181], v[180:181], 1.0 op_sel_hi:[1,0]
	v_pk_mul_f32 v[126:127], v[6:7], v[126:127]
	v_pk_fma_f32 v[126:127], v[180:181], v[126:127], v[164:165]
	v_pk_mul_f32 v[128:129], v[128:129], v[248:249] op_sel_hi:[1,0]
	v_pk_add_f32 v[182:183], v[182:183], 1.0 op_sel_hi:[1,0]
	v_pk_mul_f32 v[128:129], v[8:9], v[128:129]
	v_pk_fma_f32 v[128:129], v[182:183], v[128:129], v[166:167]
	v_cvt_pk_bf16_f32 v164, v126, v127
	v_cvt_pk_bf16_f32 v165, v128, v129
	global_store_dwordx2 v245, v[164:165], s[10:11] offset:512
	v_pk_mul_f32 v[130:131], v[130:131], v[248:249] op_sel_hi:[1,0]
	v_pk_add_f32 v[184:185], v[184:185], 1.0 op_sel_hi:[1,0]
	v_pk_mul_f32 v[130:131], v[10:11], v[130:131]
	v_pk_fma_f32 v[130:131], v[184:185], v[130:131], v[168:169]
	v_pk_mul_f32 v[132:133], v[132:133], v[248:249] op_sel_hi:[1,0]
	v_pk_add_f32 v[186:187], v[186:187], 1.0 op_sel_hi:[1,0]
	v_pk_mul_f32 v[132:133], v[12:13], v[132:133]
	v_pk_fma_f32 v[132:133], v[186:187], v[132:133], v[170:171]
	v_cvt_pk_bf16_f32 v168, v130, v131
	v_cvt_pk_bf16_f32 v169, v132, v133
	global_store_dwordx2 v245, v[168:169], s[10:11] offset:1024
	v_pk_mul_f32 v[134:135], v[134:135], v[248:249] op_sel_hi:[1,0]
	v_pk_add_f32 v[188:189], v[188:189], 1.0 op_sel_hi:[1,0]
	v_pk_mul_f32 v[134:135], v[14:15], v[134:135]
	v_pk_fma_f32 v[134:135], v[188:189], v[134:135], v[172:173]
	v_pk_mul_f32 v[136:137], v[136:137], v[248:249] op_sel_hi:[1,0]
	v_pk_add_f32 v[190:191], v[190:191], 1.0 op_sel_hi:[1,0]
	v_pk_mul_f32 v[136:137], v[16:17], v[136:137]
	v_pk_fma_f32 v[136:137], v[190:191], v[136:137], v[174:175]
	v_cvt_pk_bf16_f32 v172, v134, v135
	v_cvt_pk_bf16_f32 v173, v136, v137
	global_store_dwordx2 v245, v[172:173], s[10:11] offset:1536
	s_add_i32 s21, s37, 1280
	s_mul_hi_u32 s7, s21, 0x38e38e39
	s_lshr_b32 s7, s7, 9
	s_mul_i32 s8, s7, 0x900
	s_sub_i32 s8, s21, s8
	s_lshl_b32 s9, s7, 11
	s_add_i32 s9, s9, s8
	s_add_i32 s9, s9, 0xffffff00
	s_lshl_b32 s10, s7, 8
	s_add_i32 s10, s10, s8
	s_cmpk_gt_i32 s8, 0xff
	s_cselect_b32 s9, s9, s10
	s_cselect_b32 s26, s12, s14
	s_cselect_b32 s27, s13, s15
	s_cselect_b32 s10, s7, 8
	s_lshl_b32 s9, s9, 12
	s_add_u32 s26, s26, s9
	s_addc_u32 s27, s27, 0
	s_add_i32 s10, s10, s82
	s_mul_i32 s10, s10, s24
	s_add_u32 s28, s58, s10
	s_addc_u32 s29, s59, 0
	s_add_u32 s28, s28, 0x3000
	s_addc_u32 s29, s29, 0
	s_add_u32 s0, s28, 0x1000
	s_addc_u32 s1, s29, 0
	global_load_dwordx4 v[122:125], v244, s[26:27] nt
	global_load_dwordx4 v[126:129], v244, s[26:27] offset:1024 nt
	global_load_dwordx4 v[130:133], v244, s[26:27] offset:2048 nt
	global_load_dwordx4 v[134:137], v244, s[26:27] offset:3072 nt
	global_load_dwordx4 v[160:163], v244, s[28:29]
	global_load_dwordx4 v[164:167], v244, s[28:29] offset:1024
	global_load_dwordx4 v[168:171], v244, s[28:29] offset:2048
	global_load_dwordx4 v[172:175], v244, s[28:29] offset:3072
	global_load_dwordx4 v[176:179], v244, s[0:1]
	global_load_dwordx4 v[180:183], v244, s[0:1] offset:1024
	global_load_dwordx4 v[184:187], v244, s[0:1] offset:2048
	global_load_dwordx4 v[188:191], v244, s[0:1] offset:3072
	s_waitcnt vmcnt(32)
; DI unsigned pk_bf16(float lo, float hi) { f32x2 v = {lo, hi}; bf16v2 b = __builtin_convertvector(v, bf16v2); return __builtin_bit_cast(unsigned, b); }
; DI float red64(float x) { for (int o = 32; o > 0; o >>= 1) x += __shfl_xor(x, o); return x; }
; DI void modnorm_rows(const Params& p, int l, int which  , bool from_inputs, bool skip_ctx, int w0, int wstride, int lane) {
;     ...
;   for (; i < nrows; i += wstride) {
;     const int row = rowof(i); const int b = row / TB, s = row % TB;
;     f32x4 v[4];
; #pragma unroll
;     for (int q = 0; q < 4; ++q) v[q] = vn[q];
;     if (i + wstride < nrows) {
;       const int rn = rowof(i + wstride); const float* src = xsrc_row(p, from_inputs, rn / TB, rn % TB);
; #pragma unroll
;       for (int q = 0; q < 4; ++q) vn[q] = *(const f32x4*)(src + q * 256 + lane * 4);
;     }
;     const float* mod = p.MOD + (size_t)(l * 9 + (s < NCTX ? 8 : b)) * 6144 + (which ? 3 * 1024 : 0);
;     f32x4 sh[4], sc[4];
; #pragma unroll
;     for (int q = 0; q < 4; ++q) { sh[q] = *(const f32x4*)(mod + q * 256 + lane * 4); sc[q] = *(const f32x4*)(mod + 1024 + q * 256 + lane * 4); }
;     float ss = 0.f;
; #pragma unroll
;     for (int q = 0; q < 4; ++q) ss += v[q][0] * v[q][0] + v[q][1] * v[q][1] + v[q][2] * v[q][2] + v[q][3] * v[q][3];
;     ss = red64(ss);
;     const float rs = rsqrtf(ss * (1.f / 1024.f) + EPSF);
;     bf16_t* dst = p.HY + (size_t)row * DM;
; #pragma unroll
;     for (int q = 0; q < 4; ++q) {
;       float o[4];
; #pragma unroll
;       for (int j = 0; j < 4; ++j) o[j] = (v[q][j] * rs * gg[q][j]) * (1.f + sc[q][j]) + sh[q][j];
;       u32x2 w = {pk_bf16(o[0], o[1]), pk_bf16(o[2], o[3])};
;       *(u32x2*)(dst + q * 256 + lane * 4) = w;
;     }
;   }
	v_pk_mul_f32 v[246:247], v[18:19], v[18:19]
	v_pk_fma_f32 v[246:247], v[20:21], v[20:21], v[246:247]
	v_pk_fma_f32 v[246:247], v[22:23], v[22:23], v[246:247]
	v_pk_fma_f32 v[246:247], v[24:25], v[24:25], v[246:247]
	v_pk_fma_f32 v[246:247], v[26:27], v[26:27], v[246:247]
	v_pk_fma_f32 v[246:247], v[28:29], v[28:29], v[246:247]
	v_pk_fma_f32 v[246:247], v[30:31], v[30:31], v[246:247]
	v_pk_fma_f32 v[246:247], v[32:33], v[32:33], v[246:247]
	s_nop 0
	v_add_f32_e32 v246, v246, v247
	s_nop 1
	v_add_f32_dpp v246, v246, v246 quad_perm:[1,0,3,2] row_mask:0xf bank_mask:0xf
	s_nop 1
	v_add_f32_dpp v246, v246, v246 quad_perm:[2,3,0,1] row_mask:0xf bank_mask:0xf
	s_nop 1
	v_add_f32_dpp v246, v246, v246 row_half_mirror row_mask:0xf bank_mask:0xf
	s_nop 1
	v_add_f32_dpp v246, v246, v246 row_mirror row_mask:0xf bank_mask:0xf
	s_nop 1
	v_add_f32_dpp v246, v246, v246 row_bcast:15 row_mask:0xa bank_mask:0xf
	s_nop 1
	v_add_f32_dpp v246, v246, v246 row_bcast:31 row_mask:0xc bank_mask:0xf
	s_nop 1
	v_readlane_b32 s0, v246, 63
	s_add_i32 s21, s37, 768
	s_lshl_b32 s21, s21, 11
	s_add_u32 s10, s16, s21
	s_addc_u32 s11, s17, 0
	v_mov_b32_e32 v248, s0
	v_fmamk_f32 v248, v248, 0x3a800000, v143
	v_rsq_f32_e32 v248, v248
	s_nop 0
	v_pk_mul_f32 v[18:19], v[18:19], v[248:249] op_sel_hi:[1,0]
	v_pk_add_f32 v[50:51], v[50:51], 1.0 op_sel_hi:[1,0]
	v_pk_mul_f32 v[18:19], v[2:3], v[18:19]
	v_pk_fma_f32 v[18:19], v[50:51], v[18:19], v[34:35]
	v_pk_mul_f32 v[20:21], v[20:21], v[248:249] op_sel_hi:[1,0]
	v_pk_add_f32 v[52:53], v[52:53], 1.0 op_sel_hi:[1,0]
	v_pk_mul_f32 v[20:21], v[4:5], v[20:21]
	v_pk_fma_f32 v[20:21], v[52:53], v[20:21], v[36:37]
	v_cvt_pk_bf16_f32 v34, v18, v19
	v_cvt_pk_bf16_f32 v35, v20, v21
	global_store_dwordx2 v245, v[34:35], s[10:11]
	v_pk_mul_f32 v[22:23], v[22:23], v[248:249] op_sel_hi:[1,0]
	v_pk_add_f32 v[54:55], v[54:55], 1.0 op_sel_hi:[1,0]
	v_pk_mul_f32 v[22:23], v[6:7], v[22:23]
	v_pk_fma_f32 v[22:23], v[54:55], v[22:23], v[38:39]
	v_pk_mul_f32 v[24:25], v[24:25], v[248:249] op_sel_hi:[1,0]
	v_pk_add_f32 v[56:57], v[56:57], 1.0 op_sel_hi:[1,0]
	v_pk_mul_f32 v[24:25], v[8:9], v[24:25]
	v_pk_fma_f32 v[24:25], v[56:57], v[24:25], v[40:41]
	v_cvt_pk_bf16_f32 v38, v22, v23
	v_cvt_pk_bf16_f32 v39, v24, v25
	global_store_dwordx2 v245, v[38:39], s[10:11] offset:512
	v_pk_mul_f32 v[26:27], v[26:27], v[248:249] op_sel_hi:[1,0]
	v_pk_add_f32 v[58:59], v[58:59], 1.0 op_sel_hi:[1,0]
	v_pk_mul_f32 v[26:27], v[10:11], v[26:27]
	v_pk_fma_f32 v[26:27], v[58:59], v[26:27], v[42:43]
	v_pk_mul_f32 v[28:29], v[28:29], v[248:249] op_sel_hi:[1,0]
	v_pk_add_f32 v[60:61], v[60:61], 1.0 op_sel_hi:[1,0]
	v_pk_mul_f32 v[28:29], v[12:13], v[28:29]
	v_pk_fma_f32 v[28:29], v[60:61], v[28:29], v[44:45]
	v_cvt_pk_bf16_f32 v42, v26, v27
	v_cvt_pk_bf16_f32 v43, v28, v29
	global_store_dwordx2 v245, v[42:43], s[10:11] offset:1024
	v_pk_mul_f32 v[30:31], v[30:31], v[248:249] op_sel_hi:[1,0]
	v_pk_add_f32 v[62:63], v[62:63], 1.0 op_sel_hi:[1,0]
	v_pk_mul_f32 v[30:31], v[14:15], v[30:31]
	v_pk_fma_f32 v[30:31], v[62:63], v[30:31], v[46:47]
	v_pk_mul_f32 v[32:33], v[32:33], v[248:249] op_sel_hi:[1,0]
	v_pk_add_f32 v[64:65], v[64:65], 1.0 op_sel_hi:[1,0]
	v_pk_mul_f32 v[32:33], v[16:17], v[32:33]
	v_pk_fma_f32 v[32:33], v[64:65], v[32:33], v[48:49]
	v_cvt_pk_bf16_f32 v46, v30, v31
	v_cvt_pk_bf16_f32 v47, v32, v33
	global_store_dwordx2 v245, v[46:47], s[10:11] offset:1536
	s_add_i32 s21, s37, 1536
	s_mul_hi_u32 s7, s21, 0x38e38e39
	s_lshr_b32 s7, s7, 9
	s_mul_i32 s8, s7, 0x900
	s_sub_i32 s8, s21, s8
	s_lshl_b32 s9, s7, 11
	s_add_i32 s9, s9, s8
	s_add_i32 s9, s9, 0xffffff00
	s_lshl_b32 s10, s7, 8
	s_add_i32 s10, s10, s8
	s_cmpk_gt_i32 s8, 0xff
	s_cselect_b32 s9, s9, s10
	s_cselect_b32 s26, s12, s14
	s_cselect_b32 s27, s13, s15
	s_cselect_b32 s10, s7, 8
	s_lshl_b32 s9, s9, 12
	s_add_u32 s26, s26, s9
	s_addc_u32 s27, s27, 0
	s_add_i32 s10, s10, s82
	s_mul_i32 s10, s10, s24
	s_add_u32 s28, s58, s10
	s_addc_u32 s29, s59, 0
	s_add_u32 s28, s28, 0x3000
	s_addc_u32 s29, s29, 0
	s_add_u32 s0, s28, 0x1000
	s_addc_u32 s1, s29, 0
	global_load_dwordx4 v[18:21], v244, s[26:27] nt
	global_load_dwordx4 v[22:25], v244, s[26:27] offset:1024 nt
	global_load_dwordx4 v[26:29], v244, s[26:27] offset:2048 nt
	global_load_dwordx4 v[30:33], v244, s[26:27] offset:3072 nt
	global_load_dwordx4 v[34:37], v244, s[28:29]
	global_load_dwordx4 v[38:41], v244, s[28:29] offset:1024
	global_load_dwordx4 v[42:45], v244, s[28:29] offset:2048
	global_load_dwordx4 v[46:49], v244, s[28:29] offset:3072
	global_load_dwordx4 v[50:53], v244, s[0:1]
	global_load_dwordx4 v[54:57], v244, s[0:1] offset:1024
	global_load_dwordx4 v[58:61], v244, s[0:1] offset:2048
	global_load_dwordx4 v[62:65], v244, s[0:1] offset:3072
	s_waitcnt vmcnt(32)
; DI unsigned pk_bf16(float lo, float hi) { f32x2 v = {lo, hi}; bf16v2 b = __builtin_convertvector(v, bf16v2); return __builtin_bit_cast(unsigned, b); }
; DI float red64(float x) { for (int o = 32; o > 0; o >>= 1) x += __shfl_xor(x, o); return x; }
; DI void modnorm_rows(const Params& p, int l, int which  , bool from_inputs, bool skip_ctx, int w0, int wstride, int lane) {
;     ...
;   for (; i < nrows; i += wstride) {
;     const int row = rowof(i); const int b = row / TB, s = row % TB;
;     f32x4 v[4];
; #pragma unroll
;     for (int q = 0; q < 4; ++q) v[q] = vn[q];
;     if (i + wstride < nrows) {
;       const int rn = rowof(i + wstride); const float* src = xsrc_row(p, from_inputs, rn / TB, rn % TB);
; #pragma unroll
;       for (int q = 0; q < 4; ++q) vn[q] = *(const f32x4*)(src + q * 256 + lane * 4);
;     }
;     const float* mod = p.MOD + (size_t)(l * 9 + (s < NCTX ? 8 : b)) * 6144 + (which ? 3 * 1024 : 0);
;     f32x4 sh[4], sc[4];
; #pragma unroll
;     for (int q = 0; q < 4; ++q) { sh[q] = *(const f32x4*)(mod + q * 256 + lane * 4); sc[q] = *(const f32x4*)(mod + 1024 + q * 256 + lane * 4); }
;     float ss = 0.f;
; #pragma unroll
;     for (int q = 0; q < 4; ++q) ss += v[q][0] * v[q][0] + v[q][1] * v[q][1] + v[q][2] * v[q][2] + v[q][3] * v[q][3];
;     ss = red64(ss);
;     const float rs = rsqrtf(ss * (1.f / 1024.f) + EPSF);
;     bf16_t* dst = p.HY + (size_t)row * DM;
; #pragma unroll
;     for (int q = 0; q < 4; ++q) {
;       float o[4];
; #pragma unroll
;       for (int j = 0; j < 4; ++j) o[j] = (v[q][j] * rs * gg[q][j]) * (1.f + sc[q][j]) + sh[q][j];
;       u32x2 w = {pk_bf16(o[0], o[1]), pk_bf16(o[2], o[3])};
;       *(u32x2*)(dst + q * 256 + lane * 4) = w;
;     }
;   }
	v_pk_mul_f32 v[246:247], v[66:67], v[66:67]
	v_pk_fma_f32 v[246:247], v[68:69], v[68:69], v[246:247]
	v_pk_fma_f32 v[246:247], v[70:71], v[70:71], v[246:247]
	v_pk_fma_f32 v[246:247], v[72:73], v[72:73], v[246:247]
	v_pk_fma_f32 v[246:247], v[74:75], v[74:75], v[246:247]
	v_pk_fma_f32 v[246:247], v[76:77], v[76:77], v[246:247]
	v_pk_fma_f32 v[246:247], v[78:79], v[78:79], v[246:247]
	v_pk_fma_f32 v[246:247], v[80:81], v[80:81], v[246:247]
	s_nop 0
	v_add_f32_e32 v246, v246, v247
	s_nop 1
	v_add_f32_dpp v246, v246, v246 quad_perm:[1,0,3,2] row_mask:0xf bank_mask:0xf
	s_nop 1
	v_add_f32_dpp v246, v246, v246 quad_perm:[2,3,0,1] row_mask:0xf bank_mask:0xf
	s_nop 1
	v_add_f32_dpp v246, v246, v246 row_half_mirror row_mask:0xf bank_mask:0xf
	s_nop 1
	v_add_f32_dpp v246, v246, v246 row_mirror row_mask:0xf bank_mask:0xf
	s_nop 1
	v_add_f32_dpp v246, v246, v246 row_bcast:15 row_mask:0xa bank_mask:0xf
	s_nop 1
	v_add_f32_dpp v246, v246, v246 row_bcast:31 row_mask:0xc bank_mask:0xf
	s_nop 1
	v_readlane_b32 s0, v246, 63
	s_add_i32 s21, s37, 1024
	s_lshl_b32 s21, s21, 11
	s_add_u32 s10, s16, s21
	s_addc_u32 s11, s17, 0
	v_mov_b32_e32 v248, s0
	v_fmamk_f32 v248, v248, 0x3a800000, v143
	v_rsq_f32_e32 v248, v248
	s_nop 0
	v_pk_mul_f32 v[66:67], v[66:67], v[248:249] op_sel_hi:[1,0]
	v_pk_add_f32 v[98:99], v[98:99], 1.0 op_sel_hi:[1,0]
	v_pk_mul_f32 v[66:67], v[2:3], v[66:67]
	v_pk_fma_f32 v[66:67], v[98:99], v[66:67], v[82:83]
	v_pk_mul_f32 v[68:69], v[68:69], v[248:249] op_sel_hi:[1,0]
	v_pk_add_f32 v[100:101], v[100:101], 1.0 op_sel_hi:[1,0]
	v_pk_mul_f32 v[68:69], v[4:5], v[68:69]
	v_pk_fma_f32 v[68:69], v[100:101], v[68:69], v[84:85]
	v_cvt_pk_bf16_f32 v82, v66, v67
	v_cvt_pk_bf16_f32 v83, v68, v69
	global_store_dwordx2 v245, v[82:83], s[10:11]
	v_pk_mul_f32 v[70:71], v[70:71], v[248:249] op_sel_hi:[1,0]
	v_pk_add_f32 v[102:103], v[102:103], 1.0 op_sel_hi:[1,0]
	v_pk_mul_f32 v[70:71], v[6:7], v[70:71]
	v_pk_fma_f32 v[70:71], v[102:103], v[70:71], v[86:87]
	v_pk_mul_f32 v[72:73], v[72:73], v[248:249] op_sel_hi:[1,0]
	v_pk_add_f32 v[104:105], v[104:105], 1.0 op_sel_hi:[1,0]
	v_pk_mul_f32 v[72:73], v[8:9], v[72:73]
	v_pk_fma_f32 v[72:73], v[104:105], v[72:73], v[88:89]
	v_cvt_pk_bf16_f32 v86, v70, v71
	v_cvt_pk_bf16_f32 v87, v72, v73
	global_store_dwordx2 v245, v[86:87], s[10:11] offset:512
	v_pk_mul_f32 v[74:75], v[74:75], v[248:249] op_sel_hi:[1,0]
	v_pk_add_f32 v[106:107], v[106:107], 1.0 op_sel_hi:[1,0]
	v_pk_mul_f32 v[74:75], v[10:11], v[74:75]
	v_pk_fma_f32 v[74:75], v[106:107], v[74:75], v[90:91]
	v_pk_mul_f32 v[76:77], v[76:77], v[248:249] op_sel_hi:[1,0]
	v_pk_add_f32 v[108:109], v[108:109], 1.0 op_sel_hi:[1,0]
	v_pk_mul_f32 v[76:77], v[12:13], v[76:77]
	v_pk_fma_f32 v[76:77], v[108:109], v[76:77], v[92:93]
	v_cvt_pk_bf16_f32 v90, v74, v75
	v_cvt_pk_bf16_f32 v91, v76, v77
	global_store_dwordx2 v245, v[90:91], s[10:11] offset:1024
	v_pk_mul_f32 v[78:79], v[78:79], v[248:249] op_sel_hi:[1,0]
	v_pk_add_f32 v[118:119], v[118:119], 1.0 op_sel_hi:[1,0]
	v_pk_mul_f32 v[78:79], v[14:15], v[78:79]
	v_pk_fma_f32 v[78:79], v[118:119], v[78:79], v[94:95]
	v_pk_mul_f32 v[80:81], v[80:81], v[248:249] op_sel_hi:[1,0]
	v_pk_add_f32 v[120:121], v[120:121], 1.0 op_sel_hi:[1,0]
	v_pk_mul_f32 v[80:81], v[16:17], v[80:81]
	v_pk_fma_f32 v[80:81], v[120:121], v[80:81], v[96:97]
	v_cvt_pk_bf16_f32 v94, v78, v79
	v_cvt_pk_bf16_f32 v95, v80, v81
	global_store_dwordx2 v245, v[94:95], s[10:11] offset:1536
	s_add_i32 s21, s37, 1792
	s_mul_hi_u32 s7, s21, 0x38e38e39
	s_lshr_b32 s7, s7, 9
	s_mul_i32 s8, s7, 0x900
	s_sub_i32 s8, s21, s8
	s_lshl_b32 s9, s7, 11
	s_add_i32 s9, s9, s8
	s_add_i32 s9, s9, 0xffffff00
	s_lshl_b32 s10, s7, 8
	s_add_i32 s10, s10, s8
	s_cmpk_gt_i32 s8, 0xff
	s_cselect_b32 s9, s9, s10
	s_cselect_b32 s26, s12, s14
	s_cselect_b32 s27, s13, s15
	s_cselect_b32 s10, s7, 8
	s_lshl_b32 s9, s9, 12
	s_add_u32 s26, s26, s9
	s_addc_u32 s27, s27, 0
	s_add_i32 s10, s10, s82
	s_mul_i32 s10, s10, s24
	s_add_u32 s28, s58, s10
	s_addc_u32 s29, s59, 0
	s_add_u32 s28, s28, 0x3000
	s_addc_u32 s29, s29, 0
	s_add_u32 s0, s28, 0x1000
	s_addc_u32 s1, s29, 0
	global_load_dwordx4 v[66:69], v244, s[26:27] nt
	global_load_dwordx4 v[70:73], v244, s[26:27] offset:1024 nt
	global_load_dwordx4 v[74:77], v244, s[26:27] offset:2048 nt
	global_load_dwordx4 v[78:81], v244, s[26:27] offset:3072 nt
	global_load_dwordx4 v[82:85], v244, s[28:29]
	global_load_dwordx4 v[86:89], v244, s[28:29] offset:1024
	global_load_dwordx4 v[90:93], v244, s[28:29] offset:2048
	global_load_dwordx4 v[94:97], v244, s[28:29] offset:3072
	global_load_dwordx4 v[98:101], v244, s[0:1]
	global_load_dwordx4 v[102:105], v244, s[0:1] offset:1024
	global_load_dwordx4 v[106:109], v244, s[0:1] offset:2048
	global_load_dwordx4 v[118:121], v244, s[0:1] offset:3072
	s_waitcnt vmcnt(32)
; DI unsigned pk_bf16(float lo, float hi) { f32x2 v = {lo, hi}; bf16v2 b = __builtin_convertvector(v, bf16v2); return __builtin_bit_cast(unsigned, b); }
; DI float red64(float x) { for (int o = 32; o > 0; o >>= 1) x += __shfl_xor(x, o); return x; }
; DI void modnorm_rows(const Params& p, int l, int which  , bool from_inputs, bool skip_ctx, int w0, int wstride, int lane) {
;     ...
;   for (; i < nrows; i += wstride) {
;     const int row = rowof(i); const int b = row / TB, s = row % TB;
;     f32x4 v[4];
; #pragma unroll
;     for (int q = 0; q < 4; ++q) v[q] = vn[q];
;     if (i + wstride < nrows) {
;       const int rn = rowof(i + wstride); const float* src = xsrc_row(p, from_inputs, rn / TB, rn % TB);
; #pragma unroll
;       for (int q = 0; q < 4; ++q) vn[q] = *(const f32x4*)(src + q * 256 + lane * 4);
;     }
;     const float* mod = p.MOD + (size_t)(l * 9 + (s < NCTX ? 8 : b)) * 6144 + (which ? 3 * 1024 : 0);
;     f32x4 sh[4], sc[4];
; #pragma unroll
;     for (int q = 0; q < 4; ++q) { sh[q] = *(const f32x4*)(mod + q * 256 + lane * 4); sc[q] = *(const f32x4*)(mod + 1024 + q * 256 + lane * 4); }
;     float ss = 0.f;
; #pragma unroll
;     for (int q = 0; q < 4; ++q) ss += v[q][0] * v[q][0] + v[q][1] * v[q][1] + v[q][2] * v[q][2] + v[q][3] * v[q][3];
;     ss = red64(ss);
;     const float rs = rsqrtf(ss * (1.f / 1024.f) + EPSF);
;     bf16_t* dst = p.HY + (size_t)row * DM;
; #pragma unroll
;     for (int q = 0; q < 4; ++q) {
;       float o[4];
; #pragma unroll
;       for (int j = 0; j < 4; ++j) o[j] = (v[q][j] * rs * gg[q][j]) * (1.f + sc[q][j]) + sh[q][j];
;       u32x2 w = {pk_bf16(o[0], o[1]), pk_bf16(o[2], o[3])};
;       *(u32x2*)(dst + q * 256 + lane * 4) = w;
;     }
;   }
	v_pk_mul_f32 v[246:247], v[122:123], v[122:123]
	v_pk_fma_f32 v[246:247], v[124:125], v[124:125], v[246:247]
	v_pk_fma_f32 v[246:247], v[126:127], v[126:127], v[246:247]
	v_pk_fma_f32 v[246:247], v[128:129], v[128:129], v[246:247]
	v_pk_fma_f32 v[246:247], v[130:131], v[130:131], v[246:247]
	v_pk_fma_f32 v[246:247], v[132:133], v[132:133], v[246:247]
	v_pk_fma_f32 v[246:247], v[134:135], v[134:135], v[246:247]
	v_pk_fma_f32 v[246:247], v[136:137], v[136:137], v[246:247]
	s_nop 0
	v_add_f32_e32 v246, v246, v247
	s_nop 1
	v_add_f32_dpp v246, v246, v246 quad_perm:[1,0,3,2] row_mask:0xf bank_mask:0xf
	s_nop 1
	v_add_f32_dpp v246, v246, v246 quad_perm:[2,3,0,1] row_mask:0xf bank_mask:0xf
	s_nop 1
	v_add_f32_dpp v246, v246, v246 row_half_mirror row_mask:0xf bank_mask:0xf
	s_nop 1
	v_add_f32_dpp v246, v246, v246 row_mirror row_mask:0xf bank_mask:0xf
	s_nop 1
	v_add_f32_dpp v246, v246, v246 row_bcast:15 row_mask:0xa bank_mask:0xf
	s_nop 1
	v_add_f32_dpp v246, v246, v246 row_bcast:31 row_mask:0xc bank_mask:0xf
	s_nop 1
	v_readlane_b32 s0, v246, 63
	s_add_i32 s21, s37, 1280
	s_lshl_b32 s21, s21, 11
	s_add_u32 s10, s16, s21
	s_addc_u32 s11, s17, 0
	v_mov_b32_e32 v248, s0
	v_fmamk_f32 v248, v248, 0x3a800000, v143
	v_rsq_f32_e32 v248, v248
	s_nop 0
	v_pk_mul_f32 v[122:123], v[122:123], v[248:249] op_sel_hi:[1,0]
	v_pk_add_f32 v[176:177], v[176:177], 1.0 op_sel_hi:[1,0]
	v_pk_mul_f32 v[122:123], v[2:3], v[122:123]
	v_pk_fma_f32 v[122:123], v[176:177], v[122:123], v[160:161]
	v_pk_mul_f32 v[124:125], v[124:125], v[248:249] op_sel_hi:[1,0]
	v_pk_add_f32 v[178:179], v[178:179], 1.0 op_sel_hi:[1,0]
	v_pk_mul_f32 v[124:125], v[4:5], v[124:125]
	v_pk_fma_f32 v[124:125], v[178:179], v[124:125], v[162:163]
	v_cvt_pk_bf16_f32 v160, v122, v123
	v_cvt_pk_bf16_f32 v161, v124, v125
	global_store_dwordx2 v245, v[160:161], s[10:11]
	v_pk_mul_f32 v[126:127], v[126:127], v[248:249] op_sel_hi:[1,0]
	v_pk_add_f32 v[180:181], v[180:181], 1.0 op_sel_hi:[1,0]
	v_pk_mul_f32 v[126:127], v[6:7], v[126:127]
	v_pk_fma_f32 v[126:127], v[180:181], v[126:127], v[164:165]
	v_pk_mul_f32 v[128:129], v[128:129], v[248:249] op_sel_hi:[1,0]
	v_pk_add_f32 v[182:183], v[182:183], 1.0 op_sel_hi:[1,0]
	v_pk_mul_f32 v[128:129], v[8:9], v[128:129]
	v_pk_fma_f32 v[128:129], v[182:183], v[128:129], v[166:167]
	v_cvt_pk_bf16_f32 v164, v126, v127
	v_cvt_pk_bf16_f32 v165, v128, v129
	global_store_dwordx2 v245, v[164:165], s[10:11] offset:512
	v_pk_mul_f32 v[130:131], v[130:131], v[248:249] op_sel_hi:[1,0]
	v_pk_add_f32 v[184:185], v[184:185], 1.0 op_sel_hi:[1,0]
	v_pk_mul_f32 v[130:131], v[10:11], v[130:131]
	v_pk_fma_f32 v[130:131], v[184:185], v[130:131], v[168:169]
	v_pk_mul_f32 v[132:133], v[132:133], v[248:249] op_sel_hi:[1,0]
	v_pk_add_f32 v[186:187], v[186:187], 1.0 op_sel_hi:[1,0]
	v_pk_mul_f32 v[132:133], v[12:13], v[132:133]
	v_pk_fma_f32 v[132:133], v[186:187], v[132:133], v[170:171]
	v_cvt_pk_bf16_f32 v168, v130, v131
	v_cvt_pk_bf16_f32 v169, v132, v133
	global_store_dwordx2 v245, v[168:169], s[10:11] offset:1024
	v_pk_mul_f32 v[134:135], v[134:135], v[248:249] op_sel_hi:[1,0]
	v_pk_add_f32 v[188:189], v[188:189], 1.0 op_sel_hi:[1,0]
	v_pk_mul_f32 v[134:135], v[14:15], v[134:135]
	v_pk_fma_f32 v[134:135], v[188:189], v[134:135], v[172:173]
	v_pk_mul_f32 v[136:137], v[136:137], v[248:249] op_sel_hi:[1,0]
	v_pk_add_f32 v[190:191], v[190:191], 1.0 op_sel_hi:[1,0]
	v_pk_mul_f32 v[136:137], v[16:17], v[136:137]
	v_pk_fma_f32 v[136:137], v[190:191], v[136:137], v[174:175]
	v_cvt_pk_bf16_f32 v172, v134, v135
	v_cvt_pk_bf16_f32 v173, v136, v137
	global_store_dwordx2 v245, v[172:173], s[10:11] offset:1536
	s_add_i32 s21, s37, 2048
	s_mul_hi_u32 s7, s21, 0x38e38e39
	s_lshr_b32 s7, s7, 9
	s_mul_i32 s8, s7, 0x900
	s_sub_i32 s8, s21, s8
	s_lshl_b32 s9, s7, 11
	s_add_i32 s9, s9, s8
	s_add_i32 s9, s9, 0xffffff00
	s_lshl_b32 s10, s7, 8
	s_add_i32 s10, s10, s8
	s_cmpk_gt_i32 s8, 0xff
	s_cselect_b32 s9, s9, s10
	s_cselect_b32 s26, s12, s14
	s_cselect_b32 s27, s13, s15
	s_cselect_b32 s10, s7, 8
	s_lshl_b32 s9, s9, 12
	s_add_u32 s26, s26, s9
	s_addc_u32 s27, s27, 0
	s_add_i32 s10, s10, s82
	s_mul_i32 s10, s10, s24
	s_add_u32 s28, s58, s10
	s_addc_u32 s29, s59, 0
	s_add_u32 s28, s28, 0x3000
	s_addc_u32 s29, s29, 0
	s_add_u32 s0, s28, 0x1000
	s_addc_u32 s1, s29, 0
	global_load_dwordx4 v[122:125], v244, s[26:27] nt
	global_load_dwordx4 v[126:129], v244, s[26:27] offset:1024 nt
	global_load_dwordx4 v[130:133], v244, s[26:27] offset:2048 nt
	global_load_dwordx4 v[134:137], v244, s[26:27] offset:3072 nt
	global_load_dwordx4 v[160:163], v244, s[28:29]
	global_load_dwordx4 v[164:167], v244, s[28:29] offset:1024
	global_load_dwordx4 v[168:171], v244, s[28:29] offset:2048
	global_load_dwordx4 v[172:175], v244, s[28:29] offset:3072
	global_load_dwordx4 v[176:179], v244, s[0:1]
	global_load_dwordx4 v[180:183], v244, s[0:1] offset:1024
	global_load_dwordx4 v[184:187], v244, s[0:1] offset:2048
	global_load_dwordx4 v[188:191], v244, s[0:1] offset:3072
	s_waitcnt vmcnt(32)
; DI unsigned pk_bf16(float lo, float hi) { f32x2 v = {lo, hi}; bf16v2 b = __builtin_convertvector(v, bf16v2); return __builtin_bit_cast(unsigned, b); }
; DI float red64(float x) { for (int o = 32; o > 0; o >>= 1) x += __shfl_xor(x, o); return x; }
; DI void modnorm_rows(const Params& p, int l, int which  , bool from_inputs, bool skip_ctx, int w0, int wstride, int lane) {
;     ...
;   for (; i < nrows; i += wstride) {
;     const int row = rowof(i); const int b = row / TB, s = row % TB;
;     f32x4 v[4];
; #pragma unroll
;     for (int q = 0; q < 4; ++q) v[q] = vn[q];
;     if (i + wstride < nrows) {
;       const int rn = rowof(i + wstride); const float* src = xsrc_row(p, from_inputs, rn / TB, rn % TB);
; #pragma unroll
;       for (int q = 0; q < 4; ++q) vn[q] = *(const f32x4*)(src + q * 256 + lane * 4);
;     }
;     const float* mod = p.MOD + (size_t)(l * 9 + (s < NCTX ? 8 : b)) * 6144 + (which ? 3 * 1024 : 0);
;     f32x4 sh[4], sc[4];
; #pragma unroll
;     for (int q = 0; q < 4; ++q) { sh[q] = *(const f32x4*)(mod + q * 256 + lane * 4); sc[q] = *(const f32x4*)(mod + 1024 + q * 256 + lane * 4); }
;     float ss = 0.f;
; #pragma unroll
;     for (int q = 0; q < 4; ++q) ss += v[q][0] * v[q][0] + v[q][1] * v[q][1] + v[q][2] * v[q][2] + v[q][3] * v[q][3];
;     ss = red64(ss);
;     const float rs = rsqrtf(ss * (1.f / 1024.f) + EPSF);
;     bf16_t* dst = p.HY + (size_t)row * DM;
; #pragma unroll
;     for (int q = 0; q < 4; ++q) {
;       float o[4];
; #pragma unroll
;       for (int j = 0; j < 4; ++j) o[j] = (v[q][j] * rs * gg[q][j]) * (1.f + sc[q][j]) + sh[q][j];
;       u32x2 w = {pk_bf16(o[0], o[1]), pk_bf16(o[2], o[3])};
;       *(u32x2*)(dst + q * 256 + lane * 4) = w;
;     }
;   }
	v_pk_mul_f32 v[246:247], v[18:19], v[18:19]
	v_pk_fma_f32 v[246:247], v[20:21], v[20:21], v[246:247]
	v_pk_fma_f32 v[246:247], v[22:23], v[22:23], v[246:247]
	v_pk_fma_f32 v[246:247], v[24:25], v[24:25], v[246:247]
	v_pk_fma_f32 v[246:247], v[26:27], v[26:27], v[246:247]
	v_pk_fma_f32 v[246:247], v[28:29], v[28:29], v[246:247]
	v_pk_fma_f32 v[246:247], v[30:31], v[30:31], v[246:247]
	v_pk_fma_f32 v[246:247], v[32:33], v[32:33], v[246:247]
	s_nop 0
	v_add_f32_e32 v246, v246, v247
	s_nop 1
	v_add_f32_dpp v246, v246, v246 quad_perm:[1,0,3,2] row_mask:0xf bank_mask:0xf
	s_nop 1
	v_add_f32_dpp v246, v246, v246 quad_perm:[2,3,0,1] row_mask:0xf bank_mask:0xf
	s_nop 1
	v_add_f32_dpp v246, v246, v246 row_half_mirror row_mask:0xf bank_mask:0xf
	s_nop 1
	v_add_f32_dpp v246, v246, v246 row_mirror row_mask:0xf bank_mask:0xf
	s_nop 1
	v_add_f32_dpp v246, v246, v246 row_bcast:15 row_mask:0xa bank_mask:0xf
	s_nop 1
	v_add_f32_dpp v246, v246, v246 row_bcast:31 row_mask:0xc bank_mask:0xf
	s_nop 1
	v_readlane_b32 s0, v246, 63
	s_add_i32 s21, s37, 1536
	s_lshl_b32 s21, s21, 11
	s_add_u32 s10, s16, s21
	s_addc_u32 s11, s17, 0
	v_mov_b32_e32 v248, s0
	v_fmamk_f32 v248, v248, 0x3a800000, v143
	v_rsq_f32_e32 v248, v248
	s_nop 0
	v_pk_mul_f32 v[18:19], v[18:19], v[248:249] op_sel_hi:[1,0]
	v_pk_add_f32 v[50:51], v[50:51], 1.0 op_sel_hi:[1,0]
	v_pk_mul_f32 v[18:19], v[2:3], v[18:19]
	v_pk_fma_f32 v[18:19], v[50:51], v[18:19], v[34:35]
	v_pk_mul_f32 v[20:21], v[20:21], v[248:249] op_sel_hi:[1,0]
	v_pk_add_f32 v[52:53], v[52:53], 1.0 op_sel_hi:[1,0]
	v_pk_mul_f32 v[20:21], v[4:5], v[20:21]
	v_pk_fma_f32 v[20:21], v[52:53], v[20:21], v[36:37]
	v_cvt_pk_bf16_f32 v34, v18, v19
	v_cvt_pk_bf16_f32 v35, v20, v21
	global_store_dwordx2 v245, v[34:35], s[10:11]
	v_pk_mul_f32 v[22:23], v[22:23], v[248:249] op_sel_hi:[1,0]
	v_pk_add_f32 v[54:55], v[54:55], 1.0 op_sel_hi:[1,0]
	v_pk_mul_f32 v[22:23], v[6:7], v[22:23]
	v_pk_fma_f32 v[22:23], v[54:55], v[22:23], v[38:39]
	v_pk_mul_f32 v[24:25], v[24:25], v[248:249] op_sel_hi:[1,0]
	v_pk_add_f32 v[56:57], v[56:57], 1.0 op_sel_hi:[1,0]
	v_pk_mul_f32 v[24:25], v[8:9], v[24:25]
	v_pk_fma_f32 v[24:25], v[56:57], v[24:25], v[40:41]
	v_cvt_pk_bf16_f32 v38, v22, v23
	v_cvt_pk_bf16_f32 v39, v24, v25
	global_store_dwordx2 v245, v[38:39], s[10:11] offset:512
	v_pk_mul_f32 v[26:27], v[26:27], v[248:249] op_sel_hi:[1,0]
	v_pk_add_f32 v[58:59], v[58:59], 1.0 op_sel_hi:[1,0]
	v_pk_mul_f32 v[26:27], v[10:11], v[26:27]
	v_pk_fma_f32 v[26:27], v[58:59], v[26:27], v[42:43]
	v_pk_mul_f32 v[28:29], v[28:29], v[248:249] op_sel_hi:[1,0]
	v_pk_add_f32 v[60:61], v[60:61], 1.0 op_sel_hi:[1,0]
	v_pk_mul_f32 v[28:29], v[12:13], v[28:29]
	v_pk_fma_f32 v[28:29], v[60:61], v[28:29], v[44:45]
	v_cvt_pk_bf16_f32 v42, v26, v27
	v_cvt_pk_bf16_f32 v43, v28, v29
	global_store_dwordx2 v245, v[42:43], s[10:11] offset:1024
	v_pk_mul_f32 v[30:31], v[30:31], v[248:249] op_sel_hi:[1,0]
	v_pk_add_f32 v[62:63], v[62:63], 1.0 op_sel_hi:[1,0]
	v_pk_mul_f32 v[30:31], v[14:15], v[30:31]
	v_pk_fma_f32 v[30:31], v[62:63], v[30:31], v[46:47]
	v_pk_mul_f32 v[32:33], v[32:33], v[248:249] op_sel_hi:[1,0]
	v_pk_add_f32 v[64:65], v[64:65], 1.0 op_sel_hi:[1,0]
	v_pk_mul_f32 v[32:33], v[16:17], v[32:33]
	v_pk_fma_f32 v[32:33], v[64:65], v[32:33], v[48:49]
	v_cvt_pk_bf16_f32 v46, v30, v31
	v_cvt_pk_bf16_f32 v47, v32, v33
	global_store_dwordx2 v245, v[46:47], s[10:11] offset:1536
	s_waitcnt vmcnt(20)
	v_pk_mul_f32 v[246:247], v[66:67], v[66:67]
	v_pk_fma_f32 v[246:247], v[68:69], v[68:69], v[246:247]
	v_pk_fma_f32 v[246:247], v[70:71], v[70:71], v[246:247]
	v_pk_fma_f32 v[246:247], v[72:73], v[72:73], v[246:247]
	v_pk_fma_f32 v[246:247], v[74:75], v[74:75], v[246:247]
	v_pk_fma_f32 v[246:247], v[76:77], v[76:77], v[246:247]
	v_pk_fma_f32 v[246:247], v[78:79], v[78:79], v[246:247]
	v_pk_fma_f32 v[246:247], v[80:81], v[80:81], v[246:247]
	s_nop 0
	v_add_f32_e32 v246, v246, v247
	s_nop 1
	v_add_f32_dpp v246, v246, v246 quad_perm:[1,0,3,2] row_mask:0xf bank_mask:0xf
	s_nop 1
	v_add_f32_dpp v246, v246, v246 quad_perm:[2,3,0,1] row_mask:0xf bank_mask:0xf
	s_nop 1
	v_add_f32_dpp v246, v246, v246 row_half_mirror row_mask:0xf bank_mask:0xf
	s_nop 1
	v_add_f32_dpp v246, v246, v246 row_mirror row_mask:0xf bank_mask:0xf
	s_nop 1
	v_add_f32_dpp v246, v246, v246 row_bcast:15 row_mask:0xa bank_mask:0xf
	s_nop 1
	v_add_f32_dpp v246, v246, v246 row_bcast:31 row_mask:0xc bank_mask:0xf
	s_nop 1
	v_readlane_b32 s0, v246, 63
	s_add_i32 s21, s37, 1792
	s_lshl_b32 s21, s21, 11
	s_add_u32 s10, s16, s21
	s_addc_u32 s11, s17, 0
	v_mov_b32_e32 v248, s0
	v_fmamk_f32 v248, v248, 0x3a800000, v143
	v_rsq_f32_e32 v248, v248
	s_nop 0
	v_pk_mul_f32 v[66:67], v[66:67], v[248:249] op_sel_hi:[1,0]
	v_pk_add_f32 v[98:99], v[98:99], 1.0 op_sel_hi:[1,0]
	v_pk_mul_f32 v[66:67], v[2:3], v[66:67]
	v_pk_fma_f32 v[66:67], v[98:99], v[66:67], v[82:83]
	v_pk_mul_f32 v[68:69], v[68:69], v[248:249] op_sel_hi:[1,0]
	v_pk_add_f32 v[100:101], v[100:101], 1.0 op_sel_hi:[1,0]
	v_pk_mul_f32 v[68:69], v[4:5], v[68:69]
	v_pk_fma_f32 v[68:69], v[100:101], v[68:69], v[84:85]
	v_cvt_pk_bf16_f32 v82, v66, v67
	v_cvt_pk_bf16_f32 v83, v68, v69
	global_store_dwordx2 v245, v[82:83], s[10:11]
	v_pk_mul_f32 v[70:71], v[70:71], v[248:249] op_sel_hi:[1,0]
	v_pk_add_f32 v[102:103], v[102:103], 1.0 op_sel_hi:[1,0]
	v_pk_mul_f32 v[70:71], v[6:7], v[70:71]
	v_pk_fma_f32 v[70:71], v[102:103], v[70:71], v[86:87]
	v_pk_mul_f32 v[72:73], v[72:73], v[248:249] op_sel_hi:[1,0]
	v_pk_add_f32 v[104:105], v[104:105], 1.0 op_sel_hi:[1,0]
	v_pk_mul_f32 v[72:73], v[8:9], v[72:73]
	v_pk_fma_f32 v[72:73], v[104:105], v[72:73], v[88:89]
	v_cvt_pk_bf16_f32 v86, v70, v71
	v_cvt_pk_bf16_f32 v87, v72, v73
	global_store_dwordx2 v245, v[86:87], s[10:11] offset:512
	v_pk_mul_f32 v[74:75], v[74:75], v[248:249] op_sel_hi:[1,0]
	v_pk_add_f32 v[106:107], v[106:107], 1.0 op_sel_hi:[1,0]
	v_pk_mul_f32 v[74:75], v[10:11], v[74:75]
	v_pk_fma_f32 v[74:75], v[106:107], v[74:75], v[90:91]
	v_pk_mul_f32 v[76:77], v[76:77], v[248:249] op_sel_hi:[1,0]
	v_pk_add_f32 v[108:109], v[108:109], 1.0 op_sel_hi:[1,0]
	v_pk_mul_f32 v[76:77], v[12:13], v[76:77]
	v_pk_fma_f32 v[76:77], v[108:109], v[76:77], v[92:93]
	v_cvt_pk_bf16_f32 v90, v74, v75
	v_cvt_pk_bf16_f32 v91, v76, v77
	global_store_dwordx2 v245, v[90:91], s[10:11] offset:1024
	v_pk_mul_f32 v[78:79], v[78:79], v[248:249] op_sel_hi:[1,0]
	v_pk_add_f32 v[118:119], v[118:119], 1.0 op_sel_hi:[1,0]
	v_pk_mul_f32 v[78:79], v[14:15], v[78:79]
	v_pk_fma_f32 v[78:79], v[118:119], v[78:79], v[94:95]
	v_pk_mul_f32 v[80:81], v[80:81], v[248:249] op_sel_hi:[1,0]
	v_pk_add_f32 v[120:121], v[120:121], 1.0 op_sel_hi:[1,0]
	v_pk_mul_f32 v[80:81], v[16:17], v[80:81]
	v_pk_fma_f32 v[80:81], v[120:121], v[80:81], v[96:97]
	v_cvt_pk_bf16_f32 v94, v78, v79
	v_cvt_pk_bf16_f32 v95, v80, v81
	global_store_dwordx2 v245, v[94:95], s[10:11] offset:1536
	s_waitcnt vmcnt(8)
; DI unsigned pk_bf16(float lo, float hi) { f32x2 v = {lo, hi}; bf16v2 b = __builtin_convertvector(v, bf16v2); return __builtin_bit_cast(unsigned, b); }
; DI float red64(float x) { for (int o = 32; o > 0; o >>= 1) x += __shfl_xor(x, o); return x; }
; DI void modnorm_rows(const Params& p, int l, int which  , bool from_inputs, bool skip_ctx, int w0, int wstride, int lane) {
;     ...
;   auto rowof = [&](int i) -> int { return skip_ctx ? (i / NLAT) * TB + NCTX + (i % NLAT) : i; };
;   int i = w0;
;   if (i >= nrows) return;
;   f32x4 vn[4];
;   {
;     const int row = rowof(i); const float* src = xsrc_row(p, from_inputs, row / TB, row % TB);
; #pragma unroll
;     for (int q = 0; q < 4; ++q) vn[q] = *(const f32x4*)(src + q * 256 + lane * 4);
;   }
;   for (; i < nrows; i += wstride) {
;     const int row = rowof(i); const int b = row / TB, s = row % TB;
;     f32x4 v[4];
; #pragma unroll
;     for (int q = 0; q < 4; ++q) v[q] = vn[q];
;     if (i + wstride < nrows) {
;       const int rn = rowof(i + wstride); const float* src = xsrc_row(p, from_inputs, rn / TB, rn % TB);
; #pragma unroll
;       for (int q = 0; q < 4; ++q) vn[q] = *(const f32x4*)(src + q * 256 + lane * 4);
;     }
;     const float* mod = p.MOD + (size_t)(l * 9 + (s < NCTX ? 8 : b)) * 6144 + (which ? 3 * 1024 : 0);
;     f32x4 sh[4], sc[4];
; #pragma unroll
;     for (int q = 0; q < 4; ++q) { sh[q] = *(const f32x4*)(mod + q * 256 + lane * 4); sc[q] = *(const f32x4*)(mod + 1024 + q * 256 + lane * 4); }
;     float ss = 0.f;
; #pragma unroll
;     for (int q = 0; q < 4; ++q) ss += v[q][0] * v[q][0] + v[q][1] * v[q][1] + v[q][2] * v[q][2] + v[q][3] * v[q][3];
;     ss = red64(ss);
;     const float rs = rsqrtf(ss * (1.f / 1024.f) + EPSF);
;     bf16_t* dst = p.HY + (size_t)row * DM;
; #pragma unroll
;     for (int q = 0; q < 4; ++q) {
;       float o[4];
; #pragma unroll
;       for (int j = 0; j < 4; ++j) o[j] = (v[q][j] * rs * gg[q][j]) * (1.f + sc[q][j]) + sh[q][j];
;       u32x2 w = {pk_bf16(o[0], o[1]), pk_bf16(o[2], o[3])};
;       *(u32x2*)(dst + q * 256 + lane * 4) = w;
;     }
;   }
	v_pk_mul_f32 v[246:247], v[122:123], v[122:123]
	v_pk_fma_f32 v[246:247], v[124:125], v[124:125], v[246:247]
	v_pk_fma_f32 v[246:247], v[126:127], v[126:127], v[246:247]
	v_pk_fma_f32 v[246:247], v[128:129], v[128:129], v[246:247]
	v_pk_fma_f32 v[246:247], v[130:131], v[130:131], v[246:247]
	v_pk_fma_f32 v[246:247], v[132:133], v[132:133], v[246:247]
	v_pk_fma_f32 v[246:247], v[134:135], v[134:135], v[246:247]
	v_pk_fma_f32 v[246:247], v[136:137], v[136:137], v[246:247]
	s_nop 0
	v_add_f32_e32 v246, v246, v247
	s_nop 1
	v_add_f32_dpp v246, v246, v246 quad_perm:[1,0,3,2] row_mask:0xf bank_mask:0xf
	s_nop 1
	v_add_f32_dpp v246, v246, v246 quad_perm:[2,3,0,1] row_mask:0xf bank_mask:0xf
	s_nop 1
	v_add_f32_dpp v246, v246, v246 row_half_mirror row_mask:0xf bank_mask:0xf
	s_nop 1
	v_add_f32_dpp v246, v246, v246 row_mirror row_mask:0xf bank_mask:0xf
	s_nop 1
	v_add_f32_dpp v246, v246, v246 row_bcast:15 row_mask:0xa bank_mask:0xf
	s_nop 1
	v_add_f32_dpp v246, v246, v246 row_bcast:31 row_mask:0xc bank_mask:0xf
	s_nop 1
	v_readlane_b32 s0, v246, 63
	s_add_i32 s21, s37, 2048
	s_lshl_b32 s21, s21, 11
	s_add_u32 s10, s16, s21
	s_addc_u32 s11, s17, 0
	v_mov_b32_e32 v248, s0
	v_fmamk_f32 v248, v248, 0x3a800000, v143
	v_rsq_f32_e32 v248, v248
	s_nop 0
	v_pk_mul_f32 v[122:123], v[122:123], v[248:249] op_sel_hi:[1,0]
	v_pk_add_f32 v[176:177], v[176:177], 1.0 op_sel_hi:[1,0]
	v_pk_mul_f32 v[122:123], v[2:3], v[122:123]
	v_pk_fma_f32 v[122:123], v[176:177], v[122:123], v[160:161]
	v_pk_mul_f32 v[124:125], v[124:125], v[248:249] op_sel_hi:[1,0]
	v_pk_add_f32 v[178:179], v[178:179], 1.0 op_sel_hi:[1,0]
	v_pk_mul_f32 v[124:125], v[4:5], v[124:125]
	v_pk_fma_f32 v[124:125], v[178:179], v[124:125], v[162:163]
	v_cvt_pk_bf16_f32 v160, v122, v123
	v_cvt_pk_bf16_f32 v161, v124, v125
	global_store_dwordx2 v245, v[160:161], s[10:11]
	v_pk_mul_f32 v[126:127], v[126:127], v[248:249] op_sel_hi:[1,0]
	v_pk_add_f32 v[180:181], v[180:181], 1.0 op_sel_hi:[1,0]
	v_pk_mul_f32 v[126:127], v[6:7], v[126:127]
	v_pk_fma_f32 v[126:127], v[180:181], v[126:127], v[164:165]
	v_pk_mul_f32 v[128:129], v[128:129], v[248:249] op_sel_hi:[1,0]
	v_pk_add_f32 v[182:183], v[182:183], 1.0 op_sel_hi:[1,0]
	v_pk_mul_f32 v[128:129], v[8:9], v[128:129]
	v_pk_fma_f32 v[128:129], v[182:183], v[128:129], v[166:167]
	v_cvt_pk_bf16_f32 v164, v126, v127
	v_cvt_pk_bf16_f32 v165, v128, v129
	global_store_dwordx2 v245, v[164:165], s[10:11] offset:512
	v_pk_mul_f32 v[130:131], v[130:131], v[248:249] op_sel_hi:[1,0]
	v_pk_add_f32 v[184:185], v[184:185], 1.0 op_sel_hi:[1,0]
	v_pk_mul_f32 v[130:131], v[10:11], v[130:131]
	v_pk_fma_f32 v[130:131], v[184:185], v[130:131], v[168:169]
	v_pk_mul_f32 v[132:133], v[132:133], v[248:249] op_sel_hi:[1,0]
	v_pk_add_f32 v[186:187], v[186:187], 1.0 op_sel_hi:[1,0]
	v_pk_mul_f32 v[132:133], v[12:13], v[132:133]
	v_pk_fma_f32 v[132:133], v[186:187], v[132:133], v[170:171]
	v_cvt_pk_bf16_f32 v168, v130, v131
	v_cvt_pk_bf16_f32 v169, v132, v133
	global_store_dwordx2 v245, v[168:169], s[10:11] offset:1024
	v_pk_mul_f32 v[134:135], v[134:135], v[248:249] op_sel_hi:[1,0]
	v_pk_add_f32 v[188:189], v[188:189], 1.0 op_sel_hi:[1,0]
	v_pk_mul_f32 v[134:135], v[14:15], v[134:135]
	v_pk_fma_f32 v[134:135], v[188:189], v[134:135], v[172:173]
	v_pk_mul_f32 v[136:137], v[136:137], v[248:249] op_sel_hi:[1,0]
	v_pk_add_f32 v[190:191], v[190:191], 1.0 op_sel_hi:[1,0]
	v_pk_mul_f32 v[136:137], v[16:17], v[136:137]
	v_pk_fma_f32 v[136:137], v[190:191], v[136:137], v[174:175]
	v_cvt_pk_bf16_f32 v172, v134, v135
	v_cvt_pk_bf16_f32 v173, v136, v137
	global_store_dwordx2 v245, v[172:173], s[10:11] offset:1536
	s_branch .Lnorm2_done
.Lnorm2_last:
	s_lshr_b32 s39, s20, 5
	s_lshl_b32 s39, s39, 2
	s_and_b32 s38, s20, 3
	s_or_b32 s39, s39, s38
	s_lshr_b32 s38, s20, 2
	s_and_b32 s38, s38, 7
	s_mul_i32 s37, s38, 0x900
	s_add_i32 s37, s37, s39
	s_add_i32 s21, s37, 256
	s_mov_b32 s7, s38
	s_add_i32 s8, s39, 256
	s_lshl_b32 s9, s7, 11
	s_add_i32 s9, s9, s8
	s_add_i32 s9, s9, 0xffffff00
	s_lshl_b32 s10, s7, 8
	s_add_i32 s10, s10, s8
	s_cmpk_gt_i32 s8, 0xff
	s_cselect_b32 s9, s9, s10
	s_cselect_b32 s26, s12, s14
	s_cselect_b32 s27, s13, s15
	s_cselect_b32 s10, s7, 8
	s_lshl_b32 s9, s9, 12
	s_add_u32 s26, s26, s9
	s_addc_u32 s27, s27, 0
	s_add_i32 s10, s10, s82
	s_mul_i32 s10, s10, s24
	s_add_u32 s28, s58, s10
	s_addc_u32 s29, s59, 0
	s_add_u32 s28, s28, 0x3000
	s_addc_u32 s29, s29, 0
	s_add_u32 s0, s28, 0x1000
	s_addc_u32 s1, s29, 0
	global_load_dwordx4 v[18:21], v244, s[26:27] nt
	global_load_dwordx4 v[22:25], v244, s[26:27] offset:1024 nt
	global_load_dwordx4 v[26:29], v244, s[26:27] offset:2048 nt
	global_load_dwordx4 v[30:33], v244, s[26:27] offset:3072 nt
	global_load_dwordx4 v[34:37], v244, s[28:29]
	global_load_dwordx4 v[38:41], v244, s[28:29] offset:1024
	global_load_dwordx4 v[42:45], v244, s[28:29] offset:2048
	global_load_dwordx4 v[46:49], v244, s[28:29] offset:3072
	global_load_dwordx4 v[50:53], v244, s[0:1]
	global_load_dwordx4 v[54:57], v244, s[0:1] offset:1024
	global_load_dwordx4 v[58:61], v244, s[0:1] offset:2048
	global_load_dwordx4 v[62:65], v244, s[0:1] offset:3072
	s_add_i32 s21, s37, 512
	s_mov_b32 s7, s38
	s_add_i32 s8, s39, 512
	s_lshl_b32 s9, s7, 11
	s_add_i32 s9, s9, s8
	s_add_i32 s9, s9, 0xffffff00
	s_lshl_b32 s10, s7, 8
	s_add_i32 s10, s10, s8
	s_cmpk_gt_i32 s8, 0xff
	s_cselect_b32 s9, s9, s10
	s_cselect_b32 s26, s12, s14
	s_cselect_b32 s27, s13, s15
	s_cselect_b32 s10, s7, 8
	s_lshl_b32 s9, s9, 12
	s_add_u32 s26, s26, s9
	s_addc_u32 s27, s27, 0
	s_add_i32 s10, s10, s82
	s_mul_i32 s10, s10, s24
	s_add_u32 s28, s58, s10
	s_addc_u32 s29, s59, 0
	s_add_u32 s28, s28, 0x3000
; DI unsigned pk_bf16(float lo, float hi) { f32x2 v = {lo, hi}; bf16v2 b = __builtin_convertvector(v, bf16v2); return __builtin_bit_cast(unsigned, b); }
; DI float red64(float x) { for (int o = 32; o > 0; o >>= 1) x += __shfl_xor(x, o); return x; }
; DI void modnorm_rows(const Params& p, int l, int which  , bool from_inputs, bool skip_ctx, int w0, int wstride, int lane) {
;     ...
;   for (; i < nrows; i += wstride) {
;     const int row = rowof(i); const int b = row / TB, s = row % TB;
;     f32x4 v[4];
; #pragma unroll
;     for (int q = 0; q < 4; ++q) v[q] = vn[q];
;     if (i + wstride < nrows) {
;       const int rn = rowof(i + wstride); const float* src = xsrc_row(p, from_inputs, rn / TB, rn % TB);
; #pragma unroll
;       for (int q = 0; q < 4; ++q) vn[q] = *(const f32x4*)(src + q * 256 + lane * 4);
;     }
;     const float* mod = p.MOD + (size_t)(l * 9 + (s < NCTX ? 8 : b)) * 6144 + (which ? 3 * 1024 : 0);
;     f32x4 sh[4], sc[4];
; #pragma unroll
;     for (int q = 0; q < 4; ++q) { sh[q] = *(const f32x4*)(mod + q * 256 + lane * 4); sc[q] = *(const f32x4*)(mod + 1024 + q * 256 + lane * 4); }
;     float ss = 0.f;
; #pragma unroll
;     for (int q = 0; q < 4; ++q) ss += v[q][0] * v[q][0] + v[q][1] * v[q][1] + v[q][2] * v[q][2] + v[q][3] * v[q][3];
;     ss = red64(ss);
;     const float rs = rsqrtf(ss * (1.f / 1024.f) + EPSF);
;     bf16_t* dst = p.HY + (size_t)row * DM;
; #pragma unroll
;     for (int q = 0; q < 4; ++q) {
;       float o[4];
; #pragma unroll
;       for (int j = 0; j < 4; ++j) o[j] = (v[q][j] * rs * gg[q][j]) * (1.f + sc[q][j]) + sh[q][j];
;       u32x2 w = {pk_bf16(o[0], o[1]), pk_bf16(o[2], o[3])};
;       *(u32x2*)(dst + q * 256 + lane * 4) = w;
;     }
;   }
	s_addc_u32 s29, s29, 0
	s_add_u32 s0, s28, 0x1000
	s_addc_u32 s1, s29, 0
	global_load_dwordx4 v[66:69], v244, s[26:27] nt
	global_load_dwordx4 v[70:73], v244, s[26:27] offset:1024 nt
	global_load_dwordx4 v[74:77], v244, s[26:27] offset:2048 nt
	global_load_dwordx4 v[78:81], v244, s[26:27] offset:3072 nt
	global_load_dwordx4 v[82:85], v244, s[28:29]
	global_load_dwordx4 v[86:89], v244, s[28:29] offset:1024
	global_load_dwordx4 v[90:93], v244, s[28:29] offset:2048
	global_load_dwordx4 v[94:97], v244, s[28:29] offset:3072
	global_load_dwordx4 v[98:101], v244, s[0:1]
	global_load_dwordx4 v[102:105], v244, s[0:1] offset:1024
	global_load_dwordx4 v[106:109], v244, s[0:1] offset:2048
	global_load_dwordx4 v[118:121], v244, s[0:1] offset:3072
	s_add_i32 s21, s37, 768
	s_mov_b32 s7, s38
	s_add_i32 s8, s39, 768
	s_lshl_b32 s9, s7, 11
	s_add_i32 s9, s9, s8
	s_add_i32 s9, s9, 0xffffff00
	s_lshl_b32 s10, s7, 8
	s_add_i32 s10, s10, s8
	s_cmpk_gt_i32 s8, 0xff
	s_cselect_b32 s9, s9, s10
	s_cselect_b32 s26, s12, s14
	s_cselect_b32 s27, s13, s15
	s_cselect_b32 s10, s7, 8
	s_lshl_b32 s9, s9, 12
	s_add_u32 s26, s26, s9
	s_addc_u32 s27, s27, 0
	s_add_i32 s10, s10, s82
	s_mul_i32 s10, s10, s24
	s_add_u32 s28, s58, s10
	s_addc_u32 s29, s59, 0
	s_add_u32 s28, s28, 0x3000
	s_addc_u32 s29, s29, 0
	s_add_u32 s0, s28, 0x1000
	s_addc_u32 s1, s29, 0
	global_load_dwordx4 v[122:125], v244, s[26:27] nt
	global_load_dwordx4 v[126:129], v244, s[26:27] offset:1024 nt
	global_load_dwordx4 v[130:133], v244, s[26:27] offset:2048 nt
	global_load_dwordx4 v[134:137], v244, s[26:27] offset:3072 nt
	global_load_dwordx4 v[160:163], v244, s[28:29]
	global_load_dwordx4 v[164:167], v244, s[28:29] offset:1024
	global_load_dwordx4 v[168:171], v244, s[28:29] offset:2048
	global_load_dwordx4 v[172:175], v244, s[28:29] offset:3072
	global_load_dwordx4 v[176:179], v244, s[0:1]
	global_load_dwordx4 v[180:183], v244, s[0:1] offset:1024
	global_load_dwordx4 v[184:187], v244, s[0:1] offset:2048
	global_load_dwordx4 v[188:191], v244, s[0:1] offset:3072
	s_waitcnt vmcnt(24)
	v_pk_mul_f32 v[246:247], v[18:19], v[18:19]
	v_pk_fma_f32 v[246:247], v[20:21], v[20:21], v[246:247]
	v_pk_fma_f32 v[246:247], v[22:23], v[22:23], v[246:247]
	v_pk_fma_f32 v[246:247], v[24:25], v[24:25], v[246:247]
	v_pk_fma_f32 v[246:247], v[26:27], v[26:27], v[246:247]
	v_pk_fma_f32 v[246:247], v[28:29], v[28:29], v[246:247]
	v_pk_fma_f32 v[246:247], v[30:31], v[30:31], v[246:247]
	v_pk_fma_f32 v[246:247], v[32:33], v[32:33], v[246:247]
	s_nop 0
	v_add_f32_e32 v246, v246, v247
	s_nop 1
	v_add_f32_dpp v246, v246, v246 quad_perm:[1,0,3,2] row_mask:0xf bank_mask:0xf
	s_nop 1
	v_add_f32_dpp v246, v246, v246 quad_perm:[2,3,0,1] row_mask:0xf bank_mask:0xf
	s_nop 1
	v_add_f32_dpp v246, v246, v246 row_half_mirror row_mask:0xf bank_mask:0xf
	s_nop 1
	v_add_f32_dpp v246, v246, v246 row_mirror row_mask:0xf bank_mask:0xf
	s_nop 1
	v_add_f32_dpp v246, v246, v246 row_bcast:15 row_mask:0xa bank_mask:0xf
	s_nop 1
	v_add_f32_dpp v246, v246, v246 row_bcast:31 row_mask:0xc bank_mask:0xf
	s_nop 1
	v_readlane_b32 s0, v246, 63
	s_add_i32 s21, s37, 256
	s_lshl_b32 s21, s21, 11
	s_add_u32 s10, s16, s21
	s_addc_u32 s11, s17, 0
	v_mov_b32_e32 v248, s0
	v_fmamk_f32 v248, v248, 0x3a800000, v143
	v_rsq_f32_e32 v248, v248
	s_nop 0
	v_pk_mul_f32 v[18:19], v[18:19], v[248:249] op_sel_hi:[1,0]
	v_pk_add_f32 v[50:51], v[50:51], 1.0 op_sel_hi:[1,0]
	v_pk_mul_f32 v[18:19], v[2:3], v[18:19]
	v_pk_fma_f32 v[18:19], v[50:51], v[18:19], v[34:35]
	v_pk_mul_f32 v[20:21], v[20:21], v[248:249] op_sel_hi:[1,0]
	v_pk_add_f32 v[52:53], v[52:53], 1.0 op_sel_hi:[1,0]
	v_pk_mul_f32 v[20:21], v[4:5], v[20:21]
	v_pk_fma_f32 v[20:21], v[52:53], v[20:21], v[36:37]
	v_cvt_pk_bf16_f32 v34, v18, v19
	v_cvt_pk_bf16_f32 v35, v20, v21
	global_store_dwordx2 v245, v[34:35], s[10:11]
	v_pk_mul_f32 v[22:23], v[22:23], v[248:249] op_sel_hi:[1,0]
	v_pk_add_f32 v[54:55], v[54:55], 1.0 op_sel_hi:[1,0]
	v_pk_mul_f32 v[22:23], v[6:7], v[22:23]
	v_pk_fma_f32 v[22:23], v[54:55], v[22:23], v[38:39]
	v_pk_mul_f32 v[24:25], v[24:25], v[248:249] op_sel_hi:[1,0]
	v_pk_add_f32 v[56:57], v[56:57], 1.0 op_sel_hi:[1,0]
	v_pk_mul_f32 v[24:25], v[8:9], v[24:25]
	v_pk_fma_f32 v[24:25], v[56:57], v[24:25], v[40:41]
	v_cvt_pk_bf16_f32 v38, v22, v23
	v_cvt_pk_bf16_f32 v39, v24, v25
	global_store_dwordx2 v245, v[38:39], s[10:11] offset:512
	v_pk_mul_f32 v[26:27], v[26:27], v[248:249] op_sel_hi:[1,0]
	v_pk_add_f32 v[58:59], v[58:59], 1.0 op_sel_hi:[1,0]
	v_pk_mul_f32 v[26:27], v[10:11], v[26:27]
	v_pk_fma_f32 v[26:27], v[58:59], v[26:27], v[42:43]
	v_pk_mul_f32 v[28:29], v[28:29], v[248:249] op_sel_hi:[1,0]
	v_pk_add_f32 v[60:61], v[60:61], 1.0 op_sel_hi:[1,0]
	v_pk_mul_f32 v[28:29], v[12:13], v[28:29]
	v_pk_fma_f32 v[28:29], v[60:61], v[28:29], v[44:45]
	v_cvt_pk_bf16_f32 v42, v26, v27
	v_cvt_pk_bf16_f32 v43, v28, v29
	global_store_dwordx2 v245, v[42:43], s[10:11] offset:1024
	v_pk_mul_f32 v[30:31], v[30:31], v[248:249] op_sel_hi:[1,0]
	v_pk_add_f32 v[62:63], v[62:63], 1.0 op_sel_hi:[1,0]
	v_pk_mul_f32 v[30:31], v[14:15], v[30:31]
	v_pk_fma_f32 v[30:31], v[62:63], v[30:31], v[46:47]
	v_pk_mul_f32 v[32:33], v[32:33], v[248:249] op_sel_hi:[1,0]
	v_pk_add_f32 v[64:65], v[64:65], 1.0 op_sel_hi:[1,0]
	v_pk_mul_f32 v[32:33], v[16:17], v[32:33]
	v_pk_fma_f32 v[32:33], v[64:65], v[32:33], v[48:49]
	v_cvt_pk_bf16_f32 v46, v30, v31
	v_cvt_pk_bf16_f32 v47, v32, v33
	global_store_dwordx2 v245, v[46:47], s[10:11] offset:1536
	s_add_i32 s21, s37, 1024
	s_mov_b32 s7, s38
	s_add_i32 s8, s39, 1024
	s_lshl_b32 s9, s7, 11
	s_add_i32 s9, s9, s8
	s_add_i32 s9, s9, 0xffffff00
	s_lshl_b32 s10, s7, 8
	s_add_i32 s10, s10, s8
	s_cmpk_gt_i32 s8, 0xff
	s_cselect_b32 s9, s9, s10
	s_cselect_b32 s26, s12, s14
	s_cselect_b32 s27, s13, s15
	s_cselect_b32 s10, s7, 8
	s_lshl_b32 s9, s9, 12
	s_add_u32 s26, s26, s9
	s_addc_u32 s27, s27, 0
	s_add_i32 s10, s10, s82
	s_mul_i32 s10, s10, s24
	s_add_u32 s28, s58, s10
	s_addc_u32 s29, s59, 0
	s_add_u32 s28, s28, 0x3000
	s_addc_u32 s29, s29, 0
	s_add_u32 s0, s28, 0x1000
	s_addc_u32 s1, s29, 0
	global_load_dwordx4 v[18:21], v244, s[26:27] nt
	global_load_dwordx4 v[22:25], v244, s[26:27] offset:1024 nt
	global_load_dwordx4 v[26:29], v244, s[26:27] offset:2048 nt
	global_load_dwordx4 v[30:33], v244, s[26:27] offset:3072 nt
	global_load_dwordx4 v[34:37], v244, s[28:29]
	global_load_dwordx4 v[38:41], v244, s[28:29] offset:1024
	global_load_dwordx4 v[42:45], v244, s[28:29] offset:2048
	global_load_dwordx4 v[46:49], v244, s[28:29] offset:3072
	global_load_dwordx4 v[50:53], v244, s[0:1]
	global_load_dwordx4 v[54:57], v244, s[0:1] offset:1024
	global_load_dwordx4 v[58:61], v244, s[0:1] offset:2048
	global_load_dwordx4 v[62:65], v244, s[0:1] offset:3072
	s_waitcnt vmcnt(28)
; DI unsigned pk_bf16(float lo, float hi) { f32x2 v = {lo, hi}; bf16v2 b = __builtin_convertvector(v, bf16v2); return __builtin_bit_cast(unsigned, b); }
; DI float red64(float x) { for (int o = 32; o > 0; o >>= 1) x += __shfl_xor(x, o); return x; }
; DI void modnorm_rows(const Params& p, int l, int which  , bool from_inputs, bool skip_ctx, int w0, int wstride, int lane) {
;     ...
;   for (; i < nrows; i += wstride) {
;     const int row = rowof(i); const int b = row / TB, s = row % TB;
;     f32x4 v[4];
; #pragma unroll
;     for (int q = 0; q < 4; ++q) v[q] = vn[q];
;     if (i + wstride < nrows) {
;       const int rn = rowof(i + wstride); const float* src = xsrc_row(p, from_inputs, rn / TB, rn % TB);
; #pragma unroll
;       for (int q = 0; q < 4; ++q) vn[q] = *(const f32x4*)(src + q * 256 + lane * 4);
;     }
;     const float* mod = p.MOD + (size_t)(l * 9 + (s < NCTX ? 8 : b)) * 6144 + (which ? 3 * 1024 : 0);
;     f32x4 sh[4], sc[4];
; #pragma unroll
;     for (int q = 0; q < 4; ++q) { sh[q] = *(const f32x4*)(mod + q * 256 + lane * 4); sc[q] = *(const f32x4*)(mod + 1024 + q * 256 + lane * 4); }
;     float ss = 0.f;
; #pragma unroll
;     for (int q = 0; q < 4; ++q) ss += v[q][0] * v[q][0] + v[q][1] * v[q][1] + v[q][2] * v[q][2] + v[q][3] * v[q][3];
;     ss = red64(ss);
;     const float rs = rsqrtf(ss * (1.f / 1024.f) + EPSF);
;     bf16_t* dst = p.HY + (size_t)row * DM;
; #pragma unroll
;     for (int q = 0; q < 4; ++q) {
;       float o[4];
; #pragma unroll
;       for (int j = 0; j < 4; ++j) o[j] = (v[q][j] * rs * gg[q][j]) * (1.f + sc[q][j]) + sh[q][j];
;       u32x2 w = {pk_bf16(o[0], o[1]), pk_bf16(o[2], o[3])};
;       *(u32x2*)(dst + q * 256 + lane * 4) = w;
;     }
;   }
	v_pk_mul_f32 v[246:247], v[66:67], v[66:67]
	v_pk_fma_f32 v[246:247], v[68:69], v[68:69], v[246:247]
	v_pk_fma_f32 v[246:247], v[70:71], v[70:71], v[246:247]
	v_pk_fma_f32 v[246:247], v[72:73], v[72:73], v[246:247]
	v_pk_fma_f32 v[246:247], v[74:75], v[74:75], v[246:247]
	v_pk_fma_f32 v[246:247], v[76:77], v[76:77], v[246:247]
	v_pk_fma_f32 v[246:247], v[78:79], v[78:79], v[246:247]
	v_pk_fma_f32 v[246:247], v[80:81], v[80:81], v[246:247]
	s_nop 0
	v_add_f32_e32 v246, v246, v247
	s_nop 1
	v_add_f32_dpp v246, v246, v246 quad_perm:[1,0,3,2] row_mask:0xf bank_mask:0xf
	s_nop 1
	v_add_f32_dpp v246, v246, v246 quad_perm:[2,3,0,1] row_mask:0xf bank_mask:0xf
	s_nop 1
	v_add_f32_dpp v246, v246, v246 row_half_mirror row_mask:0xf bank_mask:0xf
	s_nop 1
	v_add_f32_dpp v246, v246, v246 row_mirror row_mask:0xf bank_mask:0xf
	s_nop 1
	v_add_f32_dpp v246, v246, v246 row_bcast:15 row_mask:0xa bank_mask:0xf
	s_nop 1
	v_add_f32_dpp v246, v246, v246 row_bcast:31 row_mask:0xc bank_mask:0xf
	s_nop 1
	v_readlane_b32 s0, v246, 63
	s_add_i32 s21, s37, 512
	s_lshl_b32 s21, s21, 11
	s_add_u32 s10, s16, s21
	s_addc_u32 s11, s17, 0
	v_mov_b32_e32 v248, s0
	v_fmamk_f32 v248, v248, 0x3a800000, v143
	v_rsq_f32_e32 v248, v248
	s_nop 0
	v_pk_mul_f32 v[66:67], v[66:67], v[248:249] op_sel_hi:[1,0]
	v_pk_add_f32 v[98:99], v[98:99], 1.0 op_sel_hi:[1,0]
	v_pk_mul_f32 v[66:67], v[2:3], v[66:67]
	v_pk_fma_f32 v[66:67], v[98:99], v[66:67], v[82:83]
	v_pk_mul_f32 v[68:69], v[68:69], v[248:249] op_sel_hi:[1,0]
	v_pk_add_f32 v[100:101], v[100:101], 1.0 op_sel_hi:[1,0]
	v_pk_mul_f32 v[68:69], v[4:5], v[68:69]
	v_pk_fma_f32 v[68:69], v[100:101], v[68:69], v[84:85]
	v_cvt_pk_bf16_f32 v82, v66, v67
	v_cvt_pk_bf16_f32 v83, v68, v69
	global_store_dwordx2 v245, v[82:83], s[10:11]
	v_pk_mul_f32 v[70:71], v[70:71], v[248:249] op_sel_hi:[1,0]
	v_pk_add_f32 v[102:103], v[102:103], 1.0 op_sel_hi:[1,0]
	v_pk_mul_f32 v[70:71], v[6:7], v[70:71]
	v_pk_fma_f32 v[70:71], v[102:103], v[70:71], v[86:87]
	v_pk_mul_f32 v[72:73], v[72:73], v[248:249] op_sel_hi:[1,0]
	v_pk_add_f32 v[104:105], v[104:105], 1.0 op_sel_hi:[1,0]
	v_pk_mul_f32 v[72:73], v[8:9], v[72:73]
	v_pk_fma_f32 v[72:73], v[104:105], v[72:73], v[88:89]
	v_cvt_pk_bf16_f32 v86, v70, v71
	v_cvt_pk_bf16_f32 v87, v72, v73
	global_store_dwordx2 v245, v[86:87], s[10:11] offset:512
	v_pk_mul_f32 v[74:75], v[74:75], v[248:249] op_sel_hi:[1,0]
	v_pk_add_f32 v[106:107], v[106:107], 1.0 op_sel_hi:[1,0]
	v_pk_mul_f32 v[74:75], v[10:11], v[74:75]
	v_pk_fma_f32 v[74:75], v[106:107], v[74:75], v[90:91]
	v_pk_mul_f32 v[76:77], v[76:77], v[248:249] op_sel_hi:[1,0]
	v_pk_add_f32 v[108:109], v[108:109], 1.0 op_sel_hi:[1,0]
	v_pk_mul_f32 v[76:77], v[12:13], v[76:77]
	v_pk_fma_f32 v[76:77], v[108:109], v[76:77], v[92:93]
	v_cvt_pk_bf16_f32 v90, v74, v75
	v_cvt_pk_bf16_f32 v91, v76, v77
	global_store_dwordx2 v245, v[90:91], s[10:11] offset:1024
	v_pk_mul_f32 v[78:79], v[78:79], v[248:249] op_sel_hi:[1,0]
	v_pk_add_f32 v[118:119], v[118:119], 1.0 op_sel_hi:[1,0]
	v_pk_mul_f32 v[78:79], v[14:15], v[78:79]
	v_pk_fma_f32 v[78:79], v[118:119], v[78:79], v[94:95]
	v_pk_mul_f32 v[80:81], v[80:81], v[248:249] op_sel_hi:[1,0]
	v_pk_add_f32 v[120:121], v[120:121], 1.0 op_sel_hi:[1,0]
	v_pk_mul_f32 v[80:81], v[16:17], v[80:81]
	v_pk_fma_f32 v[80:81], v[120:121], v[80:81], v[96:97]
	v_cvt_pk_bf16_f32 v94, v78, v79
	v_cvt_pk_bf16_f32 v95, v80, v81
	global_store_dwordx2 v245, v[94:95], s[10:11] offset:1536
	s_add_i32 s21, s37, 1280
	s_mov_b32 s7, s38
	s_add_i32 s8, s39, 1280
	s_lshl_b32 s9, s7, 11
	s_add_i32 s9, s9, s8
	s_add_i32 s9, s9, 0xffffff00
	s_lshl_b32 s10, s7, 8
	s_add_i32 s10, s10, s8
	s_cmpk_gt_i32 s8, 0xff
	s_cselect_b32 s9, s9, s10
	s_cselect_b32 s26, s12, s14
	s_cselect_b32 s27, s13, s15
	s_cselect_b32 s10, s7, 8
	s_lshl_b32 s9, s9, 12
	s_add_u32 s26, s26, s9
	s_addc_u32 s27, s27, 0
	s_add_i32 s10, s10, s82
	s_mul_i32 s10, s10, s24
	s_add_u32 s28, s58, s10
	s_addc_u32 s29, s59, 0
	s_add_u32 s28, s28, 0x3000
	s_addc_u32 s29, s29, 0
	s_add_u32 s0, s28, 0x1000
	s_addc_u32 s1, s29, 0
	global_load_dwordx4 v[66:69], v244, s[26:27] nt
	global_load_dwordx4 v[70:73], v244, s[26:27] offset:1024 nt
	global_load_dwordx4 v[74:77], v244, s[26:27] offset:2048 nt
	global_load_dwordx4 v[78:81], v244, s[26:27] offset:3072 nt
	global_load_dwordx4 v[82:85], v244, s[28:29]
	global_load_dwordx4 v[86:89], v244, s[28:29] offset:1024
	global_load_dwordx4 v[90:93], v244, s[28:29] offset:2048
	global_load_dwordx4 v[94:97], v244, s[28:29] offset:3072
	global_load_dwordx4 v[98:101], v244, s[0:1]
	global_load_dwordx4 v[102:105], v244, s[0:1] offset:1024
	global_load_dwordx4 v[106:109], v244, s[0:1] offset:2048
	global_load_dwordx4 v[118:121], v244, s[0:1] offset:3072
	s_waitcnt vmcnt(32)
; DI unsigned pk_bf16(float lo, float hi) { f32x2 v = {lo, hi}; bf16v2 b = __builtin_convertvector(v, bf16v2); return __builtin_bit_cast(unsigned, b); }
; DI float red64(float x) { for (int o = 32; o > 0; o >>= 1) x += __shfl_xor(x, o); return x; }
; DI void modnorm_rows(const Params& p, int l, int which  , bool from_inputs, bool skip_ctx, int w0, int wstride, int lane) {
;     ...
;   for (; i < nrows; i += wstride) {
;     const int row = rowof(i); const int b = row / TB, s = row % TB;
;     f32x4 v[4];
; #pragma unroll
;     for (int q = 0; q < 4; ++q) v[q] = vn[q];
;     if (i + wstride < nrows) {
;       const int rn = rowof(i + wstride); const float* src = xsrc_row(p, from_inputs, rn / TB, rn % TB);
; #pragma unroll
;       for (int q = 0; q < 4; ++q) vn[q] = *(const f32x4*)(src + q * 256 + lane * 4);
;     }
;     const float* mod = p.MOD + (size_t)(l * 9 + (s < NCTX ? 8 : b)) * 6144 + (which ? 3 * 1024 : 0);
;     f32x4 sh[4], sc[4];
; #pragma unroll
;     for (int q = 0; q < 4; ++q) { sh[q] = *(const f32x4*)(mod + q * 256 + lane * 4); sc[q] = *(const f32x4*)(mod + 1024 + q * 256 + lane * 4); }
;     float ss = 0.f;
; #pragma unroll
;     for (int q = 0; q < 4; ++q) ss += v[q][0] * v[q][0] + v[q][1] * v[q][1] + v[q][2] * v[q][2] + v[q][3] * v[q][3];
;     ss = red64(ss);
;     const float rs = rsqrtf(ss * (1.f / 1024.f) + EPSF);
;     bf16_t* dst = p.HY + (size_t)row * DM;
; #pragma unroll
;     for (int q = 0; q < 4; ++q) {
;       float o[4];
; #pragma unroll
;       for (int j = 0; j < 4; ++j) o[j] = (v[q][j] * rs * gg[q][j]) * (1.f + sc[q][j]) + sh[q][j];
;       u32x2 w = {pk_bf16(o[0], o[1]), pk_bf16(o[2], o[3])};
;       *(u32x2*)(dst + q * 256 + lane * 4) = w;
;     }
;   }
	v_pk_mul_f32 v[246:247], v[122:123], v[122:123]
	v_pk_fma_f32 v[246:247], v[124:125], v[124:125], v[246:247]
	v_pk_fma_f32 v[246:247], v[126:127], v[126:127], v[246:247]
	v_pk_fma_f32 v[246:247], v[128:129], v[128:129], v[246:247]
	v_pk_fma_f32 v[246:247], v[130:131], v[130:131], v[246:247]
	v_pk_fma_f32 v[246:247], v[132:133], v[132:133], v[246:247]
	v_pk_fma_f32 v[246:247], v[134:135], v[134:135], v[246:247]
	v_pk_fma_f32 v[246:247], v[136:137], v[136:137], v[246:247]
	s_nop 0
	v_add_f32_e32 v246, v246, v247
	s_nop 1
	v_add_f32_dpp v246, v246, v246 quad_perm:[1,0,3,2] row_mask:0xf bank_mask:0xf
	s_nop 1
	v_add_f32_dpp v246, v246, v246 quad_perm:[2,3,0,1] row_mask:0xf bank_mask:0xf
	s_nop 1
	v_add_f32_dpp v246, v246, v246 row_half_mirror row_mask:0xf bank_mask:0xf
	s_nop 1
	v_add_f32_dpp v246, v246, v246 row_mirror row_mask:0xf bank_mask:0xf
	s_nop 1
	v_add_f32_dpp v246, v246, v246 row_bcast:15 row_mask:0xa bank_mask:0xf
	s_nop 1
	v_add_f32_dpp v246, v246, v246 row_bcast:31 row_mask:0xc bank_mask:0xf
	s_nop 1
	v_readlane_b32 s0, v246, 63
	s_add_i32 s21, s37, 768
	s_lshl_b32 s21, s21, 11
	s_add_u32 s10, s16, s21
	s_addc_u32 s11, s17, 0
	v_mov_b32_e32 v248, s0
	v_fmamk_f32 v248, v248, 0x3a800000, v143
	v_rsq_f32_e32 v248, v248
	s_nop 0
	v_pk_mul_f32 v[122:123], v[122:123], v[248:249] op_sel_hi:[1,0]
	v_pk_add_f32 v[176:177], v[176:177], 1.0 op_sel_hi:[1,0]
	v_pk_mul_f32 v[122:123], v[2:3], v[122:123]
	v_pk_fma_f32 v[122:123], v[176:177], v[122:123], v[160:161]
	v_pk_mul_f32 v[124:125], v[124:125], v[248:249] op_sel_hi:[1,0]
	v_pk_add_f32 v[178:179], v[178:179], 1.0 op_sel_hi:[1,0]
	v_pk_mul_f32 v[124:125], v[4:5], v[124:125]
	v_pk_fma_f32 v[124:125], v[178:179], v[124:125], v[162:163]
	v_cvt_pk_bf16_f32 v160, v122, v123
	v_cvt_pk_bf16_f32 v161, v124, v125
	global_store_dwordx2 v245, v[160:161], s[10:11]
	v_pk_mul_f32 v[126:127], v[126:127], v[248:249] op_sel_hi:[1,0]
	v_pk_add_f32 v[180:181], v[180:181], 1.0 op_sel_hi:[1,0]
	v_pk_mul_f32 v[126:127], v[6:7], v[126:127]
	v_pk_fma_f32 v[126:127], v[180:181], v[126:127], v[164:165]
	v_pk_mul_f32 v[128:129], v[128:129], v[248:249] op_sel_hi:[1,0]
	v_pk_add_f32 v[182:183], v[182:183], 1.0 op_sel_hi:[1,0]
	v_pk_mul_f32 v[128:129], v[8:9], v[128:129]
	v_pk_fma_f32 v[128:129], v[182:183], v[128:129], v[166:167]
	v_cvt_pk_bf16_f32 v164, v126, v127
	v_cvt_pk_bf16_f32 v165, v128, v129
	global_store_dwordx2 v245, v[164:165], s[10:11] offset:512
	v_pk_mul_f32 v[130:131], v[130:131], v[248:249] op_sel_hi:[1,0]
	v_pk_add_f32 v[184:185], v[184:185], 1.0 op_sel_hi:[1,0]
	v_pk_mul_f32 v[130:131], v[10:11], v[130:131]
	v_pk_fma_f32 v[130:131], v[184:185], v[130:131], v[168:169]
	v_pk_mul_f32 v[132:133], v[132:133], v[248:249] op_sel_hi:[1,0]
	v_pk_add_f32 v[186:187], v[186:187], 1.0 op_sel_hi:[1,0]
	v_pk_mul_f32 v[132:133], v[12:13], v[132:133]
	v_pk_fma_f32 v[132:133], v[186:187], v[132:133], v[170:171]
	v_cvt_pk_bf16_f32 v168, v130, v131
	v_cvt_pk_bf16_f32 v169, v132, v133
	global_store_dwordx2 v245, v[168:169], s[10:11] offset:1024
	v_pk_mul_f32 v[134:135], v[134:135], v[248:249] op_sel_hi:[1,0]
	v_pk_add_f32 v[188:189], v[188:189], 1.0 op_sel_hi:[1,0]
	v_pk_mul_f32 v[134:135], v[14:15], v[134:135]
	v_pk_fma_f32 v[134:135], v[188:189], v[134:135], v[172:173]
	v_pk_mul_f32 v[136:137], v[136:137], v[248:249] op_sel_hi:[1,0]
	v_pk_add_f32 v[190:191], v[190:191], 1.0 op_sel_hi:[1,0]
	v_pk_mul_f32 v[136:137], v[16:17], v[136:137]
	v_pk_fma_f32 v[136:137], v[190:191], v[136:137], v[174:175]
	v_cvt_pk_bf16_f32 v172, v134, v135
	v_cvt_pk_bf16_f32 v173, v136, v137
	global_store_dwordx2 v245, v[172:173], s[10:11] offset:1536
	s_add_i32 s21, s37, 1536
	s_mov_b32 s7, s38
	s_add_i32 s8, s39, 1536
	s_lshl_b32 s9, s7, 11
	s_add_i32 s9, s9, s8
	s_add_i32 s9, s9, 0xffffff00
	s_lshl_b32 s10, s7, 8
	s_add_i32 s10, s10, s8
	s_cmpk_gt_i32 s8, 0xff
	s_cselect_b32 s9, s9, s10
	s_cselect_b32 s26, s12, s14
	s_cselect_b32 s27, s13, s15
	s_cselect_b32 s10, s7, 8
	s_lshl_b32 s9, s9, 12
	s_add_u32 s26, s26, s9
	s_addc_u32 s27, s27, 0
	s_add_i32 s10, s10, s82
	s_mul_i32 s10, s10, s24
	s_add_u32 s28, s58, s10
	s_addc_u32 s29, s59, 0
	s_add_u32 s28, s28, 0x3000
	s_addc_u32 s29, s29, 0
	s_add_u32 s0, s28, 0x1000
	s_addc_u32 s1, s29, 0
	global_load_dwordx4 v[122:125], v244, s[26:27] nt
	global_load_dwordx4 v[126:129], v244, s[26:27] offset:1024 nt
	global_load_dwordx4 v[130:133], v244, s[26:27] offset:2048 nt
	global_load_dwordx4 v[134:137], v244, s[26:27] offset:3072 nt
	global_load_dwordx4 v[160:163], v244, s[28:29]
	global_load_dwordx4 v[164:167], v244, s[28:29] offset:1024
	global_load_dwordx4 v[168:171], v244, s[28:29] offset:2048
	global_load_dwordx4 v[172:175], v244, s[28:29] offset:3072
	global_load_dwordx4 v[176:179], v244, s[0:1]
	global_load_dwordx4 v[180:183], v244, s[0:1] offset:1024
	global_load_dwordx4 v[184:187], v244, s[0:1] offset:2048
	global_load_dwordx4 v[188:191], v244, s[0:1] offset:3072
	s_waitcnt vmcnt(32)
; DI unsigned pk_bf16(float lo, float hi) { f32x2 v = {lo, hi}; bf16v2 b = __builtin_convertvector(v, bf16v2); return __builtin_bit_cast(unsigned, b); }
; DI float red64(float x) { for (int o = 32; o > 0; o >>= 1) x += __shfl_xor(x, o); return x; }
; DI void modnorm_rows(const Params& p, int l, int which  , bool from_inputs, bool skip_ctx, int w0, int wstride, int lane) {
;     ...
;   for (; i < nrows; i += wstride) {
;     const int row = rowof(i); const int b = row / TB, s = row % TB;
;     f32x4 v[4];
; #pragma unroll
;     for (int q = 0; q < 4; ++q) v[q] = vn[q];
;     if (i + wstride < nrows) {
;       const int rn = rowof(i + wstride); const float* src = xsrc_row(p, from_inputs, rn / TB, rn % TB);
; #pragma unroll
;       for (int q = 0; q < 4; ++q) vn[q] = *(const f32x4*)(src + q * 256 + lane * 4);
;     }
;     const float* mod = p.MOD + (size_t)(l * 9 + (s < NCTX ? 8 : b)) * 6144 + (which ? 3 * 1024 : 0);
;     f32x4 sh[4], sc[4];
; #pragma unroll
;     for (int q = 0; q < 4; ++q) { sh[q] = *(const f32x4*)(mod + q * 256 + lane * 4); sc[q] = *(const f32x4*)(mod + 1024 + q * 256 + lane * 4); }
;     float ss = 0.f;
; #pragma unroll
;     for (int q = 0; q < 4; ++q) ss += v[q][0] * v[q][0] + v[q][1] * v[q][1] + v[q][2] * v[q][2] + v[q][3] * v[q][3];
;     ss = red64(ss);
;     const float rs = rsqrtf(ss * (1.f / 1024.f) + EPSF);
;     bf16_t* dst = p.HY + (size_t)row * DM;
; #pragma unroll
;     for (int q = 0; q < 4; ++q) {
;       float o[4];
; #pragma unroll
;       for (int j = 0; j < 4; ++j) o[j] = (v[q][j] * rs * gg[q][j]) * (1.f + sc[q][j]) + sh[q][j];
;       u32x2 w = {pk_bf16(o[0], o[1]), pk_bf16(o[2], o[3])};
;       *(u32x2*)(dst + q * 256 + lane * 4) = w;
;     }
;   }
	v_pk_mul_f32 v[246:247], v[18:19], v[18:19]
	v_pk_fma_f32 v[246:247], v[20:21], v[20:21], v[246:247]
	v_pk_fma_f32 v[246:247], v[22:23], v[22:23], v[246:247]
	v_pk_fma_f32 v[246:247], v[24:25], v[24:25], v[246:247]
	v_pk_fma_f32 v[246:247], v[26:27], v[26:27], v[246:247]
	v_pk_fma_f32 v[246:247], v[28:29], v[28:29], v[246:247]
	v_pk_fma_f32 v[246:247], v[30:31], v[30:31], v[246:247]
	v_pk_fma_f32 v[246:247], v[32:33], v[32:33], v[246:247]
	s_nop 0
	v_add_f32_e32 v246, v246, v247
	s_nop 1
	v_add_f32_dpp v246, v246, v246 quad_perm:[1,0,3,2] row_mask:0xf bank_mask:0xf
	s_nop 1
	v_add_f32_dpp v246, v246, v246 quad_perm:[2,3,0,1] row_mask:0xf bank_mask:0xf
	s_nop 1
	v_add_f32_dpp v246, v246, v246 row_half_mirror row_mask:0xf bank_mask:0xf
	s_nop 1
	v_add_f32_dpp v246, v246, v246 row_mirror row_mask:0xf bank_mask:0xf
	s_nop 1
	v_add_f32_dpp v246, v246, v246 row_bcast:15 row_mask:0xa bank_mask:0xf
	s_nop 1
	v_add_f32_dpp v246, v246, v246 row_bcast:31 row_mask:0xc bank_mask:0xf
	s_nop 1
	v_readlane_b32 s0, v246, 63
	s_add_i32 s21, s37, 1024
	s_lshl_b32 s21, s21, 11
	s_add_u32 s10, s16, s21
	s_addc_u32 s11, s17, 0
	v_mov_b32_e32 v248, s0
	v_fmamk_f32 v248, v248, 0x3a800000, v143
	v_rsq_f32_e32 v248, v248
	s_nop 0
	v_pk_mul_f32 v[18:19], v[18:19], v[248:249] op_sel_hi:[1,0]
	v_pk_add_f32 v[50:51], v[50:51], 1.0 op_sel_hi:[1,0]
	v_pk_mul_f32 v[18:19], v[2:3], v[18:19]
	v_pk_fma_f32 v[18:19], v[50:51], v[18:19], v[34:35]
	v_pk_mul_f32 v[20:21], v[20:21], v[248:249] op_sel_hi:[1,0]
	v_pk_add_f32 v[52:53], v[52:53], 1.0 op_sel_hi:[1,0]
	v_pk_mul_f32 v[20:21], v[4:5], v[20:21]
	v_pk_fma_f32 v[20:21], v[52:53], v[20:21], v[36:37]
	v_cvt_pk_bf16_f32 v34, v18, v19
	v_cvt_pk_bf16_f32 v35, v20, v21
	global_store_dwordx2 v245, v[34:35], s[10:11]
	v_pk_mul_f32 v[22:23], v[22:23], v[248:249] op_sel_hi:[1,0]
	v_pk_add_f32 v[54:55], v[54:55], 1.0 op_sel_hi:[1,0]
	v_pk_mul_f32 v[22:23], v[6:7], v[22:23]
	v_pk_fma_f32 v[22:23], v[54:55], v[22:23], v[38:39]
	v_pk_mul_f32 v[24:25], v[24:25], v[248:249] op_sel_hi:[1,0]
	v_pk_add_f32 v[56:57], v[56:57], 1.0 op_sel_hi:[1,0]
	v_pk_mul_f32 v[24:25], v[8:9], v[24:25]
	v_pk_fma_f32 v[24:25], v[56:57], v[24:25], v[40:41]
	v_cvt_pk_bf16_f32 v38, v22, v23
	v_cvt_pk_bf16_f32 v39, v24, v25
	global_store_dwordx2 v245, v[38:39], s[10:11] offset:512
	v_pk_mul_f32 v[26:27], v[26:27], v[248:249] op_sel_hi:[1,0]
	v_pk_add_f32 v[58:59], v[58:59], 1.0 op_sel_hi:[1,0]
	v_pk_mul_f32 v[26:27], v[10:11], v[26:27]
	v_pk_fma_f32 v[26:27], v[58:59], v[26:27], v[42:43]
	v_pk_mul_f32 v[28:29], v[28:29], v[248:249] op_sel_hi:[1,0]
	v_pk_add_f32 v[60:61], v[60:61], 1.0 op_sel_hi:[1,0]
	v_pk_mul_f32 v[28:29], v[12:13], v[28:29]
	v_pk_fma_f32 v[28:29], v[60:61], v[28:29], v[44:45]
	v_cvt_pk_bf16_f32 v42, v26, v27
	v_cvt_pk_bf16_f32 v43, v28, v29
	global_store_dwordx2 v245, v[42:43], s[10:11] offset:1024
	v_pk_mul_f32 v[30:31], v[30:31], v[248:249] op_sel_hi:[1,0]
	v_pk_add_f32 v[62:63], v[62:63], 1.0 op_sel_hi:[1,0]
	v_pk_mul_f32 v[30:31], v[14:15], v[30:31]
	v_pk_fma_f32 v[30:31], v[62:63], v[30:31], v[46:47]
	v_pk_mul_f32 v[32:33], v[32:33], v[248:249] op_sel_hi:[1,0]
	v_pk_add_f32 v[64:65], v[64:65], 1.0 op_sel_hi:[1,0]
	v_pk_mul_f32 v[32:33], v[16:17], v[32:33]
	v_pk_fma_f32 v[32:33], v[64:65], v[32:33], v[48:49]
	v_cvt_pk_bf16_f32 v46, v30, v31
	v_cvt_pk_bf16_f32 v47, v32, v33
	global_store_dwordx2 v245, v[46:47], s[10:11] offset:1536
	s_add_i32 s21, s37, 1792
	s_mov_b32 s7, s38
	s_add_i32 s8, s39, 1792
	s_lshl_b32 s9, s7, 11
	s_add_i32 s9, s9, s8
	s_add_i32 s9, s9, 0xffffff00
	s_lshl_b32 s10, s7, 8
	s_add_i32 s10, s10, s8
	s_cmpk_gt_i32 s8, 0xff
	s_cselect_b32 s9, s9, s10
	s_cselect_b32 s26, s12, s14
	s_cselect_b32 s27, s13, s15
	s_cselect_b32 s10, s7, 8
	s_lshl_b32 s9, s9, 12
	s_add_u32 s26, s26, s9
	s_addc_u32 s27, s27, 0
	s_add_i32 s10, s10, s82
	s_mul_i32 s10, s10, s24
	s_add_u32 s28, s58, s10
	s_addc_u32 s29, s59, 0
	s_add_u32 s28, s28, 0x3000
	s_addc_u32 s29, s29, 0
	s_add_u32 s0, s28, 0x1000
	s_addc_u32 s1, s29, 0
	global_load_dwordx4 v[18:21], v244, s[26:27] nt
	global_load_dwordx4 v[22:25], v244, s[26:27] offset:1024 nt
	global_load_dwordx4 v[26:29], v244, s[26:27] offset:2048 nt
	global_load_dwordx4 v[30:33], v244, s[26:27] offset:3072 nt
	global_load_dwordx4 v[34:37], v244, s[28:29]
	global_load_dwordx4 v[38:41], v244, s[28:29] offset:1024
	global_load_dwordx4 v[42:45], v244, s[28:29] offset:2048
	global_load_dwordx4 v[46:49], v244, s[28:29] offset:3072
	global_load_dwordx4 v[50:53], v244, s[0:1]
	global_load_dwordx4 v[54:57], v244, s[0:1] offset:1024
	global_load_dwordx4 v[58:61], v244, s[0:1] offset:2048
	global_load_dwordx4 v[62:65], v244, s[0:1] offset:3072
	s_waitcnt vmcnt(32)
; DI unsigned pk_bf16(float lo, float hi) { f32x2 v = {lo, hi}; bf16v2 b = __builtin_convertvector(v, bf16v2); return __builtin_bit_cast(unsigned, b); }
; DI float red64(float x) { for (int o = 32; o > 0; o >>= 1) x += __shfl_xor(x, o); return x; }
; DI void modnorm_rows(const Params& p, int l, int which  , bool from_inputs, bool skip_ctx, int w0, int wstride, int lane) {
;     ...
;   for (; i < nrows; i += wstride) {
;     const int row = rowof(i); const int b = row / TB, s = row % TB;
;     f32x4 v[4];
; #pragma unroll
;     for (int q = 0; q < 4; ++q) v[q] = vn[q];
;     if (i + wstride < nrows) {
;       const int rn = rowof(i + wstride); const float* src = xsrc_row(p, from_inputs, rn / TB, rn % TB);
; #pragma unroll
;       for (int q = 0; q < 4; ++q) vn[q] = *(const f32x4*)(src + q * 256 + lane * 4);
;     }
;     const float* mod = p.MOD + (size_t)(l * 9 + (s < NCTX ? 8 : b)) * 6144 + (which ? 3 * 1024 : 0);
;     f32x4 sh[4], sc[4];
; #pragma unroll
;     for (int q = 0; q < 4; ++q) { sh[q] = *(const f32x4*)(mod + q * 256 + lane * 4); sc[q] = *(const f32x4*)(mod + 1024 + q * 256 + lane * 4); }
;     float ss = 0.f;
; #pragma unroll
;     for (int q = 0; q < 4; ++q) ss += v[q][0] * v[q][0] + v[q][1] * v[q][1] + v[q][2] * v[q][2] + v[q][3] * v[q][3];
;     ss = red64(ss);
;     const float rs = rsqrtf(ss * (1.f / 1024.f) + EPSF);
;     bf16_t* dst = p.HY + (size_t)row * DM;
; #pragma unroll
;     for (int q = 0; q < 4; ++q) {
;       float o[4];
; #pragma unroll
;       for (int j = 0; j < 4; ++j) o[j] = (v[q][j] * rs * gg[q][j]) * (1.f + sc[q][j]) + sh[q][j];
;       u32x2 w = {pk_bf16(o[0], o[1]), pk_bf16(o[2], o[3])};
;       *(u32x2*)(dst + q * 256 + lane * 4) = w;
;     }
;   }
	v_pk_mul_f32 v[246:247], v[66:67], v[66:67]
	v_pk_fma_f32 v[246:247], v[68:69], v[68:69], v[246:247]
	v_pk_fma_f32 v[246:247], v[70:71], v[70:71], v[246:247]
	v_pk_fma_f32 v[246:247], v[72:73], v[72:73], v[246:247]
	v_pk_fma_f32 v[246:247], v[74:75], v[74:75], v[246:247]
	v_pk_fma_f32 v[246:247], v[76:77], v[76:77], v[246:247]
	v_pk_fma_f32 v[246:247], v[78:79], v[78:79], v[246:247]
	v_pk_fma_f32 v[246:247], v[80:81], v[80:81], v[246:247]
	s_nop 0
	v_add_f32_e32 v246, v246, v247
	s_nop 1
	v_add_f32_dpp v246, v246, v246 quad_perm:[1,0,3,2] row_mask:0xf bank_mask:0xf
	s_nop 1
	v_add_f32_dpp v246, v246, v246 quad_perm:[2,3,0,1] row_mask:0xf bank_mask:0xf
	s_nop 1
	v_add_f32_dpp v246, v246, v246 row_half_mirror row_mask:0xf bank_mask:0xf
	s_nop 1
	v_add_f32_dpp v246, v246, v246 row_mirror row_mask:0xf bank_mask:0xf
	s_nop 1
	v_add_f32_dpp v246, v246, v246 row_bcast:15 row_mask:0xa bank_mask:0xf
	s_nop 1
	v_add_f32_dpp v246, v246, v246 row_bcast:31 row_mask:0xc bank_mask:0xf
	s_nop 1
	v_readlane_b32 s0, v246, 63
	s_add_i32 s21, s37, 1280
	s_lshl_b32 s21, s21, 11
	s_add_u32 s10, s16, s21
	s_addc_u32 s11, s17, 0
	v_mov_b32_e32 v248, s0
	v_fmamk_f32 v248, v248, 0x3a800000, v143
	v_rsq_f32_e32 v248, v248
	s_nop 0
	v_pk_mul_f32 v[66:67], v[66:67], v[248:249] op_sel_hi:[1,0]
	v_pk_add_f32 v[98:99], v[98:99], 1.0 op_sel_hi:[1,0]
	v_pk_mul_f32 v[66:67], v[2:3], v[66:67]
	v_pk_fma_f32 v[66:67], v[98:99], v[66:67], v[82:83]
	v_pk_mul_f32 v[68:69], v[68:69], v[248:249] op_sel_hi:[1,0]
	v_pk_add_f32 v[100:101], v[100:101], 1.0 op_sel_hi:[1,0]
	v_pk_mul_f32 v[68:69], v[4:5], v[68:69]
	v_pk_fma_f32 v[68:69], v[100:101], v[68:69], v[84:85]
	v_cvt_pk_bf16_f32 v82, v66, v67
	v_cvt_pk_bf16_f32 v83, v68, v69
	global_store_dwordx2 v245, v[82:83], s[10:11]
	v_pk_mul_f32 v[70:71], v[70:71], v[248:249] op_sel_hi:[1,0]
	v_pk_add_f32 v[102:103], v[102:103], 1.0 op_sel_hi:[1,0]
	v_pk_mul_f32 v[70:71], v[6:7], v[70:71]
	v_pk_fma_f32 v[70:71], v[102:103], v[70:71], v[86:87]
	v_pk_mul_f32 v[72:73], v[72:73], v[248:249] op_sel_hi:[1,0]
	v_pk_add_f32 v[104:105], v[104:105], 1.0 op_sel_hi:[1,0]
	v_pk_mul_f32 v[72:73], v[8:9], v[72:73]
	v_pk_fma_f32 v[72:73], v[104:105], v[72:73], v[88:89]
	v_cvt_pk_bf16_f32 v86, v70, v71
	v_cvt_pk_bf16_f32 v87, v72, v73
	global_store_dwordx2 v245, v[86:87], s[10:11] offset:512
	v_pk_mul_f32 v[74:75], v[74:75], v[248:249] op_sel_hi:[1,0]
	v_pk_add_f32 v[106:107], v[106:107], 1.0 op_sel_hi:[1,0]
	v_pk_mul_f32 v[74:75], v[10:11], v[74:75]
	v_pk_fma_f32 v[74:75], v[106:107], v[74:75], v[90:91]
	v_pk_mul_f32 v[76:77], v[76:77], v[248:249] op_sel_hi:[1,0]
	v_pk_add_f32 v[108:109], v[108:109], 1.0 op_sel_hi:[1,0]
	v_pk_mul_f32 v[76:77], v[12:13], v[76:77]
	v_pk_fma_f32 v[76:77], v[108:109], v[76:77], v[92:93]
	v_cvt_pk_bf16_f32 v90, v74, v75
	v_cvt_pk_bf16_f32 v91, v76, v77
	global_store_dwordx2 v245, v[90:91], s[10:11] offset:1024
	v_pk_mul_f32 v[78:79], v[78:79], v[248:249] op_sel_hi:[1,0]
	v_pk_add_f32 v[118:119], v[118:119], 1.0 op_sel_hi:[1,0]
	v_pk_mul_f32 v[78:79], v[14:15], v[78:79]
	v_pk_fma_f32 v[78:79], v[118:119], v[78:79], v[94:95]
	v_pk_mul_f32 v[80:81], v[80:81], v[248:249] op_sel_hi:[1,0]
	v_pk_add_f32 v[120:121], v[120:121], 1.0 op_sel_hi:[1,0]
	v_pk_mul_f32 v[80:81], v[16:17], v[80:81]
	v_pk_fma_f32 v[80:81], v[120:121], v[80:81], v[96:97]
	v_cvt_pk_bf16_f32 v94, v78, v79
	v_cvt_pk_bf16_f32 v95, v80, v81
	global_store_dwordx2 v245, v[94:95], s[10:11] offset:1536
	s_add_i32 s21, s37, 2048
	s_mov_b32 s7, s38
	s_add_i32 s8, s39, 2048
	s_lshl_b32 s9, s7, 11
	s_add_i32 s9, s9, s8
	s_add_i32 s9, s9, 0xffffff00
	s_lshl_b32 s10, s7, 8
	s_add_i32 s10, s10, s8
	s_cmpk_gt_i32 s8, 0xff
	s_cselect_b32 s9, s9, s10
	s_cselect_b32 s26, s12, s14
	s_cselect_b32 s27, s13, s15
	s_cselect_b32 s10, s7, 8
	s_lshl_b32 s9, s9, 12
	s_add_u32 s26, s26, s9
	s_addc_u32 s27, s27, 0
	s_add_i32 s10, s10, s82
	s_mul_i32 s10, s10, s24
	s_add_u32 s28, s58, s10
	s_addc_u32 s29, s59, 0
	s_add_u32 s28, s28, 0x3000
	s_addc_u32 s29, s29, 0
	s_add_u32 s0, s28, 0x1000
	s_addc_u32 s1, s29, 0
	global_load_dwordx4 v[66:69], v244, s[26:27] nt
	global_load_dwordx4 v[70:73], v244, s[26:27] offset:1024 nt
	global_load_dwordx4 v[74:77], v244, s[26:27] offset:2048 nt
	global_load_dwordx4 v[78:81], v244, s[26:27] offset:3072 nt
	global_load_dwordx4 v[82:85], v244, s[28:29]
	global_load_dwordx4 v[86:89], v244, s[28:29] offset:1024
	global_load_dwordx4 v[90:93], v244, s[28:29] offset:2048
	global_load_dwordx4 v[94:97], v244, s[28:29] offset:3072
	global_load_dwordx4 v[98:101], v244, s[0:1]
	global_load_dwordx4 v[102:105], v244, s[0:1] offset:1024
	global_load_dwordx4 v[106:109], v244, s[0:1] offset:2048
	global_load_dwordx4 v[118:121], v244, s[0:1] offset:3072
	s_waitcnt vmcnt(32)
; DI unsigned pk_bf16(float lo, float hi) { f32x2 v = {lo, hi}; bf16v2 b = __builtin_convertvector(v, bf16v2); return __builtin_bit_cast(unsigned, b); }
; DI float red64(float x) { for (int o = 32; o > 0; o >>= 1) x += __shfl_xor(x, o); return x; }
; DI void modnorm_rows(const Params& p, int l, int which  , bool from_inputs, bool skip_ctx, int w0, int wstride, int lane) {
;     ...
;   for (; i < nrows; i += wstride) {
;     const int row = rowof(i); const int b = row / TB, s = row % TB;
;     f32x4 v[4];
; #pragma unroll
;     for (int q = 0; q < 4; ++q) v[q] = vn[q];
;     if (i + wstride < nrows) {
;       const int rn = rowof(i + wstride); const float* src = xsrc_row(p, from_inputs, rn / TB, rn % TB);
; #pragma unroll
;       for (int q = 0; q < 4; ++q) vn[q] = *(const f32x4*)(src + q * 256 + lane * 4);
;     }
;     const float* mod = p.MOD + (size_t)(l * 9 + (s < NCTX ? 8 : b)) * 6144 + (which ? 3 * 1024 : 0);
;     f32x4 sh[4], sc[4];
; #pragma unroll
;     for (int q = 0; q < 4; ++q) { sh[q] = *(const f32x4*)(mod + q * 256 + lane * 4); sc[q] = *(const f32x4*)(mod + 1024 + q * 256 + lane * 4); }
;     float ss = 0.f;
; #pragma unroll
;     for (int q = 0; q < 4; ++q) ss += v[q][0] * v[q][0] + v[q][1] * v[q][1] + v[q][2] * v[q][2] + v[q][3] * v[q][3];
;     ss = red64(ss);
;     const float rs = rsqrtf(ss * (1.f / 1024.f) + EPSF);
;     bf16_t* dst = p.HY + (size_t)row * DM;
; #pragma unroll
;     for (int q = 0; q < 4; ++q) {
;       float o[4];
; #pragma unroll
;       for (int j = 0; j < 4; ++j) o[j] = (v[q][j] * rs * gg[q][j]) * (1.f + sc[q][j]) + sh[q][j];
;       u32x2 w = {pk_bf16(o[0], o[1]), pk_bf16(o[2], o[3])};
;       *(u32x2*)(dst + q * 256 + lane * 4) = w;
;     }
;   }
	v_pk_mul_f32 v[246:247], v[122:123], v[122:123]
	v_pk_fma_f32 v[246:247], v[124:125], v[124:125], v[246:247]
	v_pk_fma_f32 v[246:247], v[126:127], v[126:127], v[246:247]
	v_pk_fma_f32 v[246:247], v[128:129], v[128:129], v[246:247]
	v_pk_fma_f32 v[246:247], v[130:131], v[130:131], v[246:247]
	v_pk_fma_f32 v[246:247], v[132:133], v[132:133], v[246:247]
	v_pk_fma_f32 v[246:247], v[134:135], v[134:135], v[246:247]
	v_pk_fma_f32 v[246:247], v[136:137], v[136:137], v[246:247]
	s_nop 0
	v_add_f32_e32 v246, v246, v247
	s_nop 1
	v_add_f32_dpp v246, v246, v246 quad_perm:[1,0,3,2] row_mask:0xf bank_mask:0xf
	s_nop 1
	v_add_f32_dpp v246, v246, v246 quad_perm:[2,3,0,1] row_mask:0xf bank_mask:0xf
	s_nop 1
	v_add_f32_dpp v246, v246, v246 row_half_mirror row_mask:0xf bank_mask:0xf
	s_nop 1
	v_add_f32_dpp v246, v246, v246 row_mirror row_mask:0xf bank_mask:0xf
	s_nop 1
	v_add_f32_dpp v246, v246, v246 row_bcast:15 row_mask:0xa bank_mask:0xf
	s_nop 1
	v_add_f32_dpp v246, v246, v246 row_bcast:31 row_mask:0xc bank_mask:0xf
	s_nop 1
	v_readlane_b32 s0, v246, 63
	s_add_i32 s21, s37, 1536
	s_lshl_b32 s21, s21, 11
	s_add_u32 s10, s16, s21
	s_addc_u32 s11, s17, 0
	v_mov_b32_e32 v248, s0
	v_fmamk_f32 v248, v248, 0x3a800000, v143
	v_rsq_f32_e32 v248, v248
	s_nop 0
	v_pk_mul_f32 v[122:123], v[122:123], v[248:249] op_sel_hi:[1,0]
	v_pk_add_f32 v[176:177], v[176:177], 1.0 op_sel_hi:[1,0]
	v_pk_mul_f32 v[122:123], v[2:3], v[122:123]
	v_pk_fma_f32 v[122:123], v[176:177], v[122:123], v[160:161]
	v_pk_mul_f32 v[124:125], v[124:125], v[248:249] op_sel_hi:[1,0]
	v_pk_add_f32 v[178:179], v[178:179], 1.0 op_sel_hi:[1,0]
	v_pk_mul_f32 v[124:125], v[4:5], v[124:125]
	v_pk_fma_f32 v[124:125], v[178:179], v[124:125], v[162:163]
	v_cvt_pk_bf16_f32 v160, v122, v123
	v_cvt_pk_bf16_f32 v161, v124, v125
	global_store_dwordx2 v245, v[160:161], s[10:11]
	v_pk_mul_f32 v[126:127], v[126:127], v[248:249] op_sel_hi:[1,0]
	v_pk_add_f32 v[180:181], v[180:181], 1.0 op_sel_hi:[1,0]
	v_pk_mul_f32 v[126:127], v[6:7], v[126:127]
	v_pk_fma_f32 v[126:127], v[180:181], v[126:127], v[164:165]
	v_pk_mul_f32 v[128:129], v[128:129], v[248:249] op_sel_hi:[1,0]
	v_pk_add_f32 v[182:183], v[182:183], 1.0 op_sel_hi:[1,0]
	v_pk_mul_f32 v[128:129], v[8:9], v[128:129]
	v_pk_fma_f32 v[128:129], v[182:183], v[128:129], v[166:167]
	v_cvt_pk_bf16_f32 v164, v126, v127
	v_cvt_pk_bf16_f32 v165, v128, v129
	global_store_dwordx2 v245, v[164:165], s[10:11] offset:512
	v_pk_mul_f32 v[130:131], v[130:131], v[248:249] op_sel_hi:[1,0]
	v_pk_add_f32 v[184:185], v[184:185], 1.0 op_sel_hi:[1,0]
	v_pk_mul_f32 v[130:131], v[10:11], v[130:131]
	v_pk_fma_f32 v[130:131], v[184:185], v[130:131], v[168:169]
	v_pk_mul_f32 v[132:133], v[132:133], v[248:249] op_sel_hi:[1,0]
	v_pk_add_f32 v[186:187], v[186:187], 1.0 op_sel_hi:[1,0]
	v_pk_mul_f32 v[132:133], v[12:13], v[132:133]
	v_pk_fma_f32 v[132:133], v[186:187], v[132:133], v[170:171]
	v_cvt_pk_bf16_f32 v168, v130, v131
	v_cvt_pk_bf16_f32 v169, v132, v133
	global_store_dwordx2 v245, v[168:169], s[10:11] offset:1024
	v_pk_mul_f32 v[134:135], v[134:135], v[248:249] op_sel_hi:[1,0]
	v_pk_add_f32 v[188:189], v[188:189], 1.0 op_sel_hi:[1,0]
	v_pk_mul_f32 v[134:135], v[14:15], v[134:135]
	v_pk_fma_f32 v[134:135], v[188:189], v[134:135], v[172:173]
	v_pk_mul_f32 v[136:137], v[136:137], v[248:249] op_sel_hi:[1,0]
	v_pk_add_f32 v[190:191], v[190:191], 1.0 op_sel_hi:[1,0]
	v_pk_mul_f32 v[136:137], v[16:17], v[136:137]
	v_pk_fma_f32 v[136:137], v[190:191], v[136:137], v[174:175]
	v_cvt_pk_bf16_f32 v172, v134, v135
	v_cvt_pk_bf16_f32 v173, v136, v137
	global_store_dwordx2 v245, v[172:173], s[10:11] offset:1536
	s_waitcnt vmcnt(20)
; DI unsigned pk_bf16(float lo, float hi) { f32x2 v = {lo, hi}; bf16v2 b = __builtin_convertvector(v, bf16v2); return __builtin_bit_cast(unsigned, b); }
; DI float red64(float x) { for (int o = 32; o > 0; o >>= 1) x += __shfl_xor(x, o); return x; }
; DI void modnorm_rows(const Params& p, int l, int which  , bool from_inputs, bool skip_ctx, int w0, int wstride, int lane) {
;     ...
;   for (; i < nrows; i += wstride) {
;     const int row = rowof(i); const int b = row / TB, s = row % TB;
;     f32x4 v[4];
; #pragma unroll
;     for (int q = 0; q < 4; ++q) v[q] = vn[q];
;     if (i + wstride < nrows) {
;       const int rn = rowof(i + wstride); const float* src = xsrc_row(p, from_inputs, rn / TB, rn % TB);
; #pragma unroll
;       for (int q = 0; q < 4; ++q) vn[q] = *(const f32x4*)(src + q * 256 + lane * 4);
;     }
;     const float* mod = p.MOD + (size_t)(l * 9 + (s < NCTX ? 8 : b)) * 6144 + (which ? 3 * 1024 : 0);
;     f32x4 sh[4], sc[4];
; #pragma unroll
;     for (int q = 0; q < 4; ++q) { sh[q] = *(const f32x4*)(mod + q * 256 + lane * 4); sc[q] = *(const f32x4*)(mod + 1024 + q * 256 + lane * 4); }
;     float ss = 0.f;
; #pragma unroll
;     for (int q = 0; q < 4; ++q) ss += v[q][0] * v[q][0] + v[q][1] * v[q][1] + v[q][2] * v[q][2] + v[q][3] * v[q][3];
;     ss = red64(ss);
;     const float rs = rsqrtf(ss * (1.f / 1024.f) + EPSF);
;     bf16_t* dst = p.HY + (size_t)row * DM;
; #pragma unroll
;     for (int q = 0; q < 4; ++q) {
;       float o[4];
; #pragma unroll
;       for (int j = 0; j < 4; ++j) o[j] = (v[q][j] * rs * gg[q][j]) * (1.f + sc[q][j]) + sh[q][j];
;       u32x2 w = {pk_bf16(o[0], o[1]), pk_bf16(o[2], o[3])};
;       *(u32x2*)(dst + q * 256 + lane * 4) = w;
;     }
;   }
	v_pk_mul_f32 v[246:247], v[18:19], v[18:19]
	v_pk_fma_f32 v[246:247], v[20:21], v[20:21], v[246:247]
	v_pk_fma_f32 v[246:247], v[22:23], v[22:23], v[246:247]
	v_pk_fma_f32 v[246:247], v[24:25], v[24:25], v[246:247]
	v_pk_fma_f32 v[246:247], v[26:27], v[26:27], v[246:247]
	v_pk_fma_f32 v[246:247], v[28:29], v[28:29], v[246:247]
	v_pk_fma_f32 v[246:247], v[30:31], v[30:31], v[246:247]
	v_pk_fma_f32 v[246:247], v[32:33], v[32:33], v[246:247]
	s_nop 0
	v_add_f32_e32 v246, v246, v247
	s_nop 1
	v_add_f32_dpp v246, v246, v246 quad_perm:[1,0,3,2] row_mask:0xf bank_mask:0xf
	s_nop 1
	v_add_f32_dpp v246, v246, v246 quad_perm:[2,3,0,1] row_mask:0xf bank_mask:0xf
	s_nop 1
	v_add_f32_dpp v246, v246, v246 row_half_mirror row_mask:0xf bank_mask:0xf
	s_nop 1
	v_add_f32_dpp v246, v246, v246 row_mirror row_mask:0xf bank_mask:0xf
	s_nop 1
	v_add_f32_dpp v246, v246, v246 row_bcast:15 row_mask:0xa bank_mask:0xf
	s_nop 1
	v_add_f32_dpp v246, v246, v246 row_bcast:31 row_mask:0xc bank_mask:0xf
	s_nop 1
	v_readlane_b32 s0, v246, 63
	s_add_i32 s21, s37, 1792
	s_lshl_b32 s21, s21, 11
	s_add_u32 s10, s16, s21
	s_addc_u32 s11, s17, 0
	v_mov_b32_e32 v248, s0
	v_fmamk_f32 v248, v248, 0x3a800000, v143
	v_rsq_f32_e32 v248, v248
	s_nop 0
	v_pk_mul_f32 v[18:19], v[18:19], v[248:249] op_sel_hi:[1,0]
	v_pk_add_f32 v[50:51], v[50:51], 1.0 op_sel_hi:[1,0]
	v_pk_mul_f32 v[18:19], v[2:3], v[18:19]
	v_pk_fma_f32 v[18:19], v[50:51], v[18:19], v[34:35]
	v_pk_mul_f32 v[20:21], v[20:21], v[248:249] op_sel_hi:[1,0]
	v_pk_add_f32 v[52:53], v[52:53], 1.0 op_sel_hi:[1,0]
	v_pk_mul_f32 v[20:21], v[4:5], v[20:21]
	v_pk_fma_f32 v[20:21], v[52:53], v[20:21], v[36:37]
	v_cvt_pk_bf16_f32 v34, v18, v19
	v_cvt_pk_bf16_f32 v35, v20, v21
	global_store_dwordx2 v245, v[34:35], s[10:11]
	v_pk_mul_f32 v[22:23], v[22:23], v[248:249] op_sel_hi:[1,0]
	v_pk_add_f32 v[54:55], v[54:55], 1.0 op_sel_hi:[1,0]
	v_pk_mul_f32 v[22:23], v[6:7], v[22:23]
	v_pk_fma_f32 v[22:23], v[54:55], v[22:23], v[38:39]
	v_pk_mul_f32 v[24:25], v[24:25], v[248:249] op_sel_hi:[1,0]
	v_pk_add_f32 v[56:57], v[56:57], 1.0 op_sel_hi:[1,0]
	v_pk_mul_f32 v[24:25], v[8:9], v[24:25]
	v_pk_fma_f32 v[24:25], v[56:57], v[24:25], v[40:41]
	v_cvt_pk_bf16_f32 v38, v22, v23
	v_cvt_pk_bf16_f32 v39, v24, v25
	global_store_dwordx2 v245, v[38:39], s[10:11] offset:512
	v_pk_mul_f32 v[26:27], v[26:27], v[248:249] op_sel_hi:[1,0]
	v_pk_add_f32 v[58:59], v[58:59], 1.0 op_sel_hi:[1,0]
	v_pk_mul_f32 v[26:27], v[10:11], v[26:27]
	v_pk_fma_f32 v[26:27], v[58:59], v[26:27], v[42:43]
	v_pk_mul_f32 v[28:29], v[28:29], v[248:249] op_sel_hi:[1,0]
	v_pk_add_f32 v[60:61], v[60:61], 1.0 op_sel_hi:[1,0]
	v_pk_mul_f32 v[28:29], v[12:13], v[28:29]
	v_pk_fma_f32 v[28:29], v[60:61], v[28:29], v[44:45]
	v_cvt_pk_bf16_f32 v42, v26, v27
	v_cvt_pk_bf16_f32 v43, v28, v29
	global_store_dwordx2 v245, v[42:43], s[10:11] offset:1024
	v_pk_mul_f32 v[30:31], v[30:31], v[248:249] op_sel_hi:[1,0]
	v_pk_add_f32 v[62:63], v[62:63], 1.0 op_sel_hi:[1,0]
	v_pk_mul_f32 v[30:31], v[14:15], v[30:31]
	v_pk_fma_f32 v[30:31], v[62:63], v[30:31], v[46:47]
	v_pk_mul_f32 v[32:33], v[32:33], v[248:249] op_sel_hi:[1,0]
	v_pk_add_f32 v[64:65], v[64:65], 1.0 op_sel_hi:[1,0]
	v_pk_mul_f32 v[32:33], v[16:17], v[32:33]
	v_pk_fma_f32 v[32:33], v[64:65], v[32:33], v[48:49]
	v_cvt_pk_bf16_f32 v46, v30, v31
	v_cvt_pk_bf16_f32 v47, v32, v33
	global_store_dwordx2 v245, v[46:47], s[10:11] offset:1536
	s_waitcnt vmcnt(8)
	v_pk_mul_f32 v[246:247], v[66:67], v[66:67]
	v_pk_fma_f32 v[246:247], v[68:69], v[68:69], v[246:247]
	v_pk_fma_f32 v[246:247], v[70:71], v[70:71], v[246:247]
	v_pk_fma_f32 v[246:247], v[72:73], v[72:73], v[246:247]
	v_pk_fma_f32 v[246:247], v[74:75], v[74:75], v[246:247]
	v_pk_fma_f32 v[246:247], v[76:77], v[76:77], v[246:247]
	v_pk_fma_f32 v[246:247], v[78:79], v[78:79], v[246:247]
	v_pk_fma_f32 v[246:247], v[80:81], v[80:81], v[246:247]
	s_nop 0
	v_add_f32_e32 v246, v246, v247
	s_nop 1
	v_add_f32_dpp v246, v246, v246 quad_perm:[1,0,3,2] row_mask:0xf bank_mask:0xf
	s_nop 1
	v_add_f32_dpp v246, v246, v246 quad_perm:[2,3,0,1] row_mask:0xf bank_mask:0xf
	s_nop 1
	v_add_f32_dpp v246, v246, v246 row_half_mirror row_mask:0xf bank_mask:0xf
	s_nop 1
	v_add_f32_dpp v246, v246, v246 row_mirror row_mask:0xf bank_mask:0xf
	s_nop 1
	v_add_f32_dpp v246, v246, v246 row_bcast:15 row_mask:0xa bank_mask:0xf
	s_nop 1
	v_add_f32_dpp v246, v246, v246 row_bcast:31 row_mask:0xc bank_mask:0xf
	s_nop 1
	v_readlane_b32 s0, v246, 63
	s_add_i32 s21, s37, 2048
	s_lshl_b32 s21, s21, 11
	s_add_u32 s10, s16, s21
	s_addc_u32 s11, s17, 0
	v_mov_b32_e32 v248, s0
	v_fmamk_f32 v248, v248, 0x3a800000, v143
	v_rsq_f32_e32 v248, v248
	s_nop 0
	v_pk_mul_f32 v[66:67], v[66:67], v[248:249] op_sel_hi:[1,0]
	v_pk_add_f32 v[98:99], v[98:99], 1.0 op_sel_hi:[1,0]
	v_pk_mul_f32 v[66:67], v[2:3], v[66:67]
	v_pk_fma_f32 v[66:67], v[98:99], v[66:67], v[82:83]
	v_pk_mul_f32 v[68:69], v[68:69], v[248:249] op_sel_hi:[1,0]
	v_pk_add_f32 v[100:101], v[100:101], 1.0 op_sel_hi:[1,0]
	v_pk_mul_f32 v[68:69], v[4:5], v[68:69]
	v_pk_fma_f32 v[68:69], v[100:101], v[68:69], v[84:85]
	v_cvt_pk_bf16_f32 v82, v66, v67
	v_cvt_pk_bf16_f32 v83, v68, v69
	global_store_dwordx2 v245, v[82:83], s[10:11]
	v_pk_mul_f32 v[70:71], v[70:71], v[248:249] op_sel_hi:[1,0]
	v_pk_add_f32 v[102:103], v[102:103], 1.0 op_sel_hi:[1,0]
	v_pk_mul_f32 v[70:71], v[6:7], v[70:71]
	v_pk_fma_f32 v[70:71], v[102:103], v[70:71], v[86:87]
	v_pk_mul_f32 v[72:73], v[72:73], v[248:249] op_sel_hi:[1,0]
	v_pk_add_f32 v[104:105], v[104:105], 1.0 op_sel_hi:[1,0]
	v_pk_mul_f32 v[72:73], v[8:9], v[72:73]
	v_pk_fma_f32 v[72:73], v[104:105], v[72:73], v[88:89]
	v_cvt_pk_bf16_f32 v86, v70, v71
	v_cvt_pk_bf16_f32 v87, v72, v73
	global_store_dwordx2 v245, v[86:87], s[10:11] offset:512
	v_pk_mul_f32 v[74:75], v[74:75], v[248:249] op_sel_hi:[1,0]
	v_pk_add_f32 v[106:107], v[106:107], 1.0 op_sel_hi:[1,0]
	v_pk_mul_f32 v[74:75], v[10:11], v[74:75]
	v_pk_fma_f32 v[74:75], v[106:107], v[74:75], v[90:91]
	v_pk_mul_f32 v[76:77], v[76:77], v[248:249] op_sel_hi:[1,0]
	v_pk_add_f32 v[108:109], v[108:109], 1.0 op_sel_hi:[1,0]
	v_pk_mul_f32 v[76:77], v[12:13], v[76:77]
	v_pk_fma_f32 v[76:77], v[108:109], v[76:77], v[92:93]
	v_cvt_pk_bf16_f32 v90, v74, v75
	v_cvt_pk_bf16_f32 v91, v76, v77
	global_store_dwordx2 v245, v[90:91], s[10:11] offset:1024
	v_pk_mul_f32 v[78:79], v[78:79], v[248:249] op_sel_hi:[1,0]
	v_pk_add_f32 v[118:119], v[118:119], 1.0 op_sel_hi:[1,0]
	v_pk_mul_f32 v[78:79], v[14:15], v[78:79]
	v_pk_fma_f32 v[78:79], v[118:119], v[78:79], v[94:95]
	v_pk_mul_f32 v[80:81], v[80:81], v[248:249] op_sel_hi:[1,0]
	v_pk_add_f32 v[120:121], v[120:121], 1.0 op_sel_hi:[1,0]
	v_pk_mul_f32 v[80:81], v[16:17], v[80:81]
	v_pk_fma_f32 v[80:81], v[120:121], v[80:81], v[96:97]
	v_cvt_pk_bf16_f32 v94, v78, v79
	v_cvt_pk_bf16_f32 v95, v80, v81
	global_store_dwordx2 v245, v[94:95], s[10:11] offset:1536
	s_branch .Lnorm2_done

; DI void modnorm_rows(const Params& p, int l, int which  , bool from_inputs, bool skip_ctx, int w0, int wstride, int lane) {
;   const float* g = (which ? p.norm2_g : p.norm1_g) + l * DM;
;   f32x4 gg[4];
; #pragma unroll
;   for (int i = 0; i < 4; ++i) gg[i] = *(const f32x4*)(g + i * 256 + lane * 4);
;   const int nrows = skip_ctx ? 8 * NLAT : T_TOK;
;   auto rowof = [&](int i) -> int { return skip_ctx ? (i / NLAT) * TB + NCTX + (i % NLAT) : i; };
;   int i = w0;
;   if (i >= nrows) return;
;   f32x4 vn[4];
;   {
;     const int row = rowof(i); const float* src = xsrc_row(p, from_inputs, row / TB, row % TB);
; #pragma unroll
;     for (int q = 0; q < 4; ++q) vn[q] = *(const f32x4*)(src + q * 256 + lane * 4);
;   }
;   for (; i < nrows; i += wstride) {
;     const int row = rowof(i); const int b = row / TB, s = row % TB;
;     f32x4 v[4];
; #pragma unroll
;     for (int q = 0; q < 4; ++q) v[q] = vn[q];
;     if (i + wstride < nrows) {
;       const int rn = rowof(i + wstride); const float* src = xsrc_row(p, from_inputs, rn / TB, rn % TB);
; #pragma unroll
;       for (int q = 0; q < 4; ++q) vn[q] = *(const f32x4*)(src + q * 256 + lane * 4);
;     }
;     const float* mod = p.MOD + (size_t)(l * 9 + (s < NCTX ? 8 : b)) * 6144 + (which ? 3 * 1024 : 0);
;     f32x4 sh[4], sc[4];
; #pragma unroll
;     for (int q = 0; q < 4; ++q) { sh[q] = *(const f32x4*)(mod + q * 256 + lane * 4); sc[q] = *(const f32x4*)(mod + 1024 + q * 256 + lane * 4); }
.LBB0_823:
	s_or_b64 exec, exec, s[0:1]
	v_readlane_b32 s0, v252, 9
	s_nop 1
	v_add_u32_e32 v50, s0, v158
	s_movk_i32 s0, 0x4800
	v_cmp_gt_i32_e32 vcc, s0, v50
	s_and_saveexec_b64 s[2:3], vcc
	s_cbranch_execz .LBB0_852
	v_readlane_b32 s0, v252, 9
	v_lshlrev_b32_e32 v244, 4, v115
	v_lshlrev_b32_e32 v245, 3, v115
	v_add_u32_e32 v1, s0, v158
	s_nop 1
	v_readfirstlane_b32 s20, v1
	v_readlane_b32 s4, v254, 40
	v_readlane_b32 s5, v254, 41
	v_readlane_b32 s12, v254, 28
	v_readlane_b32 s13, v254, 29
	v_readlane_b32 s14, v254, 32
	v_readlane_b32 s15, v254, 33
	v_readlane_b32 s16, v253, 40
	v_readlane_b32 s17, v253, 41
	v_readlane_b32 s18, v250, 4
	v_readlane_b32 s19, v250, 5
	s_nop 3
	s_lshl_b32 s0, s49, 12
	s_add_u32 s4, s4, s0
	s_addc_u32 s5, s5, 0
	global_load_dwordx4 v[2:5], v244, s[4:5]
	global_load_dwordx4 v[6:9], v244, s[4:5] offset:1024
	global_load_dwordx4 v[10:13], v244, s[4:5] offset:2048
	global_load_dwordx4 v[14:17], v244, s[4:5] offset:3072
	s_add_i32 s0, s77, 7
	s_cmp_gt_u32 s0, 16
	s_cselect_b32 s12, s56, s12
	s_cselect_b32 s13, s57, s13
	s_cselect_b32 s14, s64, s14
	s_cselect_b32 s15, s65, s15
	s_lshr_b32 s39, s20, 5
	s_lshl_b32 s39, s39, 2
	s_and_b32 s38, s20, 3
	s_or_b32 s39, s39, s38
	s_lshr_b32 s38, s20, 2
	s_and_b32 s38, s38, 7
	s_mul_i32 s37, s38, 0x900
	s_add_i32 s37, s37, s39
	s_add_i32 s21, s37, 0
	s_mul_hi_u32 s7, s21, 0x38e38e39
	s_lshr_b32 s7, s7, 9
	s_mul_i32 s8, s7, 0x900
	s_sub_i32 s8, s21, s8
	s_lshl_b32 s9, s7, 11
	s_add_i32 s9, s9, s8
	s_add_i32 s9, s9, 0xffffff00
	s_lshl_b32 s10, s7, 8
	s_add_i32 s10, s10, s8
	s_cmpk_gt_i32 s8, 0xff
	s_cselect_b32 s9, s9, s10
	s_cselect_b32 s26, s12, s14
	s_cselect_b32 s27, s13, s15
	s_cselect_b32 s10, s7, 8
	s_lshl_b32 s9, s9, 12
	s_add_u32 s26, s26, s9
	s_addc_u32 s27, s27, 0
	s_add_i32 s10, s10, s82
	s_mul_i32 s10, s10, s24
	s_add_u32 s28, s58, s10
	s_addc_u32 s29, s59, 0
	s_add_u32 s28, s28, 0x0
	s_addc_u32 s29, s29, 0
	s_add_u32 s0, s28, 0x1000
	s_addc_u32 s1, s29, 0
	global_load_dwordx4 v[18:21], v244, s[26:27] nt
	global_load_dwordx4 v[22:25], v244, s[26:27] offset:1024 nt
	global_load_dwordx4 v[26:29], v244, s[26:27] offset:2048 nt
	global_load_dwordx4 v[30:33], v244, s[26:27] offset:3072 nt
	global_load_dwordx4 v[34:37], v244, s[28:29]
	global_load_dwordx4 v[38:41], v244, s[28:29] offset:1024
	global_load_dwordx4 v[42:45], v244, s[28:29] offset:2048
	global_load_dwordx4 v[46:49], v244, s[28:29] offset:3072
	global_load_dwordx4 v[50:53], v244, s[0:1]
	global_load_dwordx4 v[54:57], v244, s[0:1] offset:1024
	global_load_dwordx4 v[58:61], v244, s[0:1] offset:2048
	global_load_dwordx4 v[62:65], v244, s[0:1] offset:3072
	s_add_i32 s21, s37, 256
	s_mul_hi_u32 s7, s21, 0x38e38e39
	s_lshr_b32 s7, s7, 9
	s_mul_i32 s8, s7, 0x900
	s_sub_i32 s8, s21, s8
	s_lshl_b32 s9, s7, 11
	s_add_i32 s9, s9, s8
	s_add_i32 s9, s9, 0xffffff00
	s_lshl_b32 s10, s7, 8
	s_add_i32 s10, s10, s8
	s_cmpk_gt_i32 s8, 0xff
	s_cselect_b32 s9, s9, s10
	s_cselect_b32 s26, s12, s14
	s_cselect_b32 s27, s13, s15
	s_cselect_b32 s10, s7, 8
	s_lshl_b32 s9, s9, 12
	s_add_u32 s26, s26, s9
	s_addc_u32 s27, s27, 0
	s_add_i32 s10, s10, s82
	s_mul_i32 s10, s10, s24
	s_add_u32 s28, s58, s10
	s_addc_u32 s29, s59, 0
	s_add_u32 s28, s28, 0x0
	s_addc_u32 s29, s29, 0
	s_add_u32 s0, s28, 0x1000
	s_addc_u32 s1, s29, 0
	global_load_dwordx4 v[66:69], v244, s[26:27] nt
	global_load_dwordx4 v[70:73], v244, s[26:27] offset:1024 nt
	global_load_dwordx4 v[74:77], v244, s[26:27] offset:2048 nt
	global_load_dwordx4 v[78:81], v244, s[26:27] offset:3072 nt
	global_load_dwordx4 v[82:85], v244, s[28:29]
	global_load_dwordx4 v[86:89], v244, s[28:29] offset:1024
	global_load_dwordx4 v[90:93], v244, s[28:29] offset:2048
	global_load_dwordx4 v[94:97], v244, s[28:29] offset:3072
	global_load_dwordx4 v[98:101], v244, s[0:1]
	global_load_dwordx4 v[102:105], v244, s[0:1] offset:1024
	global_load_dwordx4 v[106:109], v244, s[0:1] offset:2048
	global_load_dwordx4 v[118:121], v244, s[0:1] offset:3072
	s_add_i32 s21, s37, 512
	s_mul_hi_u32 s7, s21, 0x38e38e39
	s_lshr_b32 s7, s7, 9
	s_mul_i32 s8, s7, 0x900
	s_sub_i32 s8, s21, s8
	s_lshl_b32 s9, s7, 11
	s_add_i32 s9, s9, s8
	s_add_i32 s9, s9, 0xffffff00
	s_lshl_b32 s10, s7, 8
	s_add_i32 s10, s10, s8
	s_cmpk_gt_i32 s8, 0xff
	s_cselect_b32 s9, s9, s10
	s_cselect_b32 s26, s12, s14
	s_cselect_b32 s27, s13, s15
	s_cselect_b32 s10, s7, 8
	s_lshl_b32 s9, s9, 12
	s_add_u32 s26, s26, s9
	s_addc_u32 s27, s27, 0
	s_add_i32 s10, s10, s82
	s_mul_i32 s10, s10, s24
	s_add_u32 s28, s58, s10
	s_addc_u32 s29, s59, 0
	s_add_u32 s28, s28, 0x0
	s_addc_u32 s29, s29, 0
	s_add_u32 s0, s28, 0x1000
	s_addc_u32 s1, s29, 0
	global_load_dwordx4 v[122:125], v244, s[26:27] nt
	global_load_dwordx4 v[126:129], v244, s[26:27] offset:1024 nt
	global_load_dwordx4 v[130:133], v244, s[26:27] offset:2048 nt
	global_load_dwordx4 v[134:137], v244, s[26:27] offset:3072 nt
	global_load_dwordx4 v[160:163], v244, s[28:29]
	global_load_dwordx4 v[164:167], v244, s[28:29] offset:1024
	global_load_dwordx4 v[168:171], v244, s[28:29] offset:2048
	global_load_dwordx4 v[172:175], v244, s[28:29] offset:3072
	global_load_dwordx4 v[176:179], v244, s[0:1]
	global_load_dwordx4 v[180:183], v244, s[0:1] offset:1024
	global_load_dwordx4 v[184:187], v244, s[0:1] offset:2048
	global_load_dwordx4 v[188:191], v244, s[0:1] offset:3072
	s_waitcnt vmcnt(24)
; DI unsigned pk_bf16(float lo, float hi) { f32x2 v = {lo, hi}; bf16v2 b = __builtin_convertvector(v, bf16v2); return __builtin_bit_cast(unsigned, b); }
; DI float red64(float x) { for (int o = 32; o > 0; o >>= 1) x += __shfl_xor(x, o); return x; }
; DI void modnorm_rows(const Params& p, int l, int which  , bool from_inputs, bool skip_ctx, int w0, int wstride, int lane) {
;     ...
;     if (i + wstride < nrows) {
;       const int rn = rowof(i + wstride); const float* src = xsrc_row(p, from_inputs, rn / TB, rn % TB);
; #pragma unroll
;       for (int q = 0; q < 4; ++q) vn[q] = *(const f32x4*)(src + q * 256 + lane * 4);
;     }
;     const float* mod = p.MOD + (size_t)(l * 9 + (s < NCTX ? 8 : b)) * 6144 + (which ? 3 * 1024 : 0);
;     f32x4 sh[4], sc[4];
; #pragma unroll
;     for (int q = 0; q < 4; ++q) { sh[q] = *(const f32x4*)(mod + q * 256 + lane * 4); sc[q] = *(const f32x4*)(mod + 1024 + q * 256 + lane * 4); }
;     float ss = 0.f;
; #pragma unroll
;     for (int q = 0; q < 4; ++q) ss += v[q][0] * v[q][0] + v[q][1] * v[q][1] + v[q][2] * v[q][2] + v[q][3] * v[q][3];
;     ss = red64(ss);
;     const float rs = rsqrtf(ss * (1.f / 1024.f) + EPSF);
;     bf16_t* dst = p.HY + (size_t)row * DM;
; #pragma unroll
;     for (int q = 0; q < 4; ++q) {
;       float o[4];
; #pragma unroll
;       for (int j = 0; j < 4; ++j) o[j] = (v[q][j] * rs * gg[q][j]) * (1.f + sc[q][j]) + sh[q][j];
;       u32x2 w = {pk_bf16(o[0], o[1]), pk_bf16(o[2], o[3])};
;       *(u32x2*)(dst + q * 256 + lane * 4) = w;
;     }
	v_pk_mul_f32 v[246:247], v[18:19], v[18:19]
	v_pk_fma_f32 v[246:247], v[20:21], v[20:21], v[246:247]
	v_pk_fma_f32 v[246:247], v[22:23], v[22:23], v[246:247]
	v_pk_fma_f32 v[246:247], v[24:25], v[24:25], v[246:247]
	v_pk_fma_f32 v[246:247], v[26:27], v[26:27], v[246:247]
	v_pk_fma_f32 v[246:247], v[28:29], v[28:29], v[246:247]
	v_pk_fma_f32 v[246:247], v[30:31], v[30:31], v[246:247]
	v_pk_fma_f32 v[246:247], v[32:33], v[32:33], v[246:247]
	s_nop 0
	v_add_f32_e32 v246, v246, v247
	s_nop 1
	v_add_f32_dpp v246, v246, v246 quad_perm:[1,0,3,2] row_mask:0xf bank_mask:0xf
	s_nop 1
	v_add_f32_dpp v246, v246, v246 quad_perm:[2,3,0,1] row_mask:0xf bank_mask:0xf
	s_nop 1
	v_add_f32_dpp v246, v246, v246 row_half_mirror row_mask:0xf bank_mask:0xf
	s_nop 1
	v_add_f32_dpp v246, v246, v246 row_mirror row_mask:0xf bank_mask:0xf
	s_nop 1
	v_add_f32_dpp v246, v246, v246 row_bcast:15 row_mask:0xa bank_mask:0xf
	s_nop 1
	v_add_f32_dpp v246, v246, v246 row_bcast:31 row_mask:0xc bank_mask:0xf
	s_nop 1
	v_readlane_b32 s0, v246, 63
	s_add_i32 s21, s37, 0
	s_lshl_b32 s21, s21, 11
	s_add_u32 s10, s16, s21
	s_addc_u32 s11, s17, 0
	v_mov_b32_e32 v248, s0
	v_fmamk_f32 v248, v248, 0x3a800000, v143
	v_rsq_f32_e32 v248, v248
	s_nop 0
	v_pk_mul_f32 v[18:19], v[18:19], v[248:249] op_sel_hi:[1,0]
	v_pk_add_f32 v[50:51], v[50:51], 1.0 op_sel_hi:[1,0]
	v_pk_mul_f32 v[18:19], v[2:3], v[18:19]
	v_pk_fma_f32 v[18:19], v[50:51], v[18:19], v[34:35]
	v_pk_mul_f32 v[20:21], v[20:21], v[248:249] op_sel_hi:[1,0]
	v_pk_add_f32 v[52:53], v[52:53], 1.0 op_sel_hi:[1,0]
	v_pk_mul_f32 v[20:21], v[4:5], v[20:21]
	v_pk_fma_f32 v[20:21], v[52:53], v[20:21], v[36:37]
	v_cvt_pk_bf16_f32 v34, v18, v19
	v_cvt_pk_bf16_f32 v35, v20, v21
	global_store_dwordx2 v245, v[34:35], s[10:11]
	v_pk_mul_f32 v[22:23], v[22:23], v[248:249] op_sel_hi:[1,0]
	v_pk_add_f32 v[54:55], v[54:55], 1.0 op_sel_hi:[1,0]
	v_pk_mul_f32 v[22:23], v[6:7], v[22:23]
	v_pk_fma_f32 v[22:23], v[54:55], v[22:23], v[38:39]
	v_pk_mul_f32 v[24:25], v[24:25], v[248:249] op_sel_hi:[1,0]
	v_pk_add_f32 v[56:57], v[56:57], 1.0 op_sel_hi:[1,0]
	v_pk_mul_f32 v[24:25], v[8:9], v[24:25]
	v_pk_fma_f32 v[24:25], v[56:57], v[24:25], v[40:41]
	v_cvt_pk_bf16_f32 v38, v22, v23
	v_cvt_pk_bf16_f32 v39, v24, v25
	global_store_dwordx2 v245, v[38:39], s[10:11] offset:512
	v_pk_mul_f32 v[26:27], v[26:27], v[248:249] op_sel_hi:[1,0]
	v_pk_add_f32 v[58:59], v[58:59], 1.0 op_sel_hi:[1,0]
	v_pk_mul_f32 v[26:27], v[10:11], v[26:27]
	v_pk_fma_f32 v[26:27], v[58:59], v[26:27], v[42:43]
	v_pk_mul_f32 v[28:29], v[28:29], v[248:249] op_sel_hi:[1,0]
	v_pk_add_f32 v[60:61], v[60:61], 1.0 op_sel_hi:[1,0]
	v_pk_mul_f32 v[28:29], v[12:13], v[28:29]
	v_pk_fma_f32 v[28:29], v[60:61], v[28:29], v[44:45]
	v_cvt_pk_bf16_f32 v42, v26, v27
	v_cvt_pk_bf16_f32 v43, v28, v29
	global_store_dwordx2 v245, v[42:43], s[10:11] offset:1024
	v_pk_mul_f32 v[30:31], v[30:31], v[248:249] op_sel_hi:[1,0]
	v_pk_add_f32 v[62:63], v[62:63], 1.0 op_sel_hi:[1,0]
	v_pk_mul_f32 v[30:31], v[14:15], v[30:31]
	v_pk_fma_f32 v[30:31], v[62:63], v[30:31], v[46:47]
	v_pk_mul_f32 v[32:33], v[32:33], v[248:249] op_sel_hi:[1,0]
	v_pk_add_f32 v[64:65], v[64:65], 1.0 op_sel_hi:[1,0]
	v_pk_mul_f32 v[32:33], v[16:17], v[32:33]
	v_pk_fma_f32 v[32:33], v[64:65], v[32:33], v[48:49]
	v_cvt_pk_bf16_f32 v46, v30, v31
	v_cvt_pk_bf16_f32 v47, v32, v33
	global_store_dwordx2 v245, v[46:47], s[10:11] offset:1536
	s_add_i32 s21, s37, 768
	s_mul_hi_u32 s7, s21, 0x38e38e39
	s_lshr_b32 s7, s7, 9
	s_mul_i32 s8, s7, 0x900
	s_sub_i32 s8, s21, s8
	s_lshl_b32 s9, s7, 11
	s_add_i32 s9, s9, s8
	s_add_i32 s9, s9, 0xffffff00
	s_lshl_b32 s10, s7, 8
	s_add_i32 s10, s10, s8
	s_cmpk_gt_i32 s8, 0xff
	s_cselect_b32 s9, s9, s10
	s_cselect_b32 s26, s12, s14
	s_cselect_b32 s27, s13, s15
	s_cselect_b32 s10, s7, 8
	s_lshl_b32 s9, s9, 12
	s_add_u32 s26, s26, s9
	s_addc_u32 s27, s27, 0
	s_add_i32 s10, s10, s82
	s_mul_i32 s10, s10, s24
	s_add_u32 s28, s58, s10
	s_addc_u32 s29, s59, 0
	s_add_u32 s28, s28, 0x0
	s_addc_u32 s29, s29, 0
	s_add_u32 s0, s28, 0x1000
	s_addc_u32 s1, s29, 0
	global_load_dwordx4 v[18:21], v244, s[26:27] nt
	global_load_dwordx4 v[22:25], v244, s[26:27] offset:1024 nt
	global_load_dwordx4 v[26:29], v244, s[26:27] offset:2048 nt
	global_load_dwordx4 v[30:33], v244, s[26:27] offset:3072 nt
	global_load_dwordx4 v[34:37], v244, s[28:29]
	global_load_dwordx4 v[38:41], v244, s[28:29] offset:1024
	global_load_dwordx4 v[42:45], v244, s[28:29] offset:2048
	global_load_dwordx4 v[46:49], v244, s[28:29] offset:3072
	global_load_dwordx4 v[50:53], v244, s[0:1]
	global_load_dwordx4 v[54:57], v244, s[0:1] offset:1024
	global_load_dwordx4 v[58:61], v244, s[0:1] offset:2048
	global_load_dwordx4 v[62:65], v244, s[0:1] offset:3072
	s_waitcnt vmcnt(28)
; DI unsigned pk_bf16(float lo, float hi) { f32x2 v = {lo, hi}; bf16v2 b = __builtin_convertvector(v, bf16v2); return __builtin_bit_cast(unsigned, b); }
; DI float red64(float x) { for (int o = 32; o > 0; o >>= 1) x += __shfl_xor(x, o); return x; }
; DI void modnorm_rows(const Params& p, int l, int which  , bool from_inputs, bool skip_ctx, int w0, int wstride, int lane) {
;     ...
;     if (i + wstride < nrows) {
;       const int rn = rowof(i + wstride); const float* src = xsrc_row(p, from_inputs, rn / TB, rn % TB);
; #pragma unroll
;       for (int q = 0; q < 4; ++q) vn[q] = *(const f32x4*)(src + q * 256 + lane * 4);
;     }
;     const float* mod = p.MOD + (size_t)(l * 9 + (s < NCTX ? 8 : b)) * 6144 + (which ? 3 * 1024 : 0);
;     f32x4 sh[4], sc[4];
; #pragma unroll
;     for (int q = 0; q < 4; ++q) { sh[q] = *(const f32x4*)(mod + q * 256 + lane * 4); sc[q] = *(const f32x4*)(mod + 1024 + q * 256 + lane * 4); }
;     float ss = 0.f;
; #pragma unroll
;     for (int q = 0; q < 4; ++q) ss += v[q][0] * v[q][0] + v[q][1] * v[q][1] + v[q][2] * v[q][2] + v[q][3] * v[q][3];
;     ss = red64(ss);
;     const float rs = rsqrtf(ss * (1.f / 1024.f) + EPSF);
;     bf16_t* dst = p.HY + (size_t)row * DM;
; #pragma unroll
;     for (int q = 0; q < 4; ++q) {
;       float o[4];
; #pragma unroll
;       for (int j = 0; j < 4; ++j) o[j] = (v[q][j] * rs * gg[q][j]) * (1.f + sc[q][j]) + sh[q][j];
;       u32x2 w = {pk_bf16(o[0], o[1]), pk_bf16(o[2], o[3])};
;       *(u32x2*)(dst + q * 256 + lane * 4) = w;
;     }
	v_pk_mul_f32 v[246:247], v[66:67], v[66:67]
	v_pk_fma_f32 v[246:247], v[68:69], v[68:69], v[246:247]
	v_pk_fma_f32 v[246:247], v[70:71], v[70:71], v[246:247]
	v_pk_fma_f32 v[246:247], v[72:73], v[72:73], v[246:247]
	v_pk_fma_f32 v[246:247], v[74:75], v[74:75], v[246:247]
	v_pk_fma_f32 v[246:247], v[76:77], v[76:77], v[246:247]
	v_pk_fma_f32 v[246:247], v[78:79], v[78:79], v[246:247]
	v_pk_fma_f32 v[246:247], v[80:81], v[80:81], v[246:247]
	s_nop 0
	v_add_f32_e32 v246, v246, v247
	s_nop 1
	v_add_f32_dpp v246, v246, v246 quad_perm:[1,0,3,2] row_mask:0xf bank_mask:0xf
	s_nop 1
	v_add_f32_dpp v246, v246, v246 quad_perm:[2,3,0,1] row_mask:0xf bank_mask:0xf
	s_nop 1
	v_add_f32_dpp v246, v246, v246 row_half_mirror row_mask:0xf bank_mask:0xf
	s_nop 1
	v_add_f32_dpp v246, v246, v246 row_mirror row_mask:0xf bank_mask:0xf
	s_nop 1
	v_add_f32_dpp v246, v246, v246 row_bcast:15 row_mask:0xa bank_mask:0xf
	s_nop 1
	v_add_f32_dpp v246, v246, v246 row_bcast:31 row_mask:0xc bank_mask:0xf
	s_nop 1
	v_readlane_b32 s0, v246, 63
	s_add_i32 s21, s37, 256
	s_lshl_b32 s21, s21, 11
	s_add_u32 s10, s16, s21
	s_addc_u32 s11, s17, 0
	v_mov_b32_e32 v248, s0
	v_fmamk_f32 v248, v248, 0x3a800000, v143
	v_rsq_f32_e32 v248, v248
	s_nop 0
	v_pk_mul_f32 v[66:67], v[66:67], v[248:249] op_sel_hi:[1,0]
	v_pk_add_f32 v[98:99], v[98:99], 1.0 op_sel_hi:[1,0]
	v_pk_mul_f32 v[66:67], v[2:3], v[66:67]
	v_pk_fma_f32 v[66:67], v[98:99], v[66:67], v[82:83]
	v_pk_mul_f32 v[68:69], v[68:69], v[248:249] op_sel_hi:[1,0]
	v_pk_add_f32 v[100:101], v[100:101], 1.0 op_sel_hi:[1,0]
	v_pk_mul_f32 v[68:69], v[4:5], v[68:69]
	v_pk_fma_f32 v[68:69], v[100:101], v[68:69], v[84:85]
	v_cvt_pk_bf16_f32 v82, v66, v67
	v_cvt_pk_bf16_f32 v83, v68, v69
	global_store_dwordx2 v245, v[82:83], s[10:11]
	v_pk_mul_f32 v[70:71], v[70:71], v[248:249] op_sel_hi:[1,0]
	v_pk_add_f32 v[102:103], v[102:103], 1.0 op_sel_hi:[1,0]
	v_pk_mul_f32 v[70:71], v[6:7], v[70:71]
	v_pk_fma_f32 v[70:71], v[102:103], v[70:71], v[86:87]
	v_pk_mul_f32 v[72:73], v[72:73], v[248:249] op_sel_hi:[1,0]
	v_pk_add_f32 v[104:105], v[104:105], 1.0 op_sel_hi:[1,0]
	v_pk_mul_f32 v[72:73], v[8:9], v[72:73]
	v_pk_fma_f32 v[72:73], v[104:105], v[72:73], v[88:89]
	v_cvt_pk_bf16_f32 v86, v70, v71
	v_cvt_pk_bf16_f32 v87, v72, v73
	global_store_dwordx2 v245, v[86:87], s[10:11] offset:512
	v_pk_mul_f32 v[74:75], v[74:75], v[248:249] op_sel_hi:[1,0]
	v_pk_add_f32 v[106:107], v[106:107], 1.0 op_sel_hi:[1,0]
	v_pk_mul_f32 v[74:75], v[10:11], v[74:75]
	v_pk_fma_f32 v[74:75], v[106:107], v[74:75], v[90:91]
	v_pk_mul_f32 v[76:77], v[76:77], v[248:249] op_sel_hi:[1,0]
	v_pk_add_f32 v[108:109], v[108:109], 1.0 op_sel_hi:[1,0]
	v_pk_mul_f32 v[76:77], v[12:13], v[76:77]
	v_pk_fma_f32 v[76:77], v[108:109], v[76:77], v[92:93]
	v_cvt_pk_bf16_f32 v90, v74, v75
	v_cvt_pk_bf16_f32 v91, v76, v77
	global_store_dwordx2 v245, v[90:91], s[10:11] offset:1024
	v_pk_mul_f32 v[78:79], v[78:79], v[248:249] op_sel_hi:[1,0]
	v_pk_add_f32 v[118:119], v[118:119], 1.0 op_sel_hi:[1,0]
	v_pk_mul_f32 v[78:79], v[14:15], v[78:79]
	v_pk_fma_f32 v[78:79], v[118:119], v[78:79], v[94:95]
	v_pk_mul_f32 v[80:81], v[80:81], v[248:249] op_sel_hi:[1,0]
	v_pk_add_f32 v[120:121], v[120:121], 1.0 op_sel_hi:[1,0]
	v_pk_mul_f32 v[80:81], v[16:17], v[80:81]
	v_pk_fma_f32 v[80:81], v[120:121], v[80:81], v[96:97]
	v_cvt_pk_bf16_f32 v94, v78, v79
	v_cvt_pk_bf16_f32 v95, v80, v81
	global_store_dwordx2 v245, v[94:95], s[10:11] offset:1536
	s_add_i32 s21, s37, 1024
	s_mul_hi_u32 s7, s21, 0x38e38e39
	s_lshr_b32 s7, s7, 9
	s_mul_i32 s8, s7, 0x900
	s_sub_i32 s8, s21, s8
	s_lshl_b32 s9, s7, 11
	s_add_i32 s9, s9, s8
	s_add_i32 s9, s9, 0xffffff00
	s_lshl_b32 s10, s7, 8
	s_add_i32 s10, s10, s8
	s_cmpk_gt_i32 s8, 0xff
	s_cselect_b32 s9, s9, s10
	s_cselect_b32 s26, s12, s14
	s_cselect_b32 s27, s13, s15
	s_cselect_b32 s10, s7, 8
	s_lshl_b32 s9, s9, 12
	s_add_u32 s26, s26, s9
	s_addc_u32 s27, s27, 0
	s_add_i32 s10, s10, s82
	s_mul_i32 s10, s10, s24
	s_add_u32 s28, s58, s10
	s_addc_u32 s29, s59, 0
	s_add_u32 s28, s28, 0x0
	s_addc_u32 s29, s29, 0
	s_add_u32 s0, s28, 0x1000
	s_addc_u32 s1, s29, 0
	global_load_dwordx4 v[66:69], v244, s[26:27] nt
	global_load_dwordx4 v[70:73], v244, s[26:27] offset:1024 nt
	global_load_dwordx4 v[74:77], v244, s[26:27] offset:2048 nt
	global_load_dwordx4 v[78:81], v244, s[26:27] offset:3072 nt
	global_load_dwordx4 v[82:85], v244, s[28:29]
	global_load_dwordx4 v[86:89], v244, s[28:29] offset:1024
	global_load_dwordx4 v[90:93], v244, s[28:29] offset:2048
	global_load_dwordx4 v[94:97], v244, s[28:29] offset:3072
	global_load_dwordx4 v[98:101], v244, s[0:1]
	global_load_dwordx4 v[102:105], v244, s[0:1] offset:1024
	global_load_dwordx4 v[106:109], v244, s[0:1] offset:2048
	global_load_dwordx4 v[118:121], v244, s[0:1] offset:3072
	s_waitcnt vmcnt(32)
; DI unsigned pk_bf16(float lo, float hi) { f32x2 v = {lo, hi}; bf16v2 b = __builtin_convertvector(v, bf16v2); return __builtin_bit_cast(unsigned, b); }
; DI float red64(float x) { for (int o = 32; o > 0; o >>= 1) x += __shfl_xor(x, o); return x; }
; DI void modnorm_rows(const Params& p, int l, int which  , bool from_inputs, bool skip_ctx, int w0, int wstride, int lane) {
;     ...
;     if (i + wstride < nrows) {
;       const int rn = rowof(i + wstride); const float* src = xsrc_row(p, from_inputs, rn / TB, rn % TB);
; #pragma unroll
;       for (int q = 0; q < 4; ++q) vn[q] = *(const f32x4*)(src + q * 256 + lane * 4);
;     }
;     const float* mod = p.MOD + (size_t)(l * 9 + (s < NCTX ? 8 : b)) * 6144 + (which ? 3 * 1024 : 0);
;     f32x4 sh[4], sc[4];
; #pragma unroll
;     for (int q = 0; q < 4; ++q) { sh[q] = *(const f32x4*)(mod + q * 256 + lane * 4); sc[q] = *(const f32x4*)(mod + 1024 + q * 256 + lane * 4); }
;     float ss = 0.f;
; #pragma unroll
;     for (int q = 0; q < 4; ++q) ss += v[q][0] * v[q][0] + v[q][1] * v[q][1] + v[q][2] * v[q][2] + v[q][3] * v[q][3];
;     ss = red64(ss);
;     const float rs = rsqrtf(ss * (1.f / 1024.f) + EPSF);
;     bf16_t* dst = p.HY + (size_t)row * DM;
; #pragma unroll
;     for (int q = 0; q < 4; ++q) {
;       float o[4];
; #pragma unroll
;       for (int j = 0; j < 4; ++j) o[j] = (v[q][j] * rs * gg[q][j]) * (1.f + sc[q][j]) + sh[q][j];
;       u32x2 w = {pk_bf16(o[0], o[1]), pk_bf16(o[2], o[3])};
;       *(u32x2*)(dst + q * 256 + lane * 4) = w;
;     }
	v_pk_mul_f32 v[246:247], v[122:123], v[122:123]
	v_pk_fma_f32 v[246:247], v[124:125], v[124:125], v[246:247]
	v_pk_fma_f32 v[246:247], v[126:127], v[126:127], v[246:247]
	v_pk_fma_f32 v[246:247], v[128:129], v[128:129], v[246:247]
	v_pk_fma_f32 v[246:247], v[130:131], v[130:131], v[246:247]
	v_pk_fma_f32 v[246:247], v[132:133], v[132:133], v[246:247]
	v_pk_fma_f32 v[246:247], v[134:135], v[134:135], v[246:247]
	v_pk_fma_f32 v[246:247], v[136:137], v[136:137], v[246:247]
	s_nop 0
	v_add_f32_e32 v246, v246, v247
	s_nop 1
	v_add_f32_dpp v246, v246, v246 quad_perm:[1,0,3,2] row_mask:0xf bank_mask:0xf
	s_nop 1
	v_add_f32_dpp v246, v246, v246 quad_perm:[2,3,0,1] row_mask:0xf bank_mask:0xf
	s_nop 1
	v_add_f32_dpp v246, v246, v246 row_half_mirror row_mask:0xf bank_mask:0xf
	s_nop 1
	v_add_f32_dpp v246, v246, v246 row_mirror row_mask:0xf bank_mask:0xf
	s_nop 1
	v_add_f32_dpp v246, v246, v246 row_bcast:15 row_mask:0xa bank_mask:0xf
	s_nop 1
	v_add_f32_dpp v246, v246, v246 row_bcast:31 row_mask:0xc bank_mask:0xf
	s_nop 1
	v_readlane_b32 s0, v246, 63
	s_add_i32 s21, s37, 512
	s_lshl_b32 s21, s21, 11
	s_add_u32 s10, s16, s21
	s_addc_u32 s11, s17, 0
	v_mov_b32_e32 v248, s0
	v_fmamk_f32 v248, v248, 0x3a800000, v143
	v_rsq_f32_e32 v248, v248
	s_nop 0
	v_pk_mul_f32 v[122:123], v[122:123], v[248:249] op_sel_hi:[1,0]
	v_pk_add_f32 v[176:177], v[176:177], 1.0 op_sel_hi:[1,0]
	v_pk_mul_f32 v[122:123], v[2:3], v[122:123]
	v_pk_fma_f32 v[122:123], v[176:177], v[122:123], v[160:161]
	v_pk_mul_f32 v[124:125], v[124:125], v[248:249] op_sel_hi:[1,0]
	v_pk_add_f32 v[178:179], v[178:179], 1.0 op_sel_hi:[1,0]
	v_pk_mul_f32 v[124:125], v[4:5], v[124:125]
	v_pk_fma_f32 v[124:125], v[178:179], v[124:125], v[162:163]
	v_cvt_pk_bf16_f32 v160, v122, v123
	v_cvt_pk_bf16_f32 v161, v124, v125
	global_store_dwordx2 v245, v[160:161], s[10:11]
	v_pk_mul_f32 v[126:127], v[126:127], v[248:249] op_sel_hi:[1,0]
	v_pk_add_f32 v[180:181], v[180:181], 1.0 op_sel_hi:[1,0]
	v_pk_mul_f32 v[126:127], v[6:7], v[126:127]
	v_pk_fma_f32 v[126:127], v[180:181], v[126:127], v[164:165]
	v_pk_mul_f32 v[128:129], v[128:129], v[248:249] op_sel_hi:[1,0]
	v_pk_add_f32 v[182:183], v[182:183], 1.0 op_sel_hi:[1,0]
	v_pk_mul_f32 v[128:129], v[8:9], v[128:129]
	v_pk_fma_f32 v[128:129], v[182:183], v[128:129], v[166:167]
	v_cvt_pk_bf16_f32 v164, v126, v127
	v_cvt_pk_bf16_f32 v165, v128, v129
	global_store_dwordx2 v245, v[164:165], s[10:11] offset:512
	v_pk_mul_f32 v[130:131], v[130:131], v[248:249] op_sel_hi:[1,0]
	v_pk_add_f32 v[184:185], v[184:185], 1.0 op_sel_hi:[1,0]
	v_pk_mul_f32 v[130:131], v[10:11], v[130:131]
	v_pk_fma_f32 v[130:131], v[184:185], v[130:131], v[168:169]
	v_pk_mul_f32 v[132:133], v[132:133], v[248:249] op_sel_hi:[1,0]
	v_pk_add_f32 v[186:187], v[186:187], 1.0 op_sel_hi:[1,0]
	v_pk_mul_f32 v[132:133], v[12:13], v[132:133]
	v_pk_fma_f32 v[132:133], v[186:187], v[132:133], v[170:171]
	v_cvt_pk_bf16_f32 v168, v130, v131
	v_cvt_pk_bf16_f32 v169, v132, v133
	global_store_dwordx2 v245, v[168:169], s[10:11] offset:1024
	v_pk_mul_f32 v[134:135], v[134:135], v[248:249] op_sel_hi:[1,0]
	v_pk_add_f32 v[188:189], v[188:189], 1.0 op_sel_hi:[1,0]
	v_pk_mul_f32 v[134:135], v[14:15], v[134:135]
	v_pk_fma_f32 v[134:135], v[188:189], v[134:135], v[172:173]
	v_pk_mul_f32 v[136:137], v[136:137], v[248:249] op_sel_hi:[1,0]
	v_pk_add_f32 v[190:191], v[190:191], 1.0 op_sel_hi:[1,0]
	v_pk_mul_f32 v[136:137], v[16:17], v[136:137]
	v_pk_fma_f32 v[136:137], v[190:191], v[136:137], v[174:175]
	v_cvt_pk_bf16_f32 v172, v134, v135
	v_cvt_pk_bf16_f32 v173, v136, v137
	global_store_dwordx2 v245, v[172:173], s[10:11] offset:1536
	s_add_i32 s21, s37, 1280
	s_mul_hi_u32 s7, s21, 0x38e38e39
	s_lshr_b32 s7, s7, 9
	s_mul_i32 s8, s7, 0x900
	s_sub_i32 s8, s21, s8
	s_lshl_b32 s9, s7, 11
	s_add_i32 s9, s9, s8
	s_add_i32 s9, s9, 0xffffff00
	s_lshl_b32 s10, s7, 8
	s_add_i32 s10, s10, s8
	s_cmpk_gt_i32 s8, 0xff
	s_cselect_b32 s9, s9, s10
	s_cselect_b32 s26, s12, s14
	s_cselect_b32 s27, s13, s15
	s_cselect_b32 s10, s7, 8
	s_lshl_b32 s9, s9, 12
	s_add_u32 s26, s26, s9
	s_addc_u32 s27, s27, 0
	s_add_i32 s10, s10, s82
	s_mul_i32 s10, s10, s24
	s_add_u32 s28, s58, s10
	s_addc_u32 s29, s59, 0
	s_add_u32 s28, s28, 0x0
	s_addc_u32 s29, s29, 0
	s_add_u32 s0, s28, 0x1000
	s_addc_u32 s1, s29, 0
	global_load_dwordx4 v[122:125], v244, s[26:27] nt
	global_load_dwordx4 v[126:129], v244, s[26:27] offset:1024 nt
	global_load_dwordx4 v[130:133], v244, s[26:27] offset:2048 nt
	global_load_dwordx4 v[134:137], v244, s[26:27] offset:3072 nt
	global_load_dwordx4 v[160:163], v244, s[28:29]
	global_load_dwordx4 v[164:167], v244, s[28:29] offset:1024
	global_load_dwordx4 v[168:171], v244, s[28:29] offset:2048
	global_load_dwordx4 v[172:175], v244, s[28:29] offset:3072
	global_load_dwordx4 v[176:179], v244, s[0:1]
	global_load_dwordx4 v[180:183], v244, s[0:1] offset:1024
	global_load_dwordx4 v[184:187], v244, s[0:1] offset:2048
	global_load_dwordx4 v[188:191], v244, s[0:1] offset:3072
	s_waitcnt vmcnt(32)
; DI unsigned pk_bf16(float lo, float hi) { f32x2 v = {lo, hi}; bf16v2 b = __builtin_convertvector(v, bf16v2); return __builtin_bit_cast(unsigned, b); }
; DI float red64(float x) { for (int o = 32; o > 0; o >>= 1) x += __shfl_xor(x, o); return x; }
; DI void modnorm_rows(const Params& p, int l, int which  , bool from_inputs, bool skip_ctx, int w0, int wstride, int lane) {
;     ...
;     if (i + wstride < nrows) {
;       const int rn = rowof(i + wstride); const float* src = xsrc_row(p, from_inputs, rn / TB, rn % TB);
; #pragma unroll
;       for (int q = 0; q < 4; ++q) vn[q] = *(const f32x4*)(src + q * 256 + lane * 4);
;     }
;     const float* mod = p.MOD + (size_t)(l * 9 + (s < NCTX ? 8 : b)) * 6144 + (which ? 3 * 1024 : 0);
;     f32x4 sh[4], sc[4];
; #pragma unroll
;     for (int q = 0; q < 4; ++q) { sh[q] = *(const f32x4*)(mod + q * 256 + lane * 4); sc[q] = *(const f32x4*)(mod + 1024 + q * 256 + lane * 4); }
;     float ss = 0.f;
; #pragma unroll
;     for (int q = 0; q < 4; ++q) ss += v[q][0] * v[q][0] + v[q][1] * v[q][1] + v[q][2] * v[q][2] + v[q][3] * v[q][3];
;     ss = red64(ss);
;     const float rs = rsqrtf(ss * (1.f / 1024.f) + EPSF);
;     bf16_t* dst = p.HY + (size_t)row * DM;
; #pragma unroll
;     for (int q = 0; q < 4; ++q) {
;       float o[4];
; #pragma unroll
;       for (int j = 0; j < 4; ++j) o[j] = (v[q][j] * rs * gg[q][j]) * (1.f + sc[q][j]) + sh[q][j];
;       u32x2 w = {pk_bf16(o[0], o[1]), pk_bf16(o[2], o[3])};
;       *(u32x2*)(dst + q * 256 + lane * 4) = w;
;     }
	v_pk_mul_f32 v[246:247], v[18:19], v[18:19]
	v_pk_fma_f32 v[246:247], v[20:21], v[20:21], v[246:247]
	v_pk_fma_f32 v[246:247], v[22:23], v[22:23], v[246:247]
	v_pk_fma_f32 v[246:247], v[24:25], v[24:25], v[246:247]
	v_pk_fma_f32 v[246:247], v[26:27], v[26:27], v[246:247]
	v_pk_fma_f32 v[246:247], v[28:29], v[28:29], v[246:247]
	v_pk_fma_f32 v[246:247], v[30:31], v[30:31], v[246:247]
	v_pk_fma_f32 v[246:247], v[32:33], v[32:33], v[246:247]
	s_nop 0
	v_add_f32_e32 v246, v246, v247
	s_nop 1
	v_add_f32_dpp v246, v246, v246 quad_perm:[1,0,3,2] row_mask:0xf bank_mask:0xf
	s_nop 1
	v_add_f32_dpp v246, v246, v246 quad_perm:[2,3,0,1] row_mask:0xf bank_mask:0xf
	s_nop 1
	v_add_f32_dpp v246, v246, v246 row_half_mirror row_mask:0xf bank_mask:0xf
	s_nop 1
	v_add_f32_dpp v246, v246, v246 row_mirror row_mask:0xf bank_mask:0xf
	s_nop 1
	v_add_f32_dpp v246, v246, v246 row_bcast:15 row_mask:0xa bank_mask:0xf
	s_nop 1
	v_add_f32_dpp v246, v246, v246 row_bcast:31 row_mask:0xc bank_mask:0xf
	s_nop 1
	v_readlane_b32 s0, v246, 63
	s_add_i32 s21, s37, 768
	s_lshl_b32 s21, s21, 11
	s_add_u32 s10, s16, s21
	s_addc_u32 s11, s17, 0
	v_mov_b32_e32 v248, s0
	v_fmamk_f32 v248, v248, 0x3a800000, v143
	v_rsq_f32_e32 v248, v248
	s_nop 0
	v_pk_mul_f32 v[18:19], v[18:19], v[248:249] op_sel_hi:[1,0]
	v_pk_add_f32 v[50:51], v[50:51], 1.0 op_sel_hi:[1,0]
	v_pk_mul_f32 v[18:19], v[2:3], v[18:19]
	v_pk_fma_f32 v[18:19], v[50:51], v[18:19], v[34:35]
	v_pk_mul_f32 v[20:21], v[20:21], v[248:249] op_sel_hi:[1,0]
	v_pk_add_f32 v[52:53], v[52:53], 1.0 op_sel_hi:[1,0]
	v_pk_mul_f32 v[20:21], v[4:5], v[20:21]
	v_pk_fma_f32 v[20:21], v[52:53], v[20:21], v[36:37]
	v_cvt_pk_bf16_f32 v34, v18, v19
	v_cvt_pk_bf16_f32 v35, v20, v21
	global_store_dwordx2 v245, v[34:35], s[10:11]
	v_pk_mul_f32 v[22:23], v[22:23], v[248:249] op_sel_hi:[1,0]
	v_pk_add_f32 v[54:55], v[54:55], 1.0 op_sel_hi:[1,0]
	v_pk_mul_f32 v[22:23], v[6:7], v[22:23]
	v_pk_fma_f32 v[22:23], v[54:55], v[22:23], v[38:39]
	v_pk_mul_f32 v[24:25], v[24:25], v[248:249] op_sel_hi:[1,0]
	v_pk_add_f32 v[56:57], v[56:57], 1.0 op_sel_hi:[1,0]
	v_pk_mul_f32 v[24:25], v[8:9], v[24:25]
	v_pk_fma_f32 v[24:25], v[56:57], v[24:25], v[40:41]
	v_cvt_pk_bf16_f32 v38, v22, v23
	v_cvt_pk_bf16_f32 v39, v24, v25
	global_store_dwordx2 v245, v[38:39], s[10:11] offset:512
	v_pk_mul_f32 v[26:27], v[26:27], v[248:249] op_sel_hi:[1,0]
	v_pk_add_f32 v[58:59], v[58:59], 1.0 op_sel_hi:[1,0]
	v_pk_mul_f32 v[26:27], v[10:11], v[26:27]
	v_pk_fma_f32 v[26:27], v[58:59], v[26:27], v[42:43]
	v_pk_mul_f32 v[28:29], v[28:29], v[248:249] op_sel_hi:[1,0]
	v_pk_add_f32 v[60:61], v[60:61], 1.0 op_sel_hi:[1,0]
	v_pk_mul_f32 v[28:29], v[12:13], v[28:29]
	v_pk_fma_f32 v[28:29], v[60:61], v[28:29], v[44:45]
	v_cvt_pk_bf16_f32 v42, v26, v27
	v_cvt_pk_bf16_f32 v43, v28, v29
	global_store_dwordx2 v245, v[42:43], s[10:11] offset:1024
	v_pk_mul_f32 v[30:31], v[30:31], v[248:249] op_sel_hi:[1,0]
	v_pk_add_f32 v[62:63], v[62:63], 1.0 op_sel_hi:[1,0]
	v_pk_mul_f32 v[30:31], v[14:15], v[30:31]
	v_pk_fma_f32 v[30:31], v[62:63], v[30:31], v[46:47]
	v_pk_mul_f32 v[32:33], v[32:33], v[248:249] op_sel_hi:[1,0]
	v_pk_add_f32 v[64:65], v[64:65], 1.0 op_sel_hi:[1,0]
	v_pk_mul_f32 v[32:33], v[16:17], v[32:33]
	v_pk_fma_f32 v[32:33], v[64:65], v[32:33], v[48:49]
	v_cvt_pk_bf16_f32 v46, v30, v31
	v_cvt_pk_bf16_f32 v47, v32, v33
	global_store_dwordx2 v245, v[46:47], s[10:11] offset:1536
	s_add_i32 s21, s37, 1536
	s_mul_hi_u32 s7, s21, 0x38e38e39
	s_lshr_b32 s7, s7, 9
	s_mul_i32 s8, s7, 0x900
	s_sub_i32 s8, s21, s8
	s_lshl_b32 s9, s7, 11
	s_add_i32 s9, s9, s8
	s_add_i32 s9, s9, 0xffffff00
	s_lshl_b32 s10, s7, 8
	s_add_i32 s10, s10, s8
	s_cmpk_gt_i32 s8, 0xff
	s_cselect_b32 s9, s9, s10
	s_cselect_b32 s26, s12, s14
	s_cselect_b32 s27, s13, s15
	s_cselect_b32 s10, s7, 8
	s_lshl_b32 s9, s9, 12
	s_add_u32 s26, s26, s9
	s_addc_u32 s27, s27, 0
	s_add_i32 s10, s10, s82
	s_mul_i32 s10, s10, s24
	s_add_u32 s28, s58, s10
	s_addc_u32 s29, s59, 0
	s_add_u32 s28, s28, 0x0
	s_addc_u32 s29, s29, 0
	s_add_u32 s0, s28, 0x1000
	s_addc_u32 s1, s29, 0
	global_load_dwordx4 v[18:21], v244, s[26:27] nt
	global_load_dwordx4 v[22:25], v244, s[26:27] offset:1024 nt
	global_load_dwordx4 v[26:29], v244, s[26:27] offset:2048 nt
	global_load_dwordx4 v[30:33], v244, s[26:27] offset:3072 nt
	global_load_dwordx4 v[34:37], v244, s[28:29]
	global_load_dwordx4 v[38:41], v244, s[28:29] offset:1024
	global_load_dwordx4 v[42:45], v244, s[28:29] offset:2048
	global_load_dwordx4 v[46:49], v244, s[28:29] offset:3072
	global_load_dwordx4 v[50:53], v244, s[0:1]
	global_load_dwordx4 v[54:57], v244, s[0:1] offset:1024
	global_load_dwordx4 v[58:61], v244, s[0:1] offset:2048
	global_load_dwordx4 v[62:65], v244, s[0:1] offset:3072
	s_waitcnt vmcnt(32)
; DI unsigned pk_bf16(float lo, float hi) { f32x2 v = {lo, hi}; bf16v2 b = __builtin_convertvector(v, bf16v2); return __builtin_bit_cast(unsigned, b); }
; DI float red64(float x) { for (int o = 32; o > 0; o >>= 1) x += __shfl_xor(x, o); return x; }
; DI void modnorm_rows(const Params& p, int l, int which  , bool from_inputs, bool skip_ctx, int w0, int wstride, int lane) {
;     ...
;     if (i + wstride < nrows) {
;       const int rn = rowof(i + wstride); const float* src = xsrc_row(p, from_inputs, rn / TB, rn % TB);
; #pragma unroll
;       for (int q = 0; q < 4; ++q) vn[q] = *(const f32x4*)(src + q * 256 + lane * 4);
;     }
;     const float* mod = p.MOD + (size_t)(l * 9 + (s < NCTX ? 8 : b)) * 6144 + (which ? 3 * 1024 : 0);
;     f32x4 sh[4], sc[4];
; #pragma unroll
;     for (int q = 0; q < 4; ++q) { sh[q] = *(const f32x4*)(mod + q * 256 + lane * 4); sc[q] = *(const f32x4*)(mod + 1024 + q * 256 + lane * 4); }
;     float ss = 0.f;
; #pragma unroll
;     for (int q = 0; q < 4; ++q) ss += v[q][0] * v[q][0] + v[q][1] * v[q][1] + v[q][2] * v[q][2] + v[q][3] * v[q][3];
;     ss = red64(ss);
;     const float rs = rsqrtf(ss * (1.f / 1024.f) + EPSF);
;     bf16_t* dst = p.HY + (size_t)row * DM;
; #pragma unroll
;     for (int q = 0; q < 4; ++q) {
;       float o[4];
; #pragma unroll
;       for (int j = 0; j < 4; ++j) o[j] = (v[q][j] * rs * gg[q][j]) * (1.f + sc[q][j]) + sh[q][j];
;       u32x2 w = {pk_bf16(o[0], o[1]), pk_bf16(o[2], o[3])};
;       *(u32x2*)(dst + q * 256 + lane * 4) = w;
;     }
	v_pk_mul_f32 v[246:247], v[66:67], v[66:67]
	v_pk_fma_f32 v[246:247], v[68:69], v[68:69], v[246:247]
	v_pk_fma_f32 v[246:247], v[70:71], v[70:71], v[246:247]
	v_pk_fma_f32 v[246:247], v[72:73], v[72:73], v[246:247]
	v_pk_fma_f32 v[246:247], v[74:75], v[74:75], v[246:247]
	v_pk_fma_f32 v[246:247], v[76:77], v[76:77], v[246:247]
	v_pk_fma_f32 v[246:247], v[78:79], v[78:79], v[246:247]
	v_pk_fma_f32 v[246:247], v[80:81], v[80:81], v[246:247]
	s_nop 0
	v_add_f32_e32 v246, v246, v247
	s_nop 1
	v_add_f32_dpp v246, v246, v246 quad_perm:[1,0,3,2] row_mask:0xf bank_mask:0xf
	s_nop 1
	v_add_f32_dpp v246, v246, v246 quad_perm:[2,3,0,1] row_mask:0xf bank_mask:0xf
	s_nop 1
	v_add_f32_dpp v246, v246, v246 row_half_mirror row_mask:0xf bank_mask:0xf
	s_nop 1
	v_add_f32_dpp v246, v246, v246 row_mirror row_mask:0xf bank_mask:0xf
	s_nop 1
	v_add_f32_dpp v246, v246, v246 row_bcast:15 row_mask:0xa bank_mask:0xf
	s_nop 1
	v_add_f32_dpp v246, v246, v246 row_bcast:31 row_mask:0xc bank_mask:0xf
	s_nop 1
	v_readlane_b32 s0, v246, 63
	s_add_i32 s21, s37, 1024
	s_lshl_b32 s21, s21, 11
	s_add_u32 s10, s16, s21
	s_addc_u32 s11, s17, 0
	v_mov_b32_e32 v248, s0
	v_fmamk_f32 v248, v248, 0x3a800000, v143
	v_rsq_f32_e32 v248, v248
	s_nop 0
	v_pk_mul_f32 v[66:67], v[66:67], v[248:249] op_sel_hi:[1,0]
	v_pk_add_f32 v[98:99], v[98:99], 1.0 op_sel_hi:[1,0]
	v_pk_mul_f32 v[66:67], v[2:3], v[66:67]
	v_pk_fma_f32 v[66:67], v[98:99], v[66:67], v[82:83]
	v_pk_mul_f32 v[68:69], v[68:69], v[248:249] op_sel_hi:[1,0]
	v_pk_add_f32 v[100:101], v[100:101], 1.0 op_sel_hi:[1,0]
	v_pk_mul_f32 v[68:69], v[4:5], v[68:69]
	v_pk_fma_f32 v[68:69], v[100:101], v[68:69], v[84:85]
	v_cvt_pk_bf16_f32 v82, v66, v67
	v_cvt_pk_bf16_f32 v83, v68, v69
	global_store_dwordx2 v245, v[82:83], s[10:11]
	v_pk_mul_f32 v[70:71], v[70:71], v[248:249] op_sel_hi:[1,0]
	v_pk_add_f32 v[102:103], v[102:103], 1.0 op_sel_hi:[1,0]
	v_pk_mul_f32 v[70:71], v[6:7], v[70:71]
	v_pk_fma_f32 v[70:71], v[102:103], v[70:71], v[86:87]
	v_pk_mul_f32 v[72:73], v[72:73], v[248:249] op_sel_hi:[1,0]
	v_pk_add_f32 v[104:105], v[104:105], 1.0 op_sel_hi:[1,0]
	v_pk_mul_f32 v[72:73], v[8:9], v[72:73]
	v_pk_fma_f32 v[72:73], v[104:105], v[72:73], v[88:89]
	v_cvt_pk_bf16_f32 v86, v70, v71
	v_cvt_pk_bf16_f32 v87, v72, v73
	global_store_dwordx2 v245, v[86:87], s[10:11] offset:512
	v_pk_mul_f32 v[74:75], v[74:75], v[248:249] op_sel_hi:[1,0]
	v_pk_add_f32 v[106:107], v[106:107], 1.0 op_sel_hi:[1,0]
	v_pk_mul_f32 v[74:75], v[10:11], v[74:75]
	v_pk_fma_f32 v[74:75], v[106:107], v[74:75], v[90:91]
	v_pk_mul_f32 v[76:77], v[76:77], v[248:249] op_sel_hi:[1,0]
	v_pk_add_f32 v[108:109], v[108:109], 1.0 op_sel_hi:[1,0]
	v_pk_mul_f32 v[76:77], v[12:13], v[76:77]
	v_pk_fma_f32 v[76:77], v[108:109], v[76:77], v[92:93]
	v_cvt_pk_bf16_f32 v90, v74, v75
	v_cvt_pk_bf16_f32 v91, v76, v77
	global_store_dwordx2 v245, v[90:91], s[10:11] offset:1024
	v_pk_mul_f32 v[78:79], v[78:79], v[248:249] op_sel_hi:[1,0]
	v_pk_add_f32 v[118:119], v[118:119], 1.0 op_sel_hi:[1,0]
	v_pk_mul_f32 v[78:79], v[14:15], v[78:79]
	v_pk_fma_f32 v[78:79], v[118:119], v[78:79], v[94:95]
	v_pk_mul_f32 v[80:81], v[80:81], v[248:249] op_sel_hi:[1,0]
	v_pk_add_f32 v[120:121], v[120:121], 1.0 op_sel_hi:[1,0]
	v_pk_mul_f32 v[80:81], v[16:17], v[80:81]
	v_pk_fma_f32 v[80:81], v[120:121], v[80:81], v[96:97]
	v_cvt_pk_bf16_f32 v94, v78, v79
	v_cvt_pk_bf16_f32 v95, v80, v81
	global_store_dwordx2 v245, v[94:95], s[10:11] offset:1536
	s_add_i32 s21, s37, 1792
	s_mul_hi_u32 s7, s21, 0x38e38e39
	s_lshr_b32 s7, s7, 9
	s_mul_i32 s8, s7, 0x900
	s_sub_i32 s8, s21, s8
	s_lshl_b32 s9, s7, 11
	s_add_i32 s9, s9, s8
	s_add_i32 s9, s9, 0xffffff00
	s_lshl_b32 s10, s7, 8
	s_add_i32 s10, s10, s8
	s_cmpk_gt_i32 s8, 0xff
	s_cselect_b32 s9, s9, s10
	s_cselect_b32 s26, s12, s14
	s_cselect_b32 s27, s13, s15
	s_cselect_b32 s10, s7, 8
	s_lshl_b32 s9, s9, 12
	s_add_u32 s26, s26, s9
	s_addc_u32 s27, s27, 0
	s_add_i32 s10, s10, s82
	s_mul_i32 s10, s10, s24
	s_add_u32 s28, s58, s10
	s_addc_u32 s29, s59, 0
	s_add_u32 s28, s28, 0x0
	s_addc_u32 s29, s29, 0
	s_add_u32 s0, s28, 0x1000
	s_addc_u32 s1, s29, 0
	global_load_dwordx4 v[66:69], v244, s[26:27] nt
	global_load_dwordx4 v[70:73], v244, s[26:27] offset:1024 nt
	global_load_dwordx4 v[74:77], v244, s[26:27] offset:2048 nt
	global_load_dwordx4 v[78:81], v244, s[26:27] offset:3072 nt
	global_load_dwordx4 v[82:85], v244, s[28:29]
	global_load_dwordx4 v[86:89], v244, s[28:29] offset:1024
	global_load_dwordx4 v[90:93], v244, s[28:29] offset:2048
	global_load_dwordx4 v[94:97], v244, s[28:29] offset:3072
	global_load_dwordx4 v[98:101], v244, s[0:1]
	global_load_dwordx4 v[102:105], v244, s[0:1] offset:1024
	global_load_dwordx4 v[106:109], v244, s[0:1] offset:2048
	global_load_dwordx4 v[118:121], v244, s[0:1] offset:3072
	s_waitcnt vmcnt(32)
; DI unsigned pk_bf16(float lo, float hi) { f32x2 v = {lo, hi}; bf16v2 b = __builtin_convertvector(v, bf16v2); return __builtin_bit_cast(unsigned, b); }
; DI float red64(float x) { for (int o = 32; o > 0; o >>= 1) x += __shfl_xor(x, o); return x; }
; DI void modnorm_rows(const Params& p, int l, int which  , bool from_inputs, bool skip_ctx, int w0, int wstride, int lane) {
;     ...
;     if (i + wstride < nrows) {
;       const int rn = rowof(i + wstride); const float* src = xsrc_row(p, from_inputs, rn / TB, rn % TB);
; #pragma unroll
;       for (int q = 0; q < 4; ++q) vn[q] = *(const f32x4*)(src + q * 256 + lane * 4);
;     }
;     const float* mod = p.MOD + (size_t)(l * 9 + (s < NCTX ? 8 : b)) * 6144 + (which ? 3 * 1024 : 0);
;     f32x4 sh[4], sc[4];
; #pragma unroll
;     for (int q = 0; q < 4; ++q) { sh[q] = *(const f32x4*)(mod + q * 256 + lane * 4); sc[q] = *(const f32x4*)(mod + 1024 + q * 256 + lane * 4); }
;     float ss = 0.f;
; #pragma unroll
;     for (int q = 0; q < 4; ++q) ss += v[q][0] * v[q][0] + v[q][1] * v[q][1] + v[q][2] * v[q][2] + v[q][3] * v[q][3];
;     ss = red64(ss);
;     const float rs = rsqrtf(ss * (1.f / 1024.f) + EPSF);
;     bf16_t* dst = p.HY + (size_t)row * DM;
; #pragma unroll
;     for (int q = 0; q < 4; ++q) {
;       float o[4];
; #pragma unroll
;       for (int j = 0; j < 4; ++j) o[j] = (v[q][j] * rs * gg[q][j]) * (1.f + sc[q][j]) + sh[q][j];
;       u32x2 w = {pk_bf16(o[0], o[1]), pk_bf16(o[2], o[3])};
;       *(u32x2*)(dst + q * 256 + lane * 4) = w;
;     }
	v_pk_mul_f32 v[246:247], v[122:123], v[122:123]
	v_pk_fma_f32 v[246:247], v[124:125], v[124:125], v[246:247]
	v_pk_fma_f32 v[246:247], v[126:127], v[126:127], v[246:247]
	v_pk_fma_f32 v[246:247], v[128:129], v[128:129], v[246:247]
	v_pk_fma_f32 v[246:247], v[130:131], v[130:131], v[246:247]
	v_pk_fma_f32 v[246:247], v[132:133], v[132:133], v[246:247]
	v_pk_fma_f32 v[246:247], v[134:135], v[134:135], v[246:247]
	v_pk_fma_f32 v[246:247], v[136:137], v[136:137], v[246:247]
	s_nop 0
	v_add_f32_e32 v246, v246, v247
	s_nop 1
	v_add_f32_dpp v246, v246, v246 quad_perm:[1,0,3,2] row_mask:0xf bank_mask:0xf
	s_nop 1
	v_add_f32_dpp v246, v246, v246 quad_perm:[2,3,0,1] row_mask:0xf bank_mask:0xf
	s_nop 1
	v_add_f32_dpp v246, v246, v246 row_half_mirror row_mask:0xf bank_mask:0xf
	s_nop 1
	v_add_f32_dpp v246, v246, v246 row_mirror row_mask:0xf bank_mask:0xf
	s_nop 1
	v_add_f32_dpp v246, v246, v246 row_bcast:15 row_mask:0xa bank_mask:0xf
	s_nop 1
	v_add_f32_dpp v246, v246, v246 row_bcast:31 row_mask:0xc bank_mask:0xf
	s_nop 1
	v_readlane_b32 s0, v246, 63
	s_add_i32 s21, s37, 1280
	s_lshl_b32 s21, s21, 11
	s_add_u32 s10, s16, s21
	s_addc_u32 s11, s17, 0
	v_mov_b32_e32 v248, s0
	v_fmamk_f32 v248, v248, 0x3a800000, v143
	v_rsq_f32_e32 v248, v248
	s_nop 0
	v_pk_mul_f32 v[122:123], v[122:123], v[248:249] op_sel_hi:[1,0]
	v_pk_add_f32 v[176:177], v[176:177], 1.0 op_sel_hi:[1,0]
	v_pk_mul_f32 v[122:123], v[2:3], v[122:123]
	v_pk_fma_f32 v[122:123], v[176:177], v[122:123], v[160:161]
	v_pk_mul_f32 v[124:125], v[124:125], v[248:249] op_sel_hi:[1,0]
	v_pk_add_f32 v[178:179], v[178:179], 1.0 op_sel_hi:[1,0]
	v_pk_mul_f32 v[124:125], v[4:5], v[124:125]
	v_pk_fma_f32 v[124:125], v[178:179], v[124:125], v[162:163]
	v_cvt_pk_bf16_f32 v160, v122, v123
	v_cvt_pk_bf16_f32 v161, v124, v125
	global_store_dwordx2 v245, v[160:161], s[10:11]
	v_pk_mul_f32 v[126:127], v[126:127], v[248:249] op_sel_hi:[1,0]
	v_pk_add_f32 v[180:181], v[180:181], 1.0 op_sel_hi:[1,0]
	v_pk_mul_f32 v[126:127], v[6:7], v[126:127]
	v_pk_fma_f32 v[126:127], v[180:181], v[126:127], v[164:165]
	v_pk_mul_f32 v[128:129], v[128:129], v[248:249] op_sel_hi:[1,0]
	v_pk_add_f32 v[182:183], v[182:183], 1.0 op_sel_hi:[1,0]
	v_pk_mul_f32 v[128:129], v[8:9], v[128:129]
	v_pk_fma_f32 v[128:129], v[182:183], v[128:129], v[166:167]
	v_cvt_pk_bf16_f32 v164, v126, v127
	v_cvt_pk_bf16_f32 v165, v128, v129
	global_store_dwordx2 v245, v[164:165], s[10:11] offset:512
	v_pk_mul_f32 v[130:131], v[130:131], v[248:249] op_sel_hi:[1,0]
	v_pk_add_f32 v[184:185], v[184:185], 1.0 op_sel_hi:[1,0]
	v_pk_mul_f32 v[130:131], v[10:11], v[130:131]
	v_pk_fma_f32 v[130:131], v[184:185], v[130:131], v[168:169]
	v_pk_mul_f32 v[132:133], v[132:133], v[248:249] op_sel_hi:[1,0]
	v_pk_add_f32 v[186:187], v[186:187], 1.0 op_sel_hi:[1,0]
	v_pk_mul_f32 v[132:133], v[12:13], v[132:133]
	v_pk_fma_f32 v[132:133], v[186:187], v[132:133], v[170:171]
	v_cvt_pk_bf16_f32 v168, v130, v131
	v_cvt_pk_bf16_f32 v169, v132, v133
	global_store_dwordx2 v245, v[168:169], s[10:11] offset:1024
	v_pk_mul_f32 v[134:135], v[134:135], v[248:249] op_sel_hi:[1,0]
	v_pk_add_f32 v[188:189], v[188:189], 1.0 op_sel_hi:[1,0]
	v_pk_mul_f32 v[134:135], v[14:15], v[134:135]
	v_pk_fma_f32 v[134:135], v[188:189], v[134:135], v[172:173]
	v_pk_mul_f32 v[136:137], v[136:137], v[248:249] op_sel_hi:[1,0]
	v_pk_add_f32 v[190:191], v[190:191], 1.0 op_sel_hi:[1,0]
	v_pk_mul_f32 v[136:137], v[16:17], v[136:137]
	v_pk_fma_f32 v[136:137], v[190:191], v[136:137], v[174:175]
	v_cvt_pk_bf16_f32 v172, v134, v135
	v_cvt_pk_bf16_f32 v173, v136, v137
	global_store_dwordx2 v245, v[172:173], s[10:11] offset:1536
	s_add_i32 s21, s37, 2048
	s_mul_hi_u32 s7, s21, 0x38e38e39
	s_lshr_b32 s7, s7, 9
	s_mul_i32 s8, s7, 0x900
	s_sub_i32 s8, s21, s8
	s_lshl_b32 s9, s7, 11
	s_add_i32 s9, s9, s8
	s_add_i32 s9, s9, 0xffffff00
	s_lshl_b32 s10, s7, 8
	s_add_i32 s10, s10, s8
	s_cmpk_gt_i32 s8, 0xff
	s_cselect_b32 s9, s9, s10
	s_cselect_b32 s26, s12, s14
	s_cselect_b32 s27, s13, s15
	s_cselect_b32 s10, s7, 8
	s_lshl_b32 s9, s9, 12
	s_add_u32 s26, s26, s9
	s_addc_u32 s27, s27, 0
	s_add_i32 s10, s10, s82
	s_mul_i32 s10, s10, s24
	s_add_u32 s28, s58, s10
	s_addc_u32 s29, s59, 0
	s_add_u32 s28, s28, 0x0
	s_addc_u32 s29, s29, 0
	s_add_u32 s0, s28, 0x1000
	s_addc_u32 s1, s29, 0
	global_load_dwordx4 v[122:125], v244, s[26:27] nt
	global_load_dwordx4 v[126:129], v244, s[26:27] offset:1024 nt
	global_load_dwordx4 v[130:133], v244, s[26:27] offset:2048 nt
	global_load_dwordx4 v[134:137], v244, s[26:27] offset:3072 nt
	global_load_dwordx4 v[160:163], v244, s[28:29]
	global_load_dwordx4 v[164:167], v244, s[28:29] offset:1024
	global_load_dwordx4 v[168:171], v244, s[28:29] offset:2048
	global_load_dwordx4 v[172:175], v244, s[28:29] offset:3072
	global_load_dwordx4 v[176:179], v244, s[0:1]
	global_load_dwordx4 v[180:183], v244, s[0:1] offset:1024
	global_load_dwordx4 v[184:187], v244, s[0:1] offset:2048
	global_load_dwordx4 v[188:191], v244, s[0:1] offset:3072
	s_waitcnt vmcnt(32)
; DI unsigned pk_bf16(float lo, float hi) { f32x2 v = {lo, hi}; bf16v2 b = __builtin_convertvector(v, bf16v2); return __builtin_bit_cast(unsigned, b); }
; DI float red64(float x) { for (int o = 32; o > 0; o >>= 1) x += __shfl_xor(x, o); return x; }
; DI void modnorm_rows(const Params& p, int l, int which  , bool from_inputs, bool skip_ctx, int w0, int wstride, int lane) {
;     ...
;     for (int q = 0; q < 4; ++q) ss += v[q][0] * v[q][0] + v[q][1] * v[q][1] + v[q][2] * v[q][2] + v[q][3] * v[q][3];
;     ss = red64(ss);
;     const float rs = rsqrtf(ss * (1.f / 1024.f) + EPSF);
;     bf16_t* dst = p.HY + (size_t)row * DM;
; #pragma unroll
;     for (int q = 0; q < 4; ++q) {
;       float o[4];
; #pragma unroll
;       for (int j = 0; j < 4; ++j) o[j] = (v[q][j] * rs * gg[q][j]) * (1.f + sc[q][j]) + sh[q][j];
;       u32x2 w = {pk_bf16(o[0], o[1]), pk_bf16(o[2], o[3])};
;       *(u32x2*)(dst + q * 256 + lane * 4) = w;
;     }
	v_pk_mul_f32 v[246:247], v[18:19], v[18:19]
	v_pk_fma_f32 v[246:247], v[20:21], v[20:21], v[246:247]
	v_pk_fma_f32 v[246:247], v[22:23], v[22:23], v[246:247]
	v_pk_fma_f32 v[246:247], v[24:25], v[24:25], v[246:247]
	v_pk_fma_f32 v[246:247], v[26:27], v[26:27], v[246:247]
	v_pk_fma_f32 v[246:247], v[28:29], v[28:29], v[246:247]
	v_pk_fma_f32 v[246:247], v[30:31], v[30:31], v[246:247]
	v_pk_fma_f32 v[246:247], v[32:33], v[32:33], v[246:247]
	s_nop 0
	v_add_f32_e32 v246, v246, v247
	s_nop 1
	v_add_f32_dpp v246, v246, v246 quad_perm:[1,0,3,2] row_mask:0xf bank_mask:0xf
	s_nop 1
	v_add_f32_dpp v246, v246, v246 quad_perm:[2,3,0,1] row_mask:0xf bank_mask:0xf
	s_nop 1
	v_add_f32_dpp v246, v246, v246 row_half_mirror row_mask:0xf bank_mask:0xf
	s_nop 1
	v_add_f32_dpp v246, v246, v246 row_mirror row_mask:0xf bank_mask:0xf
	s_nop 1
	v_add_f32_dpp v246, v246, v246 row_bcast:15 row_mask:0xa bank_mask:0xf
	s_nop 1
	v_add_f32_dpp v246, v246, v246 row_bcast:31 row_mask:0xc bank_mask:0xf
	s_nop 1
	v_readlane_b32 s0, v246, 63
	s_add_i32 s21, s37, 1536
	s_lshl_b32 s21, s21, 11
	s_add_u32 s10, s16, s21
	s_addc_u32 s11, s17, 0
	v_mov_b32_e32 v248, s0
	v_fmamk_f32 v248, v248, 0x3a800000, v143
	v_rsq_f32_e32 v248, v248
	s_nop 0
	v_pk_mul_f32 v[18:19], v[18:19], v[248:249] op_sel_hi:[1,0]
	v_pk_add_f32 v[50:51], v[50:51], 1.0 op_sel_hi:[1,0]
	v_pk_mul_f32 v[18:19], v[2:3], v[18:19]
	v_pk_fma_f32 v[18:19], v[50:51], v[18:19], v[34:35]
	v_pk_mul_f32 v[20:21], v[20:21], v[248:249] op_sel_hi:[1,0]
	v_pk_add_f32 v[52:53], v[52:53], 1.0 op_sel_hi:[1,0]
	v_pk_mul_f32 v[20:21], v[4:5], v[20:21]
	v_pk_fma_f32 v[20:21], v[52:53], v[20:21], v[36:37]
	v_cvt_pk_bf16_f32 v34, v18, v19
	v_cvt_pk_bf16_f32 v35, v20, v21
	global_store_dwordx2 v245, v[34:35], s[10:11]
	v_pk_mul_f32 v[22:23], v[22:23], v[248:249] op_sel_hi:[1,0]
	v_pk_add_f32 v[54:55], v[54:55], 1.0 op_sel_hi:[1,0]
	v_pk_mul_f32 v[22:23], v[6:7], v[22:23]
	v_pk_fma_f32 v[22:23], v[54:55], v[22:23], v[38:39]
	v_pk_mul_f32 v[24:25], v[24:25], v[248:249] op_sel_hi:[1,0]
	v_pk_add_f32 v[56:57], v[56:57], 1.0 op_sel_hi:[1,0]
	v_pk_mul_f32 v[24:25], v[8:9], v[24:25]
	v_pk_fma_f32 v[24:25], v[56:57], v[24:25], v[40:41]
	v_cvt_pk_bf16_f32 v38, v22, v23
	v_cvt_pk_bf16_f32 v39, v24, v25
	global_store_dwordx2 v245, v[38:39], s[10:11] offset:512
	v_pk_mul_f32 v[26:27], v[26:27], v[248:249] op_sel_hi:[1,0]
	v_pk_add_f32 v[58:59], v[58:59], 1.0 op_sel_hi:[1,0]
	v_pk_mul_f32 v[26:27], v[10:11], v[26:27]
	v_pk_fma_f32 v[26:27], v[58:59], v[26:27], v[42:43]
	v_pk_mul_f32 v[28:29], v[28:29], v[248:249] op_sel_hi:[1,0]
	v_pk_add_f32 v[60:61], v[60:61], 1.0 op_sel_hi:[1,0]
	v_pk_mul_f32 v[28:29], v[12:13], v[28:29]
	v_pk_fma_f32 v[28:29], v[60:61], v[28:29], v[44:45]
	v_cvt_pk_bf16_f32 v42, v26, v27
	v_cvt_pk_bf16_f32 v43, v28, v29
	global_store_dwordx2 v245, v[42:43], s[10:11] offset:1024
	v_pk_mul_f32 v[30:31], v[30:31], v[248:249] op_sel_hi:[1,0]
	v_pk_add_f32 v[62:63], v[62:63], 1.0 op_sel_hi:[1,0]
	v_pk_mul_f32 v[30:31], v[14:15], v[30:31]
	v_pk_fma_f32 v[30:31], v[62:63], v[30:31], v[46:47]
	v_pk_mul_f32 v[32:33], v[32:33], v[248:249] op_sel_hi:[1,0]
	v_pk_add_f32 v[64:65], v[64:65], 1.0 op_sel_hi:[1,0]
	v_pk_mul_f32 v[32:33], v[16:17], v[32:33]
	v_pk_fma_f32 v[32:33], v[64:65], v[32:33], v[48:49]
	v_cvt_pk_bf16_f32 v46, v30, v31
	v_cvt_pk_bf16_f32 v47, v32, v33
	global_store_dwordx2 v245, v[46:47], s[10:11] offset:1536
	s_waitcnt vmcnt(20)
	v_pk_mul_f32 v[246:247], v[66:67], v[66:67]
	v_pk_fma_f32 v[246:247], v[68:69], v[68:69], v[246:247]
	v_pk_fma_f32 v[246:247], v[70:71], v[70:71], v[246:247]
	v_pk_fma_f32 v[246:247], v[72:73], v[72:73], v[246:247]
	v_pk_fma_f32 v[246:247], v[74:75], v[74:75], v[246:247]
	v_pk_fma_f32 v[246:247], v[76:77], v[76:77], v[246:247]
	v_pk_fma_f32 v[246:247], v[78:79], v[78:79], v[246:247]
	v_pk_fma_f32 v[246:247], v[80:81], v[80:81], v[246:247]
	s_nop 0
	v_add_f32_e32 v246, v246, v247
	s_nop 1
	v_add_f32_dpp v246, v246, v246 quad_perm:[1,0,3,2] row_mask:0xf bank_mask:0xf
	s_nop 1
	v_add_f32_dpp v246, v246, v246 quad_perm:[2,3,0,1] row_mask:0xf bank_mask:0xf
	s_nop 1
	v_add_f32_dpp v246, v246, v246 row_half_mirror row_mask:0xf bank_mask:0xf
	s_nop 1
	v_add_f32_dpp v246, v246, v246 row_mirror row_mask:0xf bank_mask:0xf
	s_nop 1
	v_add_f32_dpp v246, v246, v246 row_bcast:15 row_mask:0xa bank_mask:0xf
	s_nop 1
	v_add_f32_dpp v246, v246, v246 row_bcast:31 row_mask:0xc bank_mask:0xf
	s_nop 1
	v_readlane_b32 s0, v246, 63
	s_add_i32 s21, s37, 1792
	s_lshl_b32 s21, s21, 11
	s_add_u32 s10, s16, s21
	s_addc_u32 s11, s17, 0
	v_mov_b32_e32 v248, s0
	v_fmamk_f32 v248, v248, 0x3a800000, v143
	v_rsq_f32_e32 v248, v248
	s_nop 0
	v_pk_mul_f32 v[66:67], v[66:67], v[248:249] op_sel_hi:[1,0]
	v_pk_add_f32 v[98:99], v[98:99], 1.0 op_sel_hi:[1,0]
	v_pk_mul_f32 v[66:67], v[2:3], v[66:67]
	v_pk_fma_f32 v[66:67], v[98:99], v[66:67], v[82:83]
	v_pk_mul_f32 v[68:69], v[68:69], v[248:249] op_sel_hi:[1,0]
	v_pk_add_f32 v[100:101], v[100:101], 1.0 op_sel_hi:[1,0]
	v_pk_mul_f32 v[68:69], v[4:5], v[68:69]
	v_pk_fma_f32 v[68:69], v[100:101], v[68:69], v[84:85]
	v_cvt_pk_bf16_f32 v82, v66, v67
	v_cvt_pk_bf16_f32 v83, v68, v69
	global_store_dwordx2 v245, v[82:83], s[10:11]
	v_pk_mul_f32 v[70:71], v[70:71], v[248:249] op_sel_hi:[1,0]
	v_pk_add_f32 v[102:103], v[102:103], 1.0 op_sel_hi:[1,0]
	v_pk_mul_f32 v[70:71], v[6:7], v[70:71]
	v_pk_fma_f32 v[70:71], v[102:103], v[70:71], v[86:87]
	v_pk_mul_f32 v[72:73], v[72:73], v[248:249] op_sel_hi:[1,0]
	v_pk_add_f32 v[104:105], v[104:105], 1.0 op_sel_hi:[1,0]
	v_pk_mul_f32 v[72:73], v[8:9], v[72:73]
	v_pk_fma_f32 v[72:73], v[104:105], v[72:73], v[88:89]
	v_cvt_pk_bf16_f32 v86, v70, v71
	v_cvt_pk_bf16_f32 v87, v72, v73
	global_store_dwordx2 v245, v[86:87], s[10:11] offset:512
	v_pk_mul_f32 v[74:75], v[74:75], v[248:249] op_sel_hi:[1,0]
	v_pk_add_f32 v[106:107], v[106:107], 1.0 op_sel_hi:[1,0]
	v_pk_mul_f32 v[74:75], v[10:11], v[74:75]
	v_pk_fma_f32 v[74:75], v[106:107], v[74:75], v[90:91]
	v_pk_mul_f32 v[76:77], v[76:77], v[248:249] op_sel_hi:[1,0]
	v_pk_add_f32 v[108:109], v[108:109], 1.0 op_sel_hi:[1,0]
	v_pk_mul_f32 v[76:77], v[12:13], v[76:77]
	v_pk_fma_f32 v[76:77], v[108:109], v[76:77], v[92:93]
	v_cvt_pk_bf16_f32 v90, v74, v75
	v_cvt_pk_bf16_f32 v91, v76, v77
	global_store_dwordx2 v245, v[90:91], s[10:11] offset:1024
	v_pk_mul_f32 v[78:79], v[78:79], v[248:249] op_sel_hi:[1,0]
	v_pk_add_f32 v[118:119], v[118:119], 1.0 op_sel_hi:[1,0]
	v_pk_mul_f32 v[78:79], v[14:15], v[78:79]
	v_pk_fma_f32 v[78:79], v[118:119], v[78:79], v[94:95]
	v_pk_mul_f32 v[80:81], v[80:81], v[248:249] op_sel_hi:[1,0]
	v_pk_add_f32 v[120:121], v[120:121], 1.0 op_sel_hi:[1,0]
	v_pk_mul_f32 v[80:81], v[16:17], v[80:81]
	v_pk_fma_f32 v[80:81], v[120:121], v[80:81], v[96:97]
	v_cvt_pk_bf16_f32 v94, v78, v79
	v_cvt_pk_bf16_f32 v95, v80, v81
	global_store_dwordx2 v245, v[94:95], s[10:11] offset:1536
	s_waitcnt vmcnt(8)
; DI unsigned pk_bf16(float lo, float hi) { f32x2 v = {lo, hi}; bf16v2 b = __builtin_convertvector(v, bf16v2); return __builtin_bit_cast(unsigned, b); }
; DI float red64(float x) { for (int o = 32; o > 0; o >>= 1) x += __shfl_xor(x, o); return x; }
; DI void modnorm_rows(const Params& p, int l, int which  , bool from_inputs, bool skip_ctx, int w0, int wstride, int lane) {
;     ...
;     for (int q = 0; q < 4; ++q) ss += v[q][0] * v[q][0] + v[q][1] * v[q][1] + v[q][2] * v[q][2] + v[q][3] * v[q][3];
;     ss = red64(ss);
;     const float rs = rsqrtf(ss * (1.f / 1024.f) + EPSF);
;     bf16_t* dst = p.HY + (size_t)row * DM;
; #pragma unroll
;     for (int q = 0; q < 4; ++q) {
;       float o[4];
; #pragma unroll
;       for (int j = 0; j < 4; ++j) o[j] = (v[q][j] * rs * gg[q][j]) * (1.f + sc[q][j]) + sh[q][j];
;       u32x2 w = {pk_bf16(o[0], o[1]), pk_bf16(o[2], o[3])};
;       *(u32x2*)(dst + q * 256 + lane * 4) = w;
;     }
	v_pk_mul_f32 v[246:247], v[122:123], v[122:123]
	v_pk_fma_f32 v[246:247], v[124:125], v[124:125], v[246:247]
	v_pk_fma_f32 v[246:247], v[126:127], v[126:127], v[246:247]
	v_pk_fma_f32 v[246:247], v[128:129], v[128:129], v[246:247]
	v_pk_fma_f32 v[246:247], v[130:131], v[130:131], v[246:247]
	v_pk_fma_f32 v[246:247], v[132:133], v[132:133], v[246:247]
	v_pk_fma_f32 v[246:247], v[134:135], v[134:135], v[246:247]
	v_pk_fma_f32 v[246:247], v[136:137], v[136:137], v[246:247]
	s_nop 0
	v_add_f32_e32 v246, v246, v247
	s_nop 1
	v_add_f32_dpp v246, v246, v246 quad_perm:[1,0,3,2] row_mask:0xf bank_mask:0xf
	s_nop 1
	v_add_f32_dpp v246, v246, v246 quad_perm:[2,3,0,1] row_mask:0xf bank_mask:0xf
	s_nop 1
	v_add_f32_dpp v246, v246, v246 row_half_mirror row_mask:0xf bank_mask:0xf
	s_nop 1
	v_add_f32_dpp v246, v246, v246 row_mirror row_mask:0xf bank_mask:0xf
	s_nop 1
	v_add_f32_dpp v246, v246, v246 row_bcast:15 row_mask:0xa bank_mask:0xf
	s_nop 1
	v_add_f32_dpp v246, v246, v246 row_bcast:31 row_mask:0xc bank_mask:0xf
	s_nop 1
	v_readlane_b32 s0, v246, 63
	s_add_i32 s21, s37, 2048
	s_lshl_b32 s21, s21, 11
	s_add_u32 s10, s16, s21
	s_addc_u32 s11, s17, 0
	v_mov_b32_e32 v248, s0
	v_fmamk_f32 v248, v248, 0x3a800000, v143
	v_rsq_f32_e32 v248, v248
	s_nop 0
	v_pk_mul_f32 v[122:123], v[122:123], v[248:249] op_sel_hi:[1,0]
	v_pk_add_f32 v[176:177], v[176:177], 1.0 op_sel_hi:[1,0]
	v_pk_mul_f32 v[122:123], v[2:3], v[122:123]
	v_pk_fma_f32 v[122:123], v[176:177], v[122:123], v[160:161]
	v_pk_mul_f32 v[124:125], v[124:125], v[248:249] op_sel_hi:[1,0]
	v_pk_add_f32 v[178:179], v[178:179], 1.0 op_sel_hi:[1,0]
	v_pk_mul_f32 v[124:125], v[4:5], v[124:125]
	v_pk_fma_f32 v[124:125], v[178:179], v[124:125], v[162:163]
	v_cvt_pk_bf16_f32 v160, v122, v123
	v_cvt_pk_bf16_f32 v161, v124, v125
	global_store_dwordx2 v245, v[160:161], s[10:11]
	v_pk_mul_f32 v[126:127], v[126:127], v[248:249] op_sel_hi:[1,0]
	v_pk_add_f32 v[180:181], v[180:181], 1.0 op_sel_hi:[1,0]
	v_pk_mul_f32 v[126:127], v[6:7], v[126:127]
	v_pk_fma_f32 v[126:127], v[180:181], v[126:127], v[164:165]
	v_pk_mul_f32 v[128:129], v[128:129], v[248:249] op_sel_hi:[1,0]
	v_pk_add_f32 v[182:183], v[182:183], 1.0 op_sel_hi:[1,0]
	v_pk_mul_f32 v[128:129], v[8:9], v[128:129]
	v_pk_fma_f32 v[128:129], v[182:183], v[128:129], v[166:167]
	v_cvt_pk_bf16_f32 v164, v126, v127
	v_cvt_pk_bf16_f32 v165, v128, v129
	global_store_dwordx2 v245, v[164:165], s[10:11] offset:512
	v_pk_mul_f32 v[130:131], v[130:131], v[248:249] op_sel_hi:[1,0]
	v_pk_add_f32 v[184:185], v[184:185], 1.0 op_sel_hi:[1,0]
	v_pk_mul_f32 v[130:131], v[10:11], v[130:131]
	v_pk_fma_f32 v[130:131], v[184:185], v[130:131], v[168:169]
	v_pk_mul_f32 v[132:133], v[132:133], v[248:249] op_sel_hi:[1,0]
	v_pk_add_f32 v[186:187], v[186:187], 1.0 op_sel_hi:[1,0]
	v_pk_mul_f32 v[132:133], v[12:13], v[132:133]
	v_pk_fma_f32 v[132:133], v[186:187], v[132:133], v[170:171]
	v_cvt_pk_bf16_f32 v168, v130, v131
	v_cvt_pk_bf16_f32 v169, v132, v133
	global_store_dwordx2 v245, v[168:169], s[10:11] offset:1024
	v_pk_mul_f32 v[134:135], v[134:135], v[248:249] op_sel_hi:[1,0]
	v_pk_add_f32 v[188:189], v[188:189], 1.0 op_sel_hi:[1,0]
	v_pk_mul_f32 v[134:135], v[14:15], v[134:135]
	v_pk_fma_f32 v[134:135], v[188:189], v[134:135], v[172:173]
	v_pk_mul_f32 v[136:137], v[136:137], v[248:249] op_sel_hi:[1,0]
	v_pk_add_f32 v[190:191], v[190:191], 1.0 op_sel_hi:[1,0]
	v_pk_mul_f32 v[136:137], v[16:17], v[136:137]
	v_pk_fma_f32 v[136:137], v[190:191], v[136:137], v[174:175]
	v_cvt_pk_bf16_f32 v172, v134, v135
	v_cvt_pk_bf16_f32 v173, v136, v137
	global_store_dwordx2 v245, v[172:173], s[10:11] offset:1536
	s_branch .Lnorm1_done
